# GEMM main loops: B0-fragment LDS reads issued one slot earlier (stage-only slot) with counted vmcnt(8) visibility, lightening the read-heavy slot
# speedup vs baseline: 1.0042x; 1.0042x over previous
; #define PG8_STAGE(bufoff, gbase, voff) do { _Pragma("unroll") for (int _i = 0; _i < 2; ++_i) \
;         __builtin_amdgcn_global_load_lds((const unsigned*)((const char*)(gbase) + (voff)[_i]), (LAS unsigned*)(lds + (bufoff) + ldsw + _i * 8192), 16, 0, 0); } while (0)
; #define PG8_LDA(dst, b, h) do { _Pragma("unroll") for (int m = 0; m < 4; ++m) _Pragma("unroll") for (int k = 0; k < 2; ++k) dst[m][k] = *(const LAS bf16x8*)(lds + PG8_SA(b, h) + aoff + m * 2048 + k * 1024); } while (0)
; #define PG8_LDB(dst, b, h) do { _Pragma("unroll") for (int n = 0; n < 2; ++n) _Pragma("unroll") for (int k = 0; k < 2; ++k) dst[n][k] = *(const LAS bf16x8*)(lds + PG8_SB(b, h) + boff + n * 2048 + k * 1024); } while (0)
; #define PG8_MMA(ai, bj, At, Bt) do { __builtin_amdgcn_s_setprio(1); _Pragma("unroll") for (int m = 0; m < 4; ++m) _Pragma("unroll") for (int n = 0; n < 2; ++n) _Pragma("unroll") for (int k = 0; k < 2; ++k) \
;         acc[ai][bj][m][n] = __builtin_amdgcn_mfma_f32_16x16x32_bf16(Bt[n][k], At[m][k], acc[ai][bj][m][n], 0, 0, 0); __builtin_amdgcn_s_setprio(0); } while (0)
; #define PG8_BAR __builtin_amdgcn_s_barrier()
; template <class Epi, class Sched>
; __device__ __forceinline__ void gemm_phase(LAS unsigned char* lds, const Gemm g, const Sched& S, const Epi& E) {
;     ...
;     for (;;) {
;         const bool has_next = S.next(ui + 1, nxt);
;         const char* nA = has_next ? PG8_APTR(nxt) : cA; const char* nB = has_next ? PG8_BPTR(nxt) : cB;
;         const int nt = cur.nt;
;         for (int t = 0; t < nt; t += 2) {
;             const bool last = (t == nt - 2);
;             const char* a1 = cA + (size_t)(t + 1) * kstep;
;             const char* a2 = last ? nA : cA + (size_t)(t + 2) * kstep; const char* b2 = last ? nB : cB + (size_t)(t + 2) * kstep;
;             const char* a3 = a2 + kstep; const char* b3 = b2 + kstep;
;             PG8_LDB(B0, 0, 0); PG8_SCHED; PG8_LDA(At, 0, 0); PG8_STAGE(PG8_SA(1, 1), a1 + hstepA, voffA);
;             PG8_WAIT_L(8); PG8_BAR; PG8_WAIT_L(0); PG8_MMA(0, 0, At, B0); PG8_BAR; PG8_SCHED;
;     ...
; #pragma unroll
;         for (int a = 0; a < 2; ++a)
; #pragma unroll
;             for (int b = 0; b < 2; ++b)
; #pragma unroll
;                 for (int m = 0; m < 4; ++m)
; #pragma unroll
;                     for (int n = 0; n < 2; ++n) acc[a][b][m][n] = (f32x4){0.f, 0.f, 0.f, 0.f};
;         cur = nxt; cA = nA; cB = nB; ++ui;
.LBB0_371:
	s_add_i32 s17, s57, -2
	s_add_u32 s59, s36, 0x100
	v_mov_b32_e32 v2, 0
	s_addc_u32 s60, s37, 0
	s_mov_b32 s42, 0
	v_mov_b32_e32 v3, v2
	v_mov_b32_e32 v4, v2
	v_mov_b32_e32 v5, v2
	v_mov_b32_e32 v6, v2
	v_mov_b32_e32 v7, v2
	v_mov_b32_e32 v8, v2
	v_mov_b32_e32 v9, v2
	v_mov_b32_e32 v18, v2
	v_mov_b32_e32 v19, v2
	v_mov_b32_e32 v20, v2
	v_mov_b32_e32 v21, v2
	v_mov_b32_e32 v22, v2
	v_mov_b32_e32 v23, v2
	v_mov_b32_e32 v24, v2
	v_mov_b32_e32 v25, v2
	v_mov_b32_e32 v26, v2
	v_mov_b32_e32 v27, v2
	v_mov_b32_e32 v28, v2
	v_mov_b32_e32 v29, v2
	v_mov_b32_e32 v34, v2
	v_mov_b32_e32 v35, v2
	v_mov_b32_e32 v36, v2
	v_mov_b32_e32 v37, v2
	v_mov_b32_e32 v42, v2
	v_mov_b32_e32 v43, v2
	v_mov_b32_e32 v44, v2
	v_mov_b32_e32 v45, v2
	v_mov_b32_e32 v50, v2
	v_mov_b32_e32 v51, v2
	v_mov_b32_e32 v52, v2
	v_mov_b32_e32 v53, v2
	v_mov_b32_e32 v10, v2
	v_mov_b32_e32 v11, v2
	v_mov_b32_e32 v12, v2
	v_mov_b32_e32 v13, v2
	v_mov_b32_e32 v14, v2
	v_mov_b32_e32 v15, v2
	v_mov_b32_e32 v16, v2
	v_mov_b32_e32 v17, v2
	v_mov_b32_e32 v30, v2
	v_mov_b32_e32 v31, v2
	v_mov_b32_e32 v32, v2
	v_mov_b32_e32 v33, v2
	v_mov_b32_e32 v38, v2
	v_mov_b32_e32 v39, v2
	v_mov_b32_e32 v40, v2
	v_mov_b32_e32 v41, v2
	v_mov_b32_e32 v46, v2
	v_mov_b32_e32 v47, v2
	v_mov_b32_e32 v48, v2
	v_mov_b32_e32 v49, v2
	v_mov_b32_e32 v54, v2
	v_mov_b32_e32 v55, v2
	v_mov_b32_e32 v56, v2
	v_mov_b32_e32 v57, v2
	v_mov_b32_e32 v58, v2
	v_mov_b32_e32 v59, v2
	v_mov_b32_e32 v60, v2
	v_mov_b32_e32 v61, v2
	v_mov_b32_e32 v62, v2
	v_mov_b32_e32 v63, v2
	v_mov_b32_e32 v64, v2
	v_mov_b32_e32 v65, v2
	v_mov_b32_e32 v66, v2
	v_mov_b32_e32 v67, v2
	v_mov_b32_e32 v68, v2
	v_mov_b32_e32 v69, v2
	v_mov_b32_e32 v70, v2
	v_mov_b32_e32 v71, v2
	v_mov_b32_e32 v72, v2
	v_mov_b32_e32 v73, v2
	v_mov_b32_e32 v74, v2
	v_mov_b32_e32 v75, v2
	v_mov_b32_e32 v76, v2
	v_mov_b32_e32 v77, v2
	v_mov_b32_e32 v82, v2
	v_mov_b32_e32 v83, v2
	v_mov_b32_e32 v84, v2
	v_mov_b32_e32 v85, v2
	v_mov_b32_e32 v90, v2
	v_mov_b32_e32 v91, v2
	v_mov_b32_e32 v92, v2
	v_mov_b32_e32 v93, v2
	v_mov_b32_e32 v98, v2
	v_mov_b32_e32 v99, v2
	v_mov_b32_e32 v100, v2
	v_mov_b32_e32 v101, v2
	v_mov_b32_e32 v106, v2
	v_mov_b32_e32 v107, v2
	v_mov_b32_e32 v108, v2
	v_mov_b32_e32 v109, v2
	v_mov_b32_e32 v114, v2
	v_mov_b32_e32 v115, v2
	v_mov_b32_e32 v116, v2
	v_mov_b32_e32 v117, v2
	v_mov_b32_e32 v78, v2
	v_mov_b32_e32 v79, v2
	v_mov_b32_e32 v80, v2
	v_mov_b32_e32 v81, v2
	v_mov_b32_e32 v86, v2
	v_mov_b32_e32 v87, v2
	v_mov_b32_e32 v88, v2
	v_mov_b32_e32 v89, v2
	v_mov_b32_e32 v94, v2
	v_mov_b32_e32 v95, v2
	v_mov_b32_e32 v96, v2
	v_mov_b32_e32 v97, v2
	v_mov_b32_e32 v102, v2
	v_mov_b32_e32 v103, v2
	v_mov_b32_e32 v104, v2
	v_mov_b32_e32 v105, v2
	v_mov_b32_e32 v110, v2
	v_mov_b32_e32 v111, v2
	v_mov_b32_e32 v112, v2
	v_mov_b32_e32 v113, v2
	s_waitcnt lgkmcnt(0)
	v_mov_b32_e32 v118, v2
	v_mov_b32_e32 v119, v2
	v_mov_b32_e32 v120, v2
	v_mov_b32_e32 v121, v2
	v_mov_b32_e32 v122, v2
	v_mov_b32_e32 v123, v2
	v_mov_b32_e32 v124, v2
	v_mov_b32_e32 v125, v2
	v_mov_b32_e32 v126, v2
	v_mov_b32_e32 v127, v2
	v_mov_b32_e32 v128, v2
	v_mov_b32_e32 v129, v2
	v_add_u32_e32 v0, 0x10000, v148
	ds_read_b128 v[142:145], v0
	ds_read_b128 v[152:155], v0 offset:1024
	ds_read_b128 v[156:159], v0 offset:2048
	ds_read_b128 v[160:163], v0 offset:3072
.LBB0_372:
	s_add_i32 s61, s42, 2
	s_add_u32 s36, s22, 0x100
	s_addc_u32 s37, s23, 0
	s_add_i32 s62, 0, 0x10000
	v_add_u32_e32 v0, s62, v148
	s_cmp_eq_u32 s17, s42
	s_cselect_b32 s42, s0, s59
	s_cselect_b32 s45, s19, s37
	s_cselect_b32 s44, s18, s36
	s_cselect_b32 s43, s1, s60
	v_lshl_add_u64 v[196:197], s[22:23], 0, v[140:141]
	s_add_i32 m0, s50, 0xc000
	ds_read_b128 v[164:167], v150
	ds_read_b128 v[168:171], v150 offset:1024
	ds_read_b128 v[172:175], v150 offset:2048
	ds_read_b128 v[176:179], v150 offset:3072
	ds_read_b128 v[180:183], v150 offset:4096
	ds_read_b128 v[184:187], v150 offset:5120
	ds_read_b128 v[188:191], v150 offset:6144
	ds_read_b128 v[192:195], v150 offset:7168
	global_load_lds_dwordx4 v[196:197], off
	v_lshl_add_u64 v[196:197], s[22:23], 0, v[138:139]
	s_add_i32 m0, s50, 0xe000
	s_nop 0
	global_load_lds_dwordx4 v[196:197], off
	s_waitcnt lgkmcnt(8)
	s_barrier
	s_waitcnt lgkmcnt(0)
	s_setprio 1
	s_waitcnt lgkmcnt(0)
	v_mfma_f32_16x16x32_bf16 v[126:129], v[142:145], v[164:167], v[126:129]
	v_mfma_f32_16x16x32_bf16 v[122:125], v[156:159], v[164:167], v[122:125]
	v_mfma_f32_16x16x32_bf16 v[118:121], v[142:145], v[172:175], v[118:121]
	v_mfma_f32_16x16x32_bf16 v[110:113], v[156:159], v[172:175], v[110:113]
	v_mfma_f32_16x16x32_bf16 v[102:105], v[142:145], v[180:183], v[102:105]
	v_mfma_f32_16x16x32_bf16 v[94:97], v[156:159], v[180:183], v[94:97]
	v_mfma_f32_16x16x32_bf16 v[86:89], v[142:145], v[188:191], v[86:89]
	v_mfma_f32_16x16x32_bf16 v[78:81], v[156:159], v[188:191], v[78:81]
	v_mfma_f32_16x16x32_bf16 v[126:129], v[152:155], v[168:171], v[126:129]
	v_mfma_f32_16x16x32_bf16 v[122:125], v[160:163], v[168:171], v[122:125]
	v_mfma_f32_16x16x32_bf16 v[118:121], v[152:155], v[176:179], v[118:121]
	v_mfma_f32_16x16x32_bf16 v[110:113], v[160:163], v[176:179], v[110:113]
	v_mfma_f32_16x16x32_bf16 v[102:105], v[152:155], v[184:187], v[102:105]
	v_mfma_f32_16x16x32_bf16 v[94:97], v[160:163], v[184:187], v[94:97]
	v_mfma_f32_16x16x32_bf16 v[86:89], v[152:155], v[192:195], v[86:89]
	v_mfma_f32_16x16x32_bf16 v[78:81], v[160:163], v[192:195], v[78:81]
	s_setprio 0
	s_barrier
; #define PG8_STAGE(bufoff, gbase, voff) do { _Pragma("unroll") for (int _i = 0; _i < 2; ++_i) \
;         __builtin_amdgcn_global_load_lds((const unsigned*)((const char*)(gbase) + (voff)[_i]), (LAS unsigned*)(lds + (bufoff) + ldsw + _i * 8192), 16, 0, 0); } while (0)
; #define PG8_LDA(dst, b, h) do { _Pragma("unroll") for (int m = 0; m < 4; ++m) _Pragma("unroll") for (int k = 0; k < 2; ++k) dst[m][k] = *(const LAS bf16x8*)(lds + PG8_SA(b, h) + aoff + m * 2048 + k * 1024); } while (0)
; #define PG8_LDB(dst, b, h) do { _Pragma("unroll") for (int n = 0; n < 2; ++n) _Pragma("unroll") for (int k = 0; k < 2; ++k) dst[n][k] = *(const LAS bf16x8*)(lds + PG8_SB(b, h) + boff + n * 2048 + k * 1024); } while (0)
; #define PG8_MMA(ai, bj, At, Bt) do { __builtin_amdgcn_s_setprio(1); _Pragma("unroll") for (int m = 0; m < 4; ++m) _Pragma("unroll") for (int n = 0; n < 2; ++n) _Pragma("unroll") for (int k = 0; k < 2; ++k) \
;         acc[ai][bj][m][n] = __builtin_amdgcn_mfma_f32_16x16x32_bf16(Bt[n][k], At[m][k], acc[ai][bj][m][n], 0, 0, 0); __builtin_amdgcn_s_setprio(0); } while (0)
; #define PG8_WAIT_V(n) asm volatile("s_waitcnt vmcnt(" #n ")" ::: "memory")
; #define PG8_WAIT_L(n) asm volatile("s_waitcnt lgkmcnt(" #n ")" ::: "memory")
; #define PG8_BAR __builtin_amdgcn_s_barrier()
; #define PG8_SCHED __builtin_amdgcn_sched_barrier(0)
; template <class Epi, class Sched>
; __device__ __forceinline__ void gemm_phase(LAS unsigned char* lds, const Gemm g, const Sched& S, const Epi& E) {
;     ...
;             PG8_LDB(B1, 0, 1); PG8_STAGE(PG8_SB(0, 0), b2, voffB);
;             PG8_BAR; PG8_WAIT_L(0); PG8_MMA(0, 1, At, B1); PG8_BAR;
;             PG8_LDA(At, 0, 1); PG8_STAGE(PG8_SA(0, 0), a2, voffA);
;             PG8_BAR; PG8_WAIT_L(0); PG8_MMA(1, 0, At, B0); PG8_BAR; PG8_SCHED;
;             PG8_STAGE(PG8_SB(0, 1), b2 + hstepB, voffB);
;             PG8_WAIT_V(6); PG8_BAR; PG8_MMA(1, 1, At, B1); PG8_BAR;
;             PG8_LDB(B0, 1, 0); PG8_SCHED; PG8_LDA(At, 1, 0); PG8_STAGE(PG8_SA(0, 1), a2 + hstepA, voffA);
;             PG8_WAIT_L(8); PG8_BAR; PG8_WAIT_L(0); PG8_MMA(0, 0, At, B0); PG8_BAR; PG8_SCHED;
	s_add_i32 s63, 0, 0x14000
	s_add_i32 s22, s62, s49
	v_add_u32_e32 v0, s63, v148
	v_lshl_add_u64 v[208:209], s[42:43], 0, v[132:133]
	s_mov_b32 m0, s22
	ds_read_b128 v[196:199], v0
	ds_read_b128 v[200:203], v0 offset:1024
	ds_read_b128 v[204:207], v0 offset:2048
	ds_read_b128 v[224:227], v0 offset:3072
	global_load_lds_dwordx4 v[208:209], off
	v_lshl_add_u64 v[228:229], s[42:43], 0, v[136:137]
	s_add_i32 m0, s22, 0x2000
	s_nop 0
	global_load_lds_dwordx4 v[228:229], off
	s_waitcnt vmcnt(8)
	s_barrier
	s_waitcnt lgkmcnt(0)
	s_setprio 1
	s_waitcnt lgkmcnt(0)
	v_mfma_f32_16x16x32_bf16 v[114:117], v[196:199], v[164:167], v[114:117]
	v_mfma_f32_16x16x32_bf16 v[106:109], v[204:207], v[164:167], v[106:109]
	v_mfma_f32_16x16x32_bf16 v[98:101], v[196:199], v[172:175], v[98:101]
	v_mfma_f32_16x16x32_bf16 v[90:93], v[204:207], v[172:175], v[90:93]
	v_mfma_f32_16x16x32_bf16 v[82:85], v[196:199], v[180:183], v[82:85]
	v_mfma_f32_16x16x32_bf16 v[74:77], v[204:207], v[180:183], v[74:77]
	v_mfma_f32_16x16x32_bf16 v[70:73], v[196:199], v[188:191], v[70:73]
	v_mfma_f32_16x16x32_bf16 v[66:69], v[204:207], v[188:191], v[66:69]
	v_mfma_f32_16x16x32_bf16 v[114:117], v[200:203], v[168:171], v[114:117]
	v_mfma_f32_16x16x32_bf16 v[106:109], v[224:227], v[168:171], v[106:109]
	v_mfma_f32_16x16x32_bf16 v[98:101], v[200:203], v[176:179], v[98:101]
	v_mfma_f32_16x16x32_bf16 v[90:93], v[224:227], v[176:179], v[90:93]
	v_mfma_f32_16x16x32_bf16 v[82:85], v[200:203], v[184:187], v[82:85]
	v_mfma_f32_16x16x32_bf16 v[74:77], v[224:227], v[184:187], v[74:77]
	v_mfma_f32_16x16x32_bf16 v[70:73], v[200:203], v[192:195], v[70:73]
	v_mfma_f32_16x16x32_bf16 v[66:69], v[224:227], v[192:195], v[66:69]
	s_setprio 0
	s_mov_b32 m0, s50
	v_lshl_add_u64 v[230:231], s[44:45], 0, v[130:131]
	s_barrier
	ds_read_b128 v[164:167], v150 offset:16384
	ds_read_b128 v[168:171], v150 offset:17408
	ds_read_b128 v[172:175], v150 offset:18432
	ds_read_b128 v[176:179], v150 offset:19456
	ds_read_b128 v[180:183], v150 offset:20480
	ds_read_b128 v[184:187], v150 offset:21504
	ds_read_b128 v[188:191], v150 offset:22528
	ds_read_b128 v[192:195], v150 offset:23552
	global_load_lds_dwordx4 v[230:231], off
	v_lshl_add_u64 v[232:233], s[44:45], 0, v[134:135]
	s_mov_b32 m0, s51
	s_nop 0
	global_load_lds_dwordx4 v[232:233], off
	s_barrier
	s_waitcnt lgkmcnt(0)
	s_setprio 1
	s_waitcnt lgkmcnt(0)
	v_mfma_f32_16x16x32_bf16 v[62:65], v[142:145], v[164:167], v[62:65]
	v_mfma_f32_16x16x32_bf16 v[58:61], v[156:159], v[164:167], v[58:61]
	v_mfma_f32_16x16x32_bf16 v[54:57], v[142:145], v[172:175], v[54:57]
	v_mfma_f32_16x16x32_bf16 v[46:49], v[156:159], v[172:175], v[46:49]
	v_mfma_f32_16x16x32_bf16 v[38:41], v[142:145], v[180:183], v[38:41]
	v_mfma_f32_16x16x32_bf16 v[30:33], v[156:159], v[180:183], v[30:33]
	v_mfma_f32_16x16x32_bf16 v[14:17], v[142:145], v[188:191], v[14:17]
	v_mfma_f32_16x16x32_bf16 v[10:13], v[156:159], v[188:191], v[10:13]
	v_mfma_f32_16x16x32_bf16 v[62:65], v[152:155], v[168:171], v[62:65]
	v_mfma_f32_16x16x32_bf16 v[58:61], v[160:163], v[168:171], v[58:61]
	v_mfma_f32_16x16x32_bf16 v[54:57], v[152:155], v[176:179], v[54:57]
	v_mfma_f32_16x16x32_bf16 v[46:49], v[160:163], v[176:179], v[46:49]
	v_mfma_f32_16x16x32_bf16 v[38:41], v[152:155], v[184:187], v[38:41]
	v_mfma_f32_16x16x32_bf16 v[30:33], v[160:163], v[184:187], v[30:33]
	v_mfma_f32_16x16x32_bf16 v[14:17], v[152:155], v[192:195], v[14:17]
	v_mfma_f32_16x16x32_bf16 v[10:13], v[160:163], v[192:195], v[10:13]
	s_setprio 0
	s_barrier
	s_add_u32 s22, s42, 0x160000
	s_addc_u32 s23, s43, 0
	s_add_i32 s62, s63, s49
	v_lshl_add_u64 v[142:143], s[22:23], 0, v[132:133]
	s_mov_b32 m0, s62
	s_nop 0
	global_load_lds_dwordx4 v[142:143], off
	v_lshl_add_u64 v[142:143], s[22:23], 0, v[136:137]
	s_add_i32 m0, s62, 0x2000
	s_nop 0
	global_load_lds_dwordx4 v[142:143], off
	v_add_u32_e32 v0, 0x18000, v148
	ds_read_b128 v[142:145], v0
	ds_read_b128 v[152:155], v0 offset:1024
	ds_read_b128 v[156:159], v0 offset:2048
	ds_read_b128 v[160:163], v0 offset:3072
	s_waitcnt vmcnt(6)
	s_barrier
	s_setprio 1
	v_mfma_f32_16x16x32_bf16 v[50:53], v[196:199], v[164:167], v[50:53]
	v_mfma_f32_16x16x32_bf16 v[42:45], v[204:207], v[164:167], v[42:45]
	v_mfma_f32_16x16x32_bf16 v[34:37], v[196:199], v[172:175], v[34:37]
	v_mfma_f32_16x16x32_bf16 v[26:29], v[204:207], v[172:175], v[26:29]
	v_mfma_f32_16x16x32_bf16 v[22:25], v[196:199], v[180:183], v[22:25]
	v_mfma_f32_16x16x32_bf16 v[18:21], v[204:207], v[180:183], v[18:21]
	v_mfma_f32_16x16x32_bf16 v[6:9], v[196:199], v[188:191], v[6:9]
	v_mfma_f32_16x16x32_bf16 v[2:5], v[204:207], v[188:191], v[2:5]
	v_mfma_f32_16x16x32_bf16 v[50:53], v[200:203], v[168:171], v[50:53]
	v_mfma_f32_16x16x32_bf16 v[42:45], v[224:227], v[168:171], v[42:45]
	v_mfma_f32_16x16x32_bf16 v[34:37], v[200:203], v[176:179], v[34:37]
	v_mfma_f32_16x16x32_bf16 v[26:29], v[224:227], v[176:179], v[26:29]
	v_mfma_f32_16x16x32_bf16 v[22:25], v[200:203], v[184:187], v[22:25]
	v_mfma_f32_16x16x32_bf16 v[18:21], v[224:227], v[184:187], v[18:21]
	v_mfma_f32_16x16x32_bf16 v[6:9], v[200:203], v[192:195], v[6:9]
	v_mfma_f32_16x16x32_bf16 v[2:5], v[224:227], v[192:195], v[2:5]
	s_setprio 0
	s_add_i32 s62, 0, 0x18000
	v_add_u32_e32 v0, s62, v148
	s_barrier
	s_add_u32 s22, s44, 0x160000
	s_addc_u32 s23, s45, 0
	s_mov_b32 m0, s52
	v_lshl_add_u64 v[196:197], s[22:23], 0, v[130:131]
	ds_read_b128 v[164:167], v150 offset:32768
	ds_read_b128 v[168:171], v150 offset:33792
	ds_read_b128 v[172:175], v150 offset:34816
	ds_read_b128 v[176:179], v150 offset:35840
	ds_read_b128 v[180:183], v150 offset:36864
	ds_read_b128 v[184:187], v150 offset:37888
	ds_read_b128 v[188:191], v150 offset:38912
	ds_read_b128 v[192:195], v150 offset:39936
	global_load_lds_dwordx4 v[196:197], off
	v_lshl_add_u64 v[196:197], s[22:23], 0, v[134:135]
	s_mov_b32 m0, s53
	s_nop 0
	global_load_lds_dwordx4 v[196:197], off
	s_waitcnt lgkmcnt(8)
	s_barrier
; #define PG8_STAGE(bufoff, gbase, voff) do { _Pragma("unroll") for (int _i = 0; _i < 2; ++_i) \
;         __builtin_amdgcn_global_load_lds((const unsigned*)((const char*)(gbase) + (voff)[_i]), (LAS unsigned*)(lds + (bufoff) + ldsw + _i * 8192), 16, 0, 0); } while (0)
; #define PG8_LDA(dst, b, h) do { _Pragma("unroll") for (int m = 0; m < 4; ++m) _Pragma("unroll") for (int k = 0; k < 2; ++k) dst[m][k] = *(const LAS bf16x8*)(lds + PG8_SA(b, h) + aoff + m * 2048 + k * 1024); } while (0)
; #define PG8_LDB(dst, b, h) do { _Pragma("unroll") for (int n = 0; n < 2; ++n) _Pragma("unroll") for (int k = 0; k < 2; ++k) dst[n][k] = *(const LAS bf16x8*)(lds + PG8_SB(b, h) + boff + n * 2048 + k * 1024); } while (0)
; #define PG8_MMA(ai, bj, At, Bt) do { __builtin_amdgcn_s_setprio(1); _Pragma("unroll") for (int m = 0; m < 4; ++m) _Pragma("unroll") for (int n = 0; n < 2; ++n) _Pragma("unroll") for (int k = 0; k < 2; ++k) \
;         acc[ai][bj][m][n] = __builtin_amdgcn_mfma_f32_16x16x32_bf16(Bt[n][k], At[m][k], acc[ai][bj][m][n], 0, 0, 0); __builtin_amdgcn_s_setprio(0); } while (0)
; #define PG8_WAIT_V(n) asm volatile("s_waitcnt vmcnt(" #n ")" ::: "memory")
; #define PG8_WAIT_L(n) asm volatile("s_waitcnt lgkmcnt(" #n ")" ::: "memory")
; #define PG8_BAR __builtin_amdgcn_s_barrier()
; #define PG8_SCHED __builtin_amdgcn_sched_barrier(0)
; template <class Epi, class Sched>
; __device__ __forceinline__ void gemm_phase(LAS unsigned char* lds, const Gemm g, const Sched& S, const Epi& E) {
;     ...
;             PG8_WAIT_L(8); PG8_BAR; PG8_WAIT_L(0); PG8_MMA(0, 0, At, B0); PG8_BAR; PG8_SCHED;
;             PG8_LDB(B1, 1, 1); PG8_STAGE(PG8_SB(1, 0), b3, voffB);
;             PG8_BAR; PG8_WAIT_L(0); PG8_MMA(0, 1, At, B1); PG8_BAR;
;             PG8_LDA(At, 1, 1); PG8_STAGE(PG8_SA(1, 0), a3, voffA);
;             PG8_BAR; PG8_WAIT_L(0); PG8_MMA(1, 0, At, B0); PG8_BAR; PG8_SCHED;
;             PG8_STAGE(PG8_SB(1, 1), b3 + hstepB, voffB);
;             PG8_WAIT_V(6); PG8_BAR; PG8_MMA(1, 1, At, B1); PG8_BAR;
	s_waitcnt lgkmcnt(0)
	s_setprio 1
	s_waitcnt lgkmcnt(0)
	v_mfma_f32_16x16x32_bf16 v[126:129], v[142:145], v[164:167], v[126:129]
	v_mfma_f32_16x16x32_bf16 v[122:125], v[156:159], v[164:167], v[122:125]
	v_mfma_f32_16x16x32_bf16 v[118:121], v[142:145], v[172:175], v[118:121]
	v_mfma_f32_16x16x32_bf16 v[110:113], v[156:159], v[172:175], v[110:113]
	v_mfma_f32_16x16x32_bf16 v[102:105], v[142:145], v[180:183], v[102:105]
	v_mfma_f32_16x16x32_bf16 v[94:97], v[156:159], v[180:183], v[94:97]
	v_mfma_f32_16x16x32_bf16 v[86:89], v[142:145], v[188:191], v[86:89]
	v_mfma_f32_16x16x32_bf16 v[78:81], v[156:159], v[188:191], v[78:81]
	v_mfma_f32_16x16x32_bf16 v[126:129], v[152:155], v[168:171], v[126:129]
	v_mfma_f32_16x16x32_bf16 v[122:125], v[160:163], v[168:171], v[122:125]
	v_mfma_f32_16x16x32_bf16 v[118:121], v[152:155], v[176:179], v[118:121]
	v_mfma_f32_16x16x32_bf16 v[110:113], v[160:163], v[176:179], v[110:113]
	v_mfma_f32_16x16x32_bf16 v[102:105], v[152:155], v[184:187], v[102:105]
	v_mfma_f32_16x16x32_bf16 v[94:97], v[160:163], v[184:187], v[94:97]
	v_mfma_f32_16x16x32_bf16 v[86:89], v[152:155], v[192:195], v[86:89]
	v_mfma_f32_16x16x32_bf16 v[78:81], v[160:163], v[192:195], v[78:81]
	s_setprio 0
	s_barrier
	s_add_i32 s44, 0, 0x1c000
	s_add_i32 s22, s62, s49
	v_add_u32_e32 v0, s44, v148
	v_lshl_add_u64 v[208:209], v[208:209], 0, s[26:27]
	s_mov_b32 m0, s22
	ds_read_b128 v[196:199], v0
	ds_read_b128 v[200:203], v0 offset:1024
	ds_read_b128 v[204:207], v0 offset:2048
	ds_read_b128 v[224:227], v0 offset:3072
	global_load_lds_dwordx4 v[208:209], off
	v_lshl_add_u64 v[208:209], v[228:229], 0, s[26:27]
	s_add_i32 m0, s22, 0x2000
	s_nop 0
	global_load_lds_dwordx4 v[208:209], off
	s_waitcnt vmcnt(8)
	s_barrier
	s_waitcnt lgkmcnt(0)
	s_setprio 1
	s_waitcnt lgkmcnt(0)
	v_mfma_f32_16x16x32_bf16 v[114:117], v[196:199], v[164:167], v[114:117]
	v_mfma_f32_16x16x32_bf16 v[106:109], v[204:207], v[164:167], v[106:109]
	v_mfma_f32_16x16x32_bf16 v[98:101], v[196:199], v[172:175], v[98:101]
	v_mfma_f32_16x16x32_bf16 v[90:93], v[204:207], v[172:175], v[90:93]
	v_mfma_f32_16x16x32_bf16 v[82:85], v[196:199], v[180:183], v[82:85]
	v_mfma_f32_16x16x32_bf16 v[74:77], v[204:207], v[180:183], v[74:77]
	v_mfma_f32_16x16x32_bf16 v[70:73], v[196:199], v[188:191], v[70:73]
	v_mfma_f32_16x16x32_bf16 v[66:69], v[204:207], v[188:191], v[66:69]
	v_mfma_f32_16x16x32_bf16 v[114:117], v[200:203], v[168:171], v[114:117]
	v_mfma_f32_16x16x32_bf16 v[106:109], v[224:227], v[168:171], v[106:109]
	v_mfma_f32_16x16x32_bf16 v[98:101], v[200:203], v[176:179], v[98:101]
	v_mfma_f32_16x16x32_bf16 v[90:93], v[224:227], v[176:179], v[90:93]
	v_mfma_f32_16x16x32_bf16 v[82:85], v[200:203], v[184:187], v[82:85]
	v_mfma_f32_16x16x32_bf16 v[74:77], v[224:227], v[184:187], v[74:77]
	v_mfma_f32_16x16x32_bf16 v[70:73], v[200:203], v[192:195], v[70:73]
	v_mfma_f32_16x16x32_bf16 v[66:69], v[224:227], v[192:195], v[66:69]
	s_setprio 0
	s_mov_b32 m0, s54
	v_lshl_add_u64 v[208:209], v[230:231], 0, s[26:27]
	s_barrier
	ds_read_b128 v[164:167], v150 offset:49152
	ds_read_b128 v[168:171], v150 offset:50176
	ds_read_b128 v[172:175], v150 offset:51200
	ds_read_b128 v[176:179], v150 offset:52224
	ds_read_b128 v[180:183], v150 offset:53248
	ds_read_b128 v[184:187], v150 offset:54272
	ds_read_b128 v[188:191], v150 offset:55296
	ds_read_b128 v[192:195], v150 offset:56320
	global_load_lds_dwordx4 v[208:209], off
	v_lshl_add_u64 v[208:209], v[232:233], 0, s[26:27]
	s_mov_b32 m0, s55
	s_nop 0
	global_load_lds_dwordx4 v[208:209], off
	s_barrier
	s_waitcnt lgkmcnt(0)
	s_setprio 1
	s_waitcnt lgkmcnt(0)
	v_mfma_f32_16x16x32_bf16 v[62:65], v[142:145], v[164:167], v[62:65]
	v_mfma_f32_16x16x32_bf16 v[58:61], v[156:159], v[164:167], v[58:61]
	v_mfma_f32_16x16x32_bf16 v[54:57], v[142:145], v[172:175], v[54:57]
	v_mfma_f32_16x16x32_bf16 v[46:49], v[156:159], v[172:175], v[46:49]
	v_mfma_f32_16x16x32_bf16 v[38:41], v[142:145], v[180:183], v[38:41]
	v_mfma_f32_16x16x32_bf16 v[30:33], v[156:159], v[180:183], v[30:33]
	v_mfma_f32_16x16x32_bf16 v[14:17], v[142:145], v[188:191], v[14:17]
	v_mfma_f32_16x16x32_bf16 v[10:13], v[156:159], v[188:191], v[10:13]
	v_mfma_f32_16x16x32_bf16 v[62:65], v[152:155], v[168:171], v[62:65]
	v_mfma_f32_16x16x32_bf16 v[58:61], v[160:163], v[168:171], v[58:61]
	v_mfma_f32_16x16x32_bf16 v[54:57], v[152:155], v[176:179], v[54:57]
	v_mfma_f32_16x16x32_bf16 v[46:49], v[160:163], v[176:179], v[46:49]
	v_mfma_f32_16x16x32_bf16 v[38:41], v[152:155], v[184:187], v[38:41]
	v_mfma_f32_16x16x32_bf16 v[30:33], v[160:163], v[184:187], v[30:33]
	v_mfma_f32_16x16x32_bf16 v[14:17], v[152:155], v[192:195], v[14:17]
	v_mfma_f32_16x16x32_bf16 v[10:13], v[160:163], v[192:195], v[10:13]
	s_setprio 0
	s_barrier
	s_add_u32 s22, s42, 0x160080
	s_addc_u32 s23, s43, 0
	s_add_i32 s42, s44, s49
	v_lshl_add_u64 v[142:143], s[22:23], 0, v[132:133]
	s_mov_b32 m0, s42
	s_nop 0
	global_load_lds_dwordx4 v[142:143], off
	v_lshl_add_u64 v[142:143], s[22:23], 0, v[136:137]
	s_add_i32 m0, s42, 0x2000
	s_nop 0
	global_load_lds_dwordx4 v[142:143], off
	v_add_u32_e32 v0, 0x10000, v148
	ds_read_b128 v[142:145], v0
	ds_read_b128 v[152:155], v0 offset:1024
	ds_read_b128 v[156:159], v0 offset:2048
	ds_read_b128 v[160:163], v0 offset:3072
	s_waitcnt vmcnt(6)
	s_barrier
; #define PG8_MMA(ai, bj, At, Bt) do { __builtin_amdgcn_s_setprio(1); _Pragma("unroll") for (int m = 0; m < 4; ++m) _Pragma("unroll") for (int n = 0; n < 2; ++n) _Pragma("unroll") for (int k = 0; k < 2; ++k) \
;         acc[ai][bj][m][n] = __builtin_amdgcn_mfma_f32_16x16x32_bf16(Bt[n][k], At[m][k], acc[ai][bj][m][n], 0, 0, 0); __builtin_amdgcn_s_setprio(0); } while (0)
; #define PG8_WAIT_V(n) asm volatile("s_waitcnt vmcnt(" #n ")" ::: "memory")
; #define PG8_BAR __builtin_amdgcn_s_barrier()
; template <class Epi, class Sched>
; __device__ __forceinline__ void gemm_phase(LAS unsigned char* lds, const Gemm g, const Sched& S, const Epi& E) {
;     ...
;             PG8_WAIT_V(6); PG8_BAR; PG8_MMA(1, 1, At, B1); PG8_BAR;
;         }
;         E(acc, cur, wr, wc, fr, fq);
;         if (!has_next) break;
;     __device__ __forceinline__ void operator()(const AccT& acc, const pg8::Unit& u, int wr, int wc, int fr, int fq) const {
;     ...
; #pragma unroll
;         for (int ai = 0; ai < 2; ++ai)
; #pragma unroll
;             for (int m = 0; m < 4; ++m) { bf16_t* rowp = C + (size_t)(row0 + ai * 128 + m * 16) * DM + col0;
; #pragma unroll
;                 for (int bj = 0; bj < 2; ++bj) *(u32x4*)(rowp + bj * 128) = pack8s(acc[ai][bj][m][0], acc[ai][bj][m][1], 1.0f); }
	s_setprio 1
	v_mfma_f32_16x16x32_bf16 v[50:53], v[196:199], v[164:167], v[50:53]
	v_mfma_f32_16x16x32_bf16 v[42:45], v[204:207], v[164:167], v[42:45]
	v_mfma_f32_16x16x32_bf16 v[34:37], v[196:199], v[172:175], v[34:37]
	v_mfma_f32_16x16x32_bf16 v[26:29], v[204:207], v[172:175], v[26:29]
	v_mfma_f32_16x16x32_bf16 v[22:25], v[196:199], v[180:183], v[22:25]
	v_mfma_f32_16x16x32_bf16 v[18:21], v[204:207], v[180:183], v[18:21]
	v_mfma_f32_16x16x32_bf16 v[6:9], v[196:199], v[188:191], v[6:9]
	v_mfma_f32_16x16x32_bf16 v[2:5], v[204:207], v[188:191], v[2:5]
	v_mfma_f32_16x16x32_bf16 v[50:53], v[200:203], v[168:171], v[50:53]
	v_mfma_f32_16x16x32_bf16 v[42:45], v[224:227], v[168:171], v[42:45]
	v_mfma_f32_16x16x32_bf16 v[34:37], v[200:203], v[176:179], v[34:37]
	v_mfma_f32_16x16x32_bf16 v[26:29], v[224:227], v[176:179], v[26:29]
	v_mfma_f32_16x16x32_bf16 v[22:25], v[200:203], v[184:187], v[22:25]
	v_mfma_f32_16x16x32_bf16 v[18:21], v[224:227], v[184:187], v[18:21]
	v_mfma_f32_16x16x32_bf16 v[6:9], v[200:203], v[192:195], v[6:9]
	v_mfma_f32_16x16x32_bf16 v[2:5], v[224:227], v[192:195], v[2:5]
	s_setprio 0
	s_add_u32 s59, s59, 0x100
	s_addc_u32 s60, s60, 0
	s_cmp_ge_i32 s61, s57
	s_mov_b64 s[22:23], s[36:37]
	s_mov_b32 s42, s61
	s_barrier
	s_cbranch_scc0 .LBB0_372
	s_waitcnt lgkmcnt(0)
	v_lshl_or_b32 v142, s12, 8, v149
	s_cmp_gt_i32 s30, -1
	s_mov_b64 s[22:23], -1
	s_cbranch_scc1 .LBB0_375
	v_lshl_add_u32 v152, s25, 8, v147
	v_ashrrev_i32_e32 v153, 31, v152
	v_ashrrev_i32_e32 v143, 31, v142
	v_lshlrev_b64 v[144:145], 12, v[152:153]
	v_lshl_add_u64 v[144:145], s[8:9], 0, v[144:145]
	v_lshlrev_b64 v[154:155], 1, v[142:143]
	v_lshl_add_u64 v[144:145], v[144:145], 0, v[154:155]
	v_cvt_pk_bf16_f32 v126, v126, v127
	v_cvt_pk_bf16_f32 v127, v128, v129
	v_cvt_pk_bf16_f32 v128, v122, v123
	v_cvt_pk_bf16_f32 v129, v124, v125
	global_store_dwordx4 v[144:145], v[126:129], off
	v_cvt_pk_bf16_f32 v114, v114, v115
	v_cvt_pk_bf16_f32 v115, v116, v117
	v_cvt_pk_bf16_f32 v116, v106, v107
	v_or_b32_e32 v106, 16, v152
	v_ashrrev_i32_e32 v107, 31, v106
	v_lshlrev_b64 v[106:107], 12, v[106:107]
	v_lshl_add_u64 v[106:107], s[8:9], 0, v[106:107]
	v_cvt_pk_bf16_f32 v117, v108, v109
	global_store_dwordx4 v[144:145], v[114:117], off offset:256
	s_mov_b32 s12, 0x80000
	s_mov_b64 s[22:23], 0x80000
	v_lshl_add_u64 v[114:115], v[106:107], 0, v[154:155]
	v_cvt_pk_bf16_f32 v106, v118, v119
	v_cvt_pk_bf16_f32 v107, v120, v121
	v_cvt_pk_bf16_f32 v108, v110, v111
	v_cvt_pk_bf16_f32 v109, v112, v113
	global_store_dwordx4 v[114:115], v[106:109], off
	v_cvt_pk_bf16_f32 v98, v98, v99
	v_cvt_pk_bf16_f32 v99, v100, v101
	v_cvt_pk_bf16_f32 v100, v90, v91
	v_or_b32_e32 v90, 32, v152
	v_ashrrev_i32_e32 v91, 31, v90
	v_lshlrev_b64 v[90:91], 12, v[90:91]
	v_lshl_add_u64 v[90:91], s[8:9], 0, v[90:91]
	v_cvt_pk_bf16_f32 v101, v92, v93
	global_store_dwordx4 v[114:115], v[98:101], off offset:256
	s_nop 1
	v_lshl_add_u64 v[98:99], v[90:91], 0, v[154:155]
	v_cvt_pk_bf16_f32 v90, v102, v103
	v_cvt_pk_bf16_f32 v91, v104, v105
	v_cvt_pk_bf16_f32 v92, v94, v95
	v_cvt_pk_bf16_f32 v93, v96, v97
	global_store_dwordx4 v[98:99], v[90:93], off
	v_cvt_pk_bf16_f32 v82, v82, v83
	v_cvt_pk_bf16_f32 v83, v84, v85
	v_cvt_pk_bf16_f32 v84, v74, v75
	v_or_b32_e32 v74, 48, v152
	v_ashrrev_i32_e32 v75, 31, v74
	v_lshlrev_b64 v[74:75], 12, v[74:75]
	v_lshl_add_u64 v[74:75], s[8:9], 0, v[74:75]
	v_cvt_pk_bf16_f32 v85, v76, v77
	global_store_dwordx4 v[98:99], v[82:85], off offset:256
	s_nop 1
	v_lshl_add_u64 v[82:83], v[74:75], 0, v[154:155]
	v_cvt_pk_bf16_f32 v74, v86, v87
	v_cvt_pk_bf16_f32 v75, v88, v89
	v_cvt_pk_bf16_f32 v76, v78, v79
	v_cvt_pk_bf16_f32 v77, v80, v81
	global_store_dwordx4 v[82:83], v[74:77], off
	v_cvt_pk_bf16_f32 v70, v70, v71
	v_cvt_pk_bf16_f32 v71, v72, v73
	v_cvt_pk_bf16_f32 v72, v66, v67
	v_cvt_pk_bf16_f32 v73, v68, v69
	global_store_dwordx4 v[82:83], v[70:73], off offset:256
	v_cvt_pk_bf16_f32 v62, v62, v63
	v_cvt_pk_bf16_f32 v63, v64, v65
	v_cvt_pk_bf16_f32 v64, v58, v59
	v_add_co_u32_e32 v58, vcc, s12, v144
	v_lshl_add_u64 v[66:67], v[144:145], 0, s[22:23]
	s_nop 0
	v_addc_co_u32_e32 v59, vcc, 0, v145, vcc
	s_mov_b32 s12, 0x90000
	v_cvt_pk_bf16_f32 v65, v60, v61
	global_store_dwordx4 v[58:59], v[62:65], off
	v_cvt_pk_bf16_f32 v50, v50, v51
	v_cvt_pk_bf16_f32 v51, v52, v53
	v_cvt_pk_bf16_f32 v52, v42, v43
	v_cvt_pk_bf16_f32 v53, v44, v45
	global_store_dwordx4 v[66:67], v[50:53], off offset:256
	s_mov_b64 s[22:23], 0x90000
	v_cvt_pk_bf16_f32 v42, v54, v55
	v_cvt_pk_bf16_f32 v43, v56, v57
	v_cvt_pk_bf16_f32 v44, v46, v47
	v_add_co_u32_e32 v46, vcc, s12, v144
	v_lshl_add_u64 v[50:51], v[144:145], 0, s[22:23]
	s_nop 0
	v_addc_co_u32_e32 v47, vcc, 0, v145, vcc
	s_mov_b32 s12, 0xa0000
	v_cvt_pk_bf16_f32 v45, v48, v49
	global_store_dwordx4 v[46:47], v[42:45], off
	v_cvt_pk_bf16_f32 v34, v34, v35
	v_cvt_pk_bf16_f32 v35, v36, v37
	v_cvt_pk_bf16_f32 v36, v26, v27
	v_cvt_pk_bf16_f32 v37, v28, v29
	global_store_dwordx4 v[50:51], v[34:37], off offset:256
	v_cvt_pk_bf16_f32 v26, v38, v39
	v_cvt_pk_bf16_f32 v27, v40, v41
	v_cvt_pk_bf16_f32 v28, v30, v31
	v_add_co_u32_e32 v30, vcc, s12, v144
	s_mov_b64 s[22:23], 0xa0000
	s_nop 0
	v_addc_co_u32_e32 v31, vcc, 0, v145, vcc
	v_lshl_add_u64 v[34:35], v[144:145], 0, s[22:23]
	v_cvt_pk_bf16_f32 v29, v32, v33
	global_store_dwordx4 v[30:31], v[26:29], off
	v_cvt_pk_bf16_f32 v22, v22, v23
	v_cvt_pk_bf16_f32 v23, v24, v25
	v_cvt_pk_bf16_f32 v24, v18, v19
	s_mov_b32 s12, 0xb0000
	v_cvt_pk_bf16_f32 v25, v20, v21
	global_store_dwordx4 v[34:35], v[22:25], off offset:256
	s_mov_b64 s[22:23], 0xb0000
	v_cvt_pk_bf16_f32 v18, v14, v15
	v_cvt_pk_bf16_f32 v19, v16, v17
	v_cvt_pk_bf16_f32 v20, v10, v11
	v_cvt_pk_bf16_f32 v21, v12, v13
	s_nop 0
	v_add_co_u32_e32 v24, vcc, s12, v144
	v_lshl_add_u64 v[22:23], v[144:145], 0, s[22:23]
	s_nop 0
	v_addc_co_u32_e32 v25, vcc, 0, v145, vcc
	s_mov_b64 s[22:23], 0
	global_store_dwordx4 v[24:25], v[18:21], off
	s_nop 1
	v_cvt_pk_bf16_f32 v18, v6, v7
	v_cvt_pk_bf16_f32 v19, v8, v9
	v_cvt_pk_bf16_f32 v20, v2, v3
	v_cvt_pk_bf16_f32 v21, v4, v5
	global_store_dwordx4 v[22:23], v[18:21], off offset:256

; #define PG8_STAGE(bufoff, gbase, voff) do { _Pragma("unroll") for (int _i = 0; _i < 2; ++_i) \
;         __builtin_amdgcn_global_load_lds((const unsigned*)((const char*)(gbase) + (voff)[_i]), (LAS unsigned*)(lds + (bufoff) + ldsw + _i * 8192), 16, 0, 0); } while (0)
; #define PG8_LDA(dst, b, h) do { _Pragma("unroll") for (int m = 0; m < 4; ++m) _Pragma("unroll") for (int k = 0; k < 2; ++k) dst[m][k] = *(const LAS bf16x8*)(lds + PG8_SA(b, h) + aoff + m * 2048 + k * 1024); } while (0)
; #define PG8_LDB(dst, b, h) do { _Pragma("unroll") for (int n = 0; n < 2; ++n) _Pragma("unroll") for (int k = 0; k < 2; ++k) dst[n][k] = *(const LAS bf16x8*)(lds + PG8_SB(b, h) + boff + n * 2048 + k * 1024); } while (0)
; #define PG8_MMA(ai, bj, At, Bt) do { __builtin_amdgcn_s_setprio(1); _Pragma("unroll") for (int m = 0; m < 4; ++m) _Pragma("unroll") for (int n = 0; n < 2; ++n) _Pragma("unroll") for (int k = 0; k < 2; ++k) \
;         acc[ai][bj][m][n] = __builtin_amdgcn_mfma_f32_16x16x32_bf16(Bt[n][k], At[m][k], acc[ai][bj][m][n], 0, 0, 0); __builtin_amdgcn_s_setprio(0); } while (0)
; #define PG8_BAR __builtin_amdgcn_s_barrier()
; template <class Epi, class Sched>
; __device__ __forceinline__ void gemm_phase(LAS unsigned char* lds, const Gemm g, const Sched& S, const Epi& E) {
;     ...
;     for (;;) {
;         const bool has_next = S.next(ui + 1, nxt);
;         const char* nA = has_next ? PG8_APTR(nxt) : cA; const char* nB = has_next ? PG8_BPTR(nxt) : cB;
;         const int nt = cur.nt;
;         for (int t = 0; t < nt; t += 2) {
;             const bool last = (t == nt - 2);
;             const char* a1 = cA + (size_t)(t + 1) * kstep;
;             const char* a2 = last ? nA : cA + (size_t)(t + 2) * kstep; const char* b2 = last ? nB : cB + (size_t)(t + 2) * kstep;
;             const char* a3 = a2 + kstep; const char* b3 = b2 + kstep;
;             PG8_LDB(B0, 0, 0); PG8_SCHED; PG8_LDA(At, 0, 0); PG8_STAGE(PG8_SA(1, 1), a1 + hstepA, voffA);
;             PG8_WAIT_L(8); PG8_BAR; PG8_WAIT_L(0); PG8_MMA(0, 0, At, B0); PG8_BAR; PG8_SCHED;
;     ...
; #pragma unroll
;         for (int a = 0; a < 2; ++a)
; #pragma unroll
;             for (int b = 0; b < 2; ++b)
; #pragma unroll
;                 for (int m = 0; m < 4; ++m)
; #pragma unroll
;                     for (int n = 0; n < 2; ++n) acc[a][b][m][n] = (f32x4){0.f, 0.f, 0.f, 0.f};
;         cur = nxt; cA = nA; cB = nB; ++ui;
.LBB0_401:
	v_mov_b64_e32 v[2:3], 0x5ac
	s_ashr_i32 s11, s10, 31
	v_cmp_lt_i64_e32 vcc, s[16:17], v[2:3]
	s_lshl_b64 s[16:17], s[10:11], 20
	s_add_u32 s16, s24, s16
	s_addc_u32 s17, s28, s17
	s_and_b64 s[18:19], vcc, exec
	s_cselect_b32 s11, s17, s23
	s_cselect_b32 s45, s16, s22
	s_ashr_i32 s9, s8, 31
	s_lshl_b64 s[18:19], s[8:9], 20
	s_add_u32 s18, s29, s18
	s_addc_u32 s19, s30, s19
	s_and_b64 s[36:37], vcc, exec
	s_cselect_b32 s9, s19, s21
	s_cselect_b32 s47, s18, s20
	s_add_u32 s48, s20, 0x100
	s_addc_u32 s49, s21, 0
	s_add_u32 s20, s22, 0x80080
	v_mov_b32_e32 v2, 0
	s_addc_u32 s21, s23, 0
	s_mov_b32 s50, -2
	v_mov_b32_e32 v3, v2
	v_mov_b32_e32 v4, v2
	v_mov_b32_e32 v5, v2
	v_mov_b32_e32 v6, v2
	v_mov_b32_e32 v7, v2
	v_mov_b32_e32 v8, v2
	v_mov_b32_e32 v9, v2
	v_mov_b32_e32 v10, v2
	v_mov_b32_e32 v11, v2
	v_mov_b32_e32 v12, v2
	v_mov_b32_e32 v13, v2
	v_mov_b32_e32 v18, v2
	v_mov_b32_e32 v19, v2
	v_mov_b32_e32 v20, v2
	v_mov_b32_e32 v21, v2
	v_mov_b32_e32 v26, v2
	v_mov_b32_e32 v27, v2
	v_mov_b32_e32 v28, v2
	v_mov_b32_e32 v29, v2
	v_mov_b32_e32 v34, v2
	v_mov_b32_e32 v35, v2
	v_mov_b32_e32 v36, v2
	v_mov_b32_e32 v37, v2
	v_mov_b32_e32 v42, v2
	v_mov_b32_e32 v43, v2
	v_mov_b32_e32 v44, v2
	v_mov_b32_e32 v45, v2
	v_mov_b32_e32 v50, v2
	v_mov_b32_e32 v51, v2
	v_mov_b32_e32 v52, v2
	v_mov_b32_e32 v53, v2
	v_mov_b32_e32 v14, v2
	v_mov_b32_e32 v15, v2
	v_mov_b32_e32 v16, v2
	v_mov_b32_e32 v17, v2
	v_mov_b32_e32 v22, v2
	v_mov_b32_e32 v23, v2
	v_mov_b32_e32 v24, v2
	v_mov_b32_e32 v25, v2
	v_mov_b32_e32 v30, v2
	v_mov_b32_e32 v31, v2
	v_mov_b32_e32 v32, v2
	v_mov_b32_e32 v33, v2
	v_mov_b32_e32 v38, v2
	v_mov_b32_e32 v39, v2
	v_mov_b32_e32 v40, v2
	v_mov_b32_e32 v41, v2
	v_mov_b32_e32 v46, v2
	v_mov_b32_e32 v47, v2
	v_mov_b32_e32 v48, v2
	v_mov_b32_e32 v49, v2
	v_mov_b32_e32 v54, v2
	v_mov_b32_e32 v55, v2
	v_mov_b32_e32 v56, v2
	v_mov_b32_e32 v57, v2
	v_mov_b32_e32 v58, v2
	v_mov_b32_e32 v59, v2
	v_mov_b32_e32 v60, v2
	v_mov_b32_e32 v61, v2
	v_mov_b32_e32 v62, v2
	v_mov_b32_e32 v63, v2
	v_mov_b32_e32 v64, v2
	v_mov_b32_e32 v65, v2
	v_mov_b32_e32 v66, v2
	v_mov_b32_e32 v67, v2
	v_mov_b32_e32 v68, v2
	v_mov_b32_e32 v69, v2
	v_mov_b32_e32 v70, v2
	v_mov_b32_e32 v71, v2
	v_mov_b32_e32 v72, v2
	v_mov_b32_e32 v73, v2
	v_mov_b32_e32 v74, v2
	v_mov_b32_e32 v75, v2
	v_mov_b32_e32 v76, v2
	v_mov_b32_e32 v77, v2
	v_mov_b32_e32 v82, v2
	v_mov_b32_e32 v83, v2
	v_mov_b32_e32 v84, v2
	v_mov_b32_e32 v85, v2
	v_mov_b32_e32 v90, v2
	v_mov_b32_e32 v91, v2
	v_mov_b32_e32 v92, v2
	v_mov_b32_e32 v93, v2
	v_mov_b32_e32 v98, v2
	v_mov_b32_e32 v99, v2
	v_mov_b32_e32 v100, v2
	v_mov_b32_e32 v101, v2
	v_mov_b32_e32 v106, v2
	v_mov_b32_e32 v107, v2
	v_mov_b32_e32 v108, v2
	v_mov_b32_e32 v109, v2
	v_mov_b32_e32 v114, v2
	v_mov_b32_e32 v115, v2
	v_mov_b32_e32 v116, v2
	v_mov_b32_e32 v117, v2
	v_mov_b32_e32 v78, v2
	v_mov_b32_e32 v79, v2
	v_mov_b32_e32 v80, v2
	v_mov_b32_e32 v81, v2
	v_mov_b32_e32 v86, v2
	v_mov_b32_e32 v87, v2
	v_mov_b32_e32 v88, v2
	v_mov_b32_e32 v89, v2
	v_mov_b32_e32 v94, v2
	v_mov_b32_e32 v95, v2
	v_mov_b32_e32 v96, v2
	v_mov_b32_e32 v97, v2
	v_mov_b32_e32 v102, v2
	v_mov_b32_e32 v103, v2
	v_mov_b32_e32 v104, v2
	v_mov_b32_e32 v105, v2
	v_mov_b32_e32 v110, v2
	v_mov_b32_e32 v111, v2
	v_mov_b32_e32 v112, v2
	v_mov_b32_e32 v113, v2
	s_waitcnt lgkmcnt(0)
	v_mov_b32_e32 v118, v2
	v_mov_b32_e32 v119, v2
	v_mov_b32_e32 v120, v2
	v_mov_b32_e32 v121, v2
	v_mov_b32_e32 v122, v2
	v_mov_b32_e32 v123, v2
	v_mov_b32_e32 v124, v2
	v_mov_b32_e32 v125, v2
	v_mov_b32_e32 v126, v2
	v_mov_b32_e32 v127, v2
	v_mov_b32_e32 v128, v2
	v_mov_b32_e32 v129, v2
	v_add_u32_e32 v145, 0x10000, v143
	ds_read_b128 v[146:149], v145
	ds_read_b128 v[150:153], v145 offset:1024
	ds_read_b128 v[154:157], v145 offset:2048
	ds_read_b128 v[158:161], v145 offset:3072
.LBB0_402:
	s_add_u32 s22, s20, 0xfff80080
	s_addc_u32 s23, s21, -1
	s_add_i32 s51, 0, 0x10000
	v_add_u32_e32 v145, s51, v143
	s_cmp_eq_u32 s50, 28
	s_cselect_b32 s37, s11, s23
	s_cselect_b32 s36, s45, s22
	s_cselect_b32 s23, s9, s49
	s_cselect_b32 s22, s47, s48
	v_lshl_add_u64 v[194:195], s[20:21], 0, v[140:141]
	s_add_i32 m0, s33, 0xc000
	ds_read_b128 v[162:165], v144
	ds_read_b128 v[166:169], v144 offset:1024
	ds_read_b128 v[170:173], v144 offset:2048
	ds_read_b128 v[174:177], v144 offset:3072
	ds_read_b128 v[178:181], v144 offset:4096
	ds_read_b128 v[182:185], v144 offset:5120
	ds_read_b128 v[186:189], v144 offset:6144
	ds_read_b128 v[190:193], v144 offset:7168
	global_load_lds_dwordx4 v[194:195], off
	v_lshl_add_u64 v[194:195], s[20:21], 0, v[138:139]
	s_add_i32 m0, s33, 0xe000
	s_nop 0
	global_load_lds_dwordx4 v[194:195], off
	s_waitcnt lgkmcnt(8)
	s_barrier
	s_waitcnt lgkmcnt(0)
	s_setprio 1
	s_waitcnt lgkmcnt(0)
	v_mfma_f32_16x16x32_bf16 v[126:129], v[146:149], v[162:165], v[126:129]
	v_mfma_f32_16x16x32_bf16 v[122:125], v[154:157], v[162:165], v[122:125]
	v_mfma_f32_16x16x32_bf16 v[118:121], v[146:149], v[170:173], v[118:121]
	v_mfma_f32_16x16x32_bf16 v[110:113], v[154:157], v[170:173], v[110:113]
	v_mfma_f32_16x16x32_bf16 v[102:105], v[146:149], v[178:181], v[102:105]
	v_mfma_f32_16x16x32_bf16 v[94:97], v[154:157], v[178:181], v[94:97]
	v_mfma_f32_16x16x32_bf16 v[86:89], v[146:149], v[186:189], v[86:89]
	v_mfma_f32_16x16x32_bf16 v[78:81], v[154:157], v[186:189], v[78:81]
	v_mfma_f32_16x16x32_bf16 v[126:129], v[150:153], v[166:169], v[126:129]
	v_mfma_f32_16x16x32_bf16 v[122:125], v[158:161], v[166:169], v[122:125]
	v_mfma_f32_16x16x32_bf16 v[118:121], v[150:153], v[174:177], v[118:121]
	v_mfma_f32_16x16x32_bf16 v[110:113], v[158:161], v[174:177], v[110:113]
	v_mfma_f32_16x16x32_bf16 v[102:105], v[150:153], v[182:185], v[102:105]
	v_mfma_f32_16x16x32_bf16 v[94:97], v[158:161], v[182:185], v[94:97]
	v_mfma_f32_16x16x32_bf16 v[86:89], v[150:153], v[190:193], v[86:89]
	v_mfma_f32_16x16x32_bf16 v[78:81], v[158:161], v[190:193], v[78:81]
	s_setprio 0
	s_barrier
; #define PG8_STAGE(bufoff, gbase, voff) do { _Pragma("unroll") for (int _i = 0; _i < 2; ++_i) \
;         __builtin_amdgcn_global_load_lds((const unsigned*)((const char*)(gbase) + (voff)[_i]), (LAS unsigned*)(lds + (bufoff) + ldsw + _i * 8192), 16, 0, 0); } while (0)
; #define PG8_LDA(dst, b, h) do { _Pragma("unroll") for (int m = 0; m < 4; ++m) _Pragma("unroll") for (int k = 0; k < 2; ++k) dst[m][k] = *(const LAS bf16x8*)(lds + PG8_SA(b, h) + aoff + m * 2048 + k * 1024); } while (0)
; #define PG8_LDB(dst, b, h) do { _Pragma("unroll") for (int n = 0; n < 2; ++n) _Pragma("unroll") for (int k = 0; k < 2; ++k) dst[n][k] = *(const LAS bf16x8*)(lds + PG8_SB(b, h) + boff + n * 2048 + k * 1024); } while (0)
; #define PG8_MMA(ai, bj, At, Bt) do { __builtin_amdgcn_s_setprio(1); _Pragma("unroll") for (int m = 0; m < 4; ++m) _Pragma("unroll") for (int n = 0; n < 2; ++n) _Pragma("unroll") for (int k = 0; k < 2; ++k) \
;         acc[ai][bj][m][n] = __builtin_amdgcn_mfma_f32_16x16x32_bf16(Bt[n][k], At[m][k], acc[ai][bj][m][n], 0, 0, 0); __builtin_amdgcn_s_setprio(0); } while (0)
; #define PG8_WAIT_V(n) asm volatile("s_waitcnt vmcnt(" #n ")" ::: "memory")
; #define PG8_WAIT_L(n) asm volatile("s_waitcnt lgkmcnt(" #n ")" ::: "memory")
; #define PG8_BAR __builtin_amdgcn_s_barrier()
; #define PG8_SCHED __builtin_amdgcn_sched_barrier(0)
; template <class Epi, class Sched>
; __device__ __forceinline__ void gemm_phase(LAS unsigned char* lds, const Gemm g, const Sched& S, const Epi& E) {
;     ...
;             PG8_LDB(B1, 0, 1); PG8_STAGE(PG8_SB(0, 0), b2, voffB);
;             PG8_BAR; PG8_WAIT_L(0); PG8_MMA(0, 1, At, B1); PG8_BAR;
;             PG8_LDA(At, 0, 1); PG8_STAGE(PG8_SA(0, 0), a2, voffA);
;             PG8_BAR; PG8_WAIT_L(0); PG8_MMA(1, 0, At, B0); PG8_BAR; PG8_SCHED;
;             PG8_STAGE(PG8_SB(0, 1), b2 + hstepB, voffB);
;             PG8_WAIT_V(6); PG8_BAR; PG8_MMA(1, 1, At, B1); PG8_BAR;
;             PG8_LDB(B0, 1, 0); PG8_SCHED; PG8_LDA(At, 1, 0); PG8_STAGE(PG8_SA(0, 1), a2 + hstepA, voffA);
;             PG8_WAIT_L(8); PG8_BAR; PG8_WAIT_L(0); PG8_MMA(0, 0, At, B0); PG8_BAR; PG8_SCHED;
	s_add_i32 s54, 0, 0x14000
	s_add_i32 s51, s51, s31
	v_add_u32_e32 v145, s54, v143
	v_lshl_add_u64 v[224:225], s[22:23], 0, v[134:135]
	s_mov_b32 m0, s51
	ds_read_b128 v[194:197], v145
	ds_read_b128 v[198:201], v145 offset:1024
	ds_read_b128 v[202:205], v145 offset:2048
	ds_read_b128 v[206:209], v145 offset:3072
	global_load_lds_dwordx4 v[224:225], off
	v_lshl_add_u64 v[226:227], s[22:23], 0, v[130:131]
	s_add_i32 m0, s51, 0x2000
	s_nop 0
	global_load_lds_dwordx4 v[226:227], off
	s_waitcnt vmcnt(8)
	s_barrier
	s_waitcnt lgkmcnt(0)
	s_setprio 1
	s_waitcnt lgkmcnt(0)
	v_mfma_f32_16x16x32_bf16 v[114:117], v[194:197], v[162:165], v[114:117]
	v_mfma_f32_16x16x32_bf16 v[106:109], v[202:205], v[162:165], v[106:109]
	v_mfma_f32_16x16x32_bf16 v[98:101], v[194:197], v[170:173], v[98:101]
	v_mfma_f32_16x16x32_bf16 v[90:93], v[202:205], v[170:173], v[90:93]
	v_mfma_f32_16x16x32_bf16 v[82:85], v[194:197], v[178:181], v[82:85]
	v_mfma_f32_16x16x32_bf16 v[74:77], v[202:205], v[178:181], v[74:77]
	v_mfma_f32_16x16x32_bf16 v[70:73], v[194:197], v[186:189], v[70:73]
	v_mfma_f32_16x16x32_bf16 v[66:69], v[202:205], v[186:189], v[66:69]
	v_mfma_f32_16x16x32_bf16 v[114:117], v[198:201], v[166:169], v[114:117]
	v_mfma_f32_16x16x32_bf16 v[106:109], v[206:209], v[166:169], v[106:109]
	v_mfma_f32_16x16x32_bf16 v[98:101], v[198:201], v[174:177], v[98:101]
	v_mfma_f32_16x16x32_bf16 v[90:93], v[206:209], v[174:177], v[90:93]
	v_mfma_f32_16x16x32_bf16 v[82:85], v[198:201], v[182:185], v[82:85]
	v_mfma_f32_16x16x32_bf16 v[74:77], v[206:209], v[182:185], v[74:77]
	v_mfma_f32_16x16x32_bf16 v[70:73], v[198:201], v[190:193], v[70:73]
	v_mfma_f32_16x16x32_bf16 v[66:69], v[206:209], v[190:193], v[66:69]
	s_setprio 0
	s_mov_b32 m0, s33
	v_lshl_add_u64 v[228:229], s[36:37], 0, v[136:137]
	s_barrier
	ds_read_b128 v[162:165], v144 offset:16384
	ds_read_b128 v[166:169], v144 offset:17408
	ds_read_b128 v[170:173], v144 offset:18432
	ds_read_b128 v[174:177], v144 offset:19456
	ds_read_b128 v[178:181], v144 offset:20480
	ds_read_b128 v[182:185], v144 offset:21504
	ds_read_b128 v[186:189], v144 offset:22528
	ds_read_b128 v[190:193], v144 offset:23552
	global_load_lds_dwordx4 v[228:229], off
	v_lshl_add_u64 v[230:231], s[36:37], 0, v[132:133]
	s_mov_b32 m0, s12
	s_nop 0
	global_load_lds_dwordx4 v[230:231], off
	s_barrier
	s_waitcnt lgkmcnt(0)
	s_setprio 1
	s_waitcnt lgkmcnt(0)
	v_mfma_f32_16x16x32_bf16 v[62:65], v[146:149], v[162:165], v[62:65]
	v_mfma_f32_16x16x32_bf16 v[58:61], v[154:157], v[162:165], v[58:61]
	v_mfma_f32_16x16x32_bf16 v[54:57], v[146:149], v[170:173], v[54:57]
	v_mfma_f32_16x16x32_bf16 v[46:49], v[154:157], v[170:173], v[46:49]
	v_mfma_f32_16x16x32_bf16 v[38:41], v[146:149], v[178:181], v[38:41]
	v_mfma_f32_16x16x32_bf16 v[30:33], v[154:157], v[178:181], v[30:33]
	v_mfma_f32_16x16x32_bf16 v[22:25], v[146:149], v[186:189], v[22:25]
	v_mfma_f32_16x16x32_bf16 v[14:17], v[154:157], v[186:189], v[14:17]
	v_mfma_f32_16x16x32_bf16 v[62:65], v[150:153], v[166:169], v[62:65]
	v_mfma_f32_16x16x32_bf16 v[58:61], v[158:161], v[166:169], v[58:61]
	v_mfma_f32_16x16x32_bf16 v[54:57], v[150:153], v[174:177], v[54:57]
	v_mfma_f32_16x16x32_bf16 v[46:49], v[158:161], v[174:177], v[46:49]
	v_mfma_f32_16x16x32_bf16 v[38:41], v[150:153], v[182:185], v[38:41]
	v_mfma_f32_16x16x32_bf16 v[30:33], v[158:161], v[182:185], v[30:33]
	v_mfma_f32_16x16x32_bf16 v[22:25], v[150:153], v[190:193], v[22:25]
	v_mfma_f32_16x16x32_bf16 v[14:17], v[158:161], v[190:193], v[14:17]
	s_setprio 0
	s_barrier
	s_add_u32 s52, s22, 0x80000
	s_addc_u32 s53, s23, 0
	s_add_i32 s51, s54, s31
	v_lshl_add_u64 v[146:147], s[52:53], 0, v[134:135]
	s_mov_b32 m0, s51
	s_nop 0
	global_load_lds_dwordx4 v[146:147], off
	v_lshl_add_u64 v[146:147], s[52:53], 0, v[130:131]
	s_add_i32 m0, s51, 0x2000
	s_nop 0
	global_load_lds_dwordx4 v[146:147], off
	v_add_u32_e32 v145, 0x18000, v143
	ds_read_b128 v[146:149], v145
	ds_read_b128 v[150:153], v145 offset:1024
	ds_read_b128 v[154:157], v145 offset:2048
	ds_read_b128 v[158:161], v145 offset:3072
	s_waitcnt vmcnt(6)
	s_barrier
	s_setprio 1
	v_mfma_f32_16x16x32_bf16 v[50:53], v[194:197], v[162:165], v[50:53]
	v_mfma_f32_16x16x32_bf16 v[42:45], v[202:205], v[162:165], v[42:45]
	v_mfma_f32_16x16x32_bf16 v[34:37], v[194:197], v[170:173], v[34:37]
	v_mfma_f32_16x16x32_bf16 v[26:29], v[202:205], v[170:173], v[26:29]
	v_mfma_f32_16x16x32_bf16 v[18:21], v[194:197], v[178:181], v[18:21]
	v_mfma_f32_16x16x32_bf16 v[10:13], v[202:205], v[178:181], v[10:13]
	v_mfma_f32_16x16x32_bf16 v[6:9], v[194:197], v[186:189], v[6:9]
	v_mfma_f32_16x16x32_bf16 v[2:5], v[202:205], v[186:189], v[2:5]
	v_mfma_f32_16x16x32_bf16 v[50:53], v[198:201], v[166:169], v[50:53]
	v_mfma_f32_16x16x32_bf16 v[42:45], v[206:209], v[166:169], v[42:45]
	v_mfma_f32_16x16x32_bf16 v[34:37], v[198:201], v[174:177], v[34:37]
	v_mfma_f32_16x16x32_bf16 v[26:29], v[206:209], v[174:177], v[26:29]
	v_mfma_f32_16x16x32_bf16 v[18:21], v[198:201], v[182:185], v[18:21]
	v_mfma_f32_16x16x32_bf16 v[10:13], v[206:209], v[182:185], v[10:13]
	v_mfma_f32_16x16x32_bf16 v[6:9], v[198:201], v[190:193], v[6:9]
	v_mfma_f32_16x16x32_bf16 v[2:5], v[206:209], v[190:193], v[2:5]
	s_setprio 0
	s_add_i32 s51, 0, 0x18000
	v_add_u32_e32 v145, s51, v143
	s_barrier
	s_add_u32 s36, s36, 0x80000
	s_addc_u32 s37, s37, 0
	s_mov_b32 m0, s3
	v_lshl_add_u64 v[194:195], s[36:37], 0, v[136:137]
	ds_read_b128 v[162:165], v144 offset:32768
	ds_read_b128 v[166:169], v144 offset:33792
	ds_read_b128 v[170:173], v144 offset:34816
	ds_read_b128 v[174:177], v144 offset:35840
	ds_read_b128 v[178:181], v144 offset:36864
	ds_read_b128 v[182:185], v144 offset:37888
	ds_read_b128 v[186:189], v144 offset:38912
	ds_read_b128 v[190:193], v144 offset:39936
	global_load_lds_dwordx4 v[194:195], off
	v_lshl_add_u64 v[194:195], s[36:37], 0, v[132:133]
	s_mov_b32 m0, s6
	s_nop 0
	global_load_lds_dwordx4 v[194:195], off
	s_waitcnt lgkmcnt(8)
	s_barrier
; #define PG8_STAGE(bufoff, gbase, voff) do { _Pragma("unroll") for (int _i = 0; _i < 2; ++_i) \
;         __builtin_amdgcn_global_load_lds((const unsigned*)((const char*)(gbase) + (voff)[_i]), (LAS unsigned*)(lds + (bufoff) + ldsw + _i * 8192), 16, 0, 0); } while (0)
; #define PG8_LDA(dst, b, h) do { _Pragma("unroll") for (int m = 0; m < 4; ++m) _Pragma("unroll") for (int k = 0; k < 2; ++k) dst[m][k] = *(const LAS bf16x8*)(lds + PG8_SA(b, h) + aoff + m * 2048 + k * 1024); } while (0)
; #define PG8_LDB(dst, b, h) do { _Pragma("unroll") for (int n = 0; n < 2; ++n) _Pragma("unroll") for (int k = 0; k < 2; ++k) dst[n][k] = *(const LAS bf16x8*)(lds + PG8_SB(b, h) + boff + n * 2048 + k * 1024); } while (0)
; #define PG8_MMA(ai, bj, At, Bt) do { __builtin_amdgcn_s_setprio(1); _Pragma("unroll") for (int m = 0; m < 4; ++m) _Pragma("unroll") for (int n = 0; n < 2; ++n) _Pragma("unroll") for (int k = 0; k < 2; ++k) \
;         acc[ai][bj][m][n] = __builtin_amdgcn_mfma_f32_16x16x32_bf16(Bt[n][k], At[m][k], acc[ai][bj][m][n], 0, 0, 0); __builtin_amdgcn_s_setprio(0); } while (0)
; #define PG8_WAIT_V(n) asm volatile("s_waitcnt vmcnt(" #n ")" ::: "memory")
; #define PG8_WAIT_L(n) asm volatile("s_waitcnt lgkmcnt(" #n ")" ::: "memory")
; #define PG8_BAR __builtin_amdgcn_s_barrier()
; #define PG8_SCHED __builtin_amdgcn_sched_barrier(0)
; template <class Epi, class Sched>
; __device__ __forceinline__ void gemm_phase(LAS unsigned char* lds, const Gemm g, const Sched& S, const Epi& E) {
;     ...
;             PG8_WAIT_L(8); PG8_BAR; PG8_WAIT_L(0); PG8_MMA(0, 0, At, B0); PG8_BAR; PG8_SCHED;
;             PG8_LDB(B1, 1, 1); PG8_STAGE(PG8_SB(1, 0), b3, voffB);
;             PG8_BAR; PG8_WAIT_L(0); PG8_MMA(0, 1, At, B1); PG8_BAR;
;             PG8_LDA(At, 1, 1); PG8_STAGE(PG8_SA(1, 0), a3, voffA);
;             PG8_BAR; PG8_WAIT_L(0); PG8_MMA(1, 0, At, B0); PG8_BAR; PG8_SCHED;
;             PG8_STAGE(PG8_SB(1, 1), b3 + hstepB, voffB);
;             PG8_WAIT_V(6); PG8_BAR; PG8_MMA(1, 1, At, B1); PG8_BAR;
	s_waitcnt lgkmcnt(0)
	s_setprio 1
	s_waitcnt lgkmcnt(0)
	v_mfma_f32_16x16x32_bf16 v[126:129], v[146:149], v[162:165], v[126:129]
	v_mfma_f32_16x16x32_bf16 v[122:125], v[154:157], v[162:165], v[122:125]
	v_mfma_f32_16x16x32_bf16 v[118:121], v[146:149], v[170:173], v[118:121]
	v_mfma_f32_16x16x32_bf16 v[110:113], v[154:157], v[170:173], v[110:113]
	v_mfma_f32_16x16x32_bf16 v[102:105], v[146:149], v[178:181], v[102:105]
	v_mfma_f32_16x16x32_bf16 v[94:97], v[154:157], v[178:181], v[94:97]
	v_mfma_f32_16x16x32_bf16 v[86:89], v[146:149], v[186:189], v[86:89]
	v_mfma_f32_16x16x32_bf16 v[78:81], v[154:157], v[186:189], v[78:81]
	v_mfma_f32_16x16x32_bf16 v[126:129], v[150:153], v[166:169], v[126:129]
	v_mfma_f32_16x16x32_bf16 v[122:125], v[158:161], v[166:169], v[122:125]
	v_mfma_f32_16x16x32_bf16 v[118:121], v[150:153], v[174:177], v[118:121]
	v_mfma_f32_16x16x32_bf16 v[110:113], v[158:161], v[174:177], v[110:113]
	v_mfma_f32_16x16x32_bf16 v[102:105], v[150:153], v[182:185], v[102:105]
	v_mfma_f32_16x16x32_bf16 v[94:97], v[158:161], v[182:185], v[94:97]
	v_mfma_f32_16x16x32_bf16 v[86:89], v[150:153], v[190:193], v[86:89]
	v_mfma_f32_16x16x32_bf16 v[78:81], v[158:161], v[190:193], v[78:81]
	s_setprio 0
	s_barrier
	s_add_i32 s36, 0, 0x1c000
	s_add_i32 s37, s51, s31
	v_add_u32_e32 v145, s36, v143
	v_lshl_add_u64 v[224:225], v[224:225], 0, s[26:27]
	s_mov_b32 m0, s37
	ds_read_b128 v[194:197], v145
	ds_read_b128 v[198:201], v145 offset:1024
	ds_read_b128 v[202:205], v145 offset:2048
	ds_read_b128 v[206:209], v145 offset:3072
	global_load_lds_dwordx4 v[224:225], off
	v_lshl_add_u64 v[224:225], v[226:227], 0, s[26:27]
	s_add_i32 m0, s37, 0x2000
	s_nop 0
	global_load_lds_dwordx4 v[224:225], off
	s_waitcnt vmcnt(8)
	s_barrier
	s_waitcnt lgkmcnt(0)
	s_setprio 1
	s_waitcnt lgkmcnt(0)
	v_mfma_f32_16x16x32_bf16 v[114:117], v[194:197], v[162:165], v[114:117]
	v_mfma_f32_16x16x32_bf16 v[106:109], v[202:205], v[162:165], v[106:109]
	v_mfma_f32_16x16x32_bf16 v[98:101], v[194:197], v[170:173], v[98:101]
	v_mfma_f32_16x16x32_bf16 v[90:93], v[202:205], v[170:173], v[90:93]
	v_mfma_f32_16x16x32_bf16 v[82:85], v[194:197], v[178:181], v[82:85]
	v_mfma_f32_16x16x32_bf16 v[74:77], v[202:205], v[178:181], v[74:77]
	v_mfma_f32_16x16x32_bf16 v[70:73], v[194:197], v[186:189], v[70:73]
	v_mfma_f32_16x16x32_bf16 v[66:69], v[202:205], v[186:189], v[66:69]
	v_mfma_f32_16x16x32_bf16 v[114:117], v[198:201], v[166:169], v[114:117]
	v_mfma_f32_16x16x32_bf16 v[106:109], v[206:209], v[166:169], v[106:109]
	v_mfma_f32_16x16x32_bf16 v[98:101], v[198:201], v[174:177], v[98:101]
	v_mfma_f32_16x16x32_bf16 v[90:93], v[206:209], v[174:177], v[90:93]
	v_mfma_f32_16x16x32_bf16 v[82:85], v[198:201], v[182:185], v[82:85]
	v_mfma_f32_16x16x32_bf16 v[74:77], v[206:209], v[182:185], v[74:77]
	v_mfma_f32_16x16x32_bf16 v[70:73], v[198:201], v[190:193], v[70:73]
	v_mfma_f32_16x16x32_bf16 v[66:69], v[206:209], v[190:193], v[66:69]
	s_setprio 0
	s_mov_b32 m0, s7
	v_lshl_add_u64 v[224:225], v[228:229], 0, s[26:27]
	s_barrier
	ds_read_b128 v[162:165], v144 offset:49152
	ds_read_b128 v[166:169], v144 offset:50176
	ds_read_b128 v[170:173], v144 offset:51200
	ds_read_b128 v[174:177], v144 offset:52224
	ds_read_b128 v[178:181], v144 offset:53248
	ds_read_b128 v[182:185], v144 offset:54272
	ds_read_b128 v[186:189], v144 offset:55296
	ds_read_b128 v[190:193], v144 offset:56320
	global_load_lds_dwordx4 v[224:225], off
	v_lshl_add_u64 v[224:225], v[230:231], 0, s[26:27]
	s_mov_b32 m0, s25
	s_nop 0
	global_load_lds_dwordx4 v[224:225], off
	s_barrier
	s_waitcnt lgkmcnt(0)
	s_setprio 1
	s_waitcnt lgkmcnt(0)
	v_mfma_f32_16x16x32_bf16 v[62:65], v[146:149], v[162:165], v[62:65]
	v_mfma_f32_16x16x32_bf16 v[58:61], v[154:157], v[162:165], v[58:61]
	v_mfma_f32_16x16x32_bf16 v[54:57], v[146:149], v[170:173], v[54:57]
	v_mfma_f32_16x16x32_bf16 v[46:49], v[154:157], v[170:173], v[46:49]
	v_mfma_f32_16x16x32_bf16 v[38:41], v[146:149], v[178:181], v[38:41]
	v_mfma_f32_16x16x32_bf16 v[30:33], v[154:157], v[178:181], v[30:33]
	v_mfma_f32_16x16x32_bf16 v[22:25], v[146:149], v[186:189], v[22:25]
	v_mfma_f32_16x16x32_bf16 v[14:17], v[154:157], v[186:189], v[14:17]
	v_mfma_f32_16x16x32_bf16 v[62:65], v[150:153], v[166:169], v[62:65]
	v_mfma_f32_16x16x32_bf16 v[58:61], v[158:161], v[166:169], v[58:61]
	v_mfma_f32_16x16x32_bf16 v[54:57], v[150:153], v[174:177], v[54:57]
	v_mfma_f32_16x16x32_bf16 v[46:49], v[158:161], v[174:177], v[46:49]
	v_mfma_f32_16x16x32_bf16 v[38:41], v[150:153], v[182:185], v[38:41]
	v_mfma_f32_16x16x32_bf16 v[30:33], v[158:161], v[182:185], v[30:33]
	v_mfma_f32_16x16x32_bf16 v[22:25], v[150:153], v[190:193], v[22:25]
	v_mfma_f32_16x16x32_bf16 v[14:17], v[158:161], v[190:193], v[14:17]
	s_setprio 0
	s_barrier
	s_add_u32 s22, s22, 0x80080
	s_addc_u32 s23, s23, 0
	s_add_i32 s36, s36, s31
	v_lshl_add_u64 v[146:147], s[22:23], 0, v[134:135]
	s_mov_b32 m0, s36
	s_nop 0
	global_load_lds_dwordx4 v[146:147], off
	v_lshl_add_u64 v[146:147], s[22:23], 0, v[130:131]
	s_add_i32 m0, s36, 0x2000
	s_nop 0
	global_load_lds_dwordx4 v[146:147], off
	v_add_u32_e32 v145, 0x10000, v143
	ds_read_b128 v[146:149], v145
	ds_read_b128 v[150:153], v145 offset:1024
	ds_read_b128 v[154:157], v145 offset:2048
	ds_read_b128 v[158:161], v145 offset:3072
	s_waitcnt vmcnt(6)
	s_barrier
; #define PG8_WAIT_V(n) asm volatile("s_waitcnt vmcnt(" #n ")" ::: "memory")
; #define PG8_BAR __builtin_amdgcn_s_barrier()
; template <class Epi, class Sched>
; __device__ __forceinline__ void gemm_phase(LAS unsigned char* lds, const Gemm g, const Sched& S, const Epi& E) {
;     ...
;         cur = nxt; cA = nA; cB = nB; ++ui;
;     }
;     PG8_WAIT_V(0);
;     if (wr == 0) PG8_BAR;
;     PG8_BAR;
;     __device__ __forceinline__ void operator()(const AccT& acc, const pg8::Unit& u, int wr, int wc, int fr, int fq) const {
;     ...
; #pragma unroll
;         for (int ai = 0; ai < 2; ++ai)
; #pragma unroll
;             for (int m = 0; m < 4; ++m) {
;                 const int row = row0 + ai * 128 + m * 16;
;                 const float rs = 1.0f;
; #pragma unroll
;                 for (int bj = 0; bj < 2; ++bj)
;                     *(u32x4*)(U + (size_t)row * DFF2 + u.pn * 256 + bj * 128 + wc * 32 + 8 * fq) = pack8s(acc[ai][bj][m][0], acc[ai][bj][m][1], rs);
;             }
	s_setprio 1
	v_mfma_f32_16x16x32_bf16 v[50:53], v[194:197], v[162:165], v[50:53]
	v_mfma_f32_16x16x32_bf16 v[42:45], v[202:205], v[162:165], v[42:45]
	v_mfma_f32_16x16x32_bf16 v[34:37], v[194:197], v[170:173], v[34:37]
	v_mfma_f32_16x16x32_bf16 v[26:29], v[202:205], v[170:173], v[26:29]
	v_mfma_f32_16x16x32_bf16 v[18:21], v[194:197], v[178:181], v[18:21]
	v_mfma_f32_16x16x32_bf16 v[10:13], v[202:205], v[178:181], v[10:13]
	v_mfma_f32_16x16x32_bf16 v[6:9], v[194:197], v[186:189], v[6:9]
	v_mfma_f32_16x16x32_bf16 v[2:5], v[202:205], v[186:189], v[2:5]
	v_mfma_f32_16x16x32_bf16 v[50:53], v[198:201], v[166:169], v[50:53]
	v_mfma_f32_16x16x32_bf16 v[42:45], v[206:209], v[166:169], v[42:45]
	v_mfma_f32_16x16x32_bf16 v[34:37], v[198:201], v[174:177], v[34:37]
	v_mfma_f32_16x16x32_bf16 v[26:29], v[206:209], v[174:177], v[26:29]
	v_mfma_f32_16x16x32_bf16 v[18:21], v[198:201], v[182:185], v[18:21]
	v_mfma_f32_16x16x32_bf16 v[10:13], v[206:209], v[182:185], v[10:13]
	v_mfma_f32_16x16x32_bf16 v[6:9], v[198:201], v[190:193], v[6:9]
	v_mfma_f32_16x16x32_bf16 v[2:5], v[206:209], v[190:193], v[2:5]
	s_setprio 0
	s_add_i32 s50, s50, 2
	s_add_u32 s48, s48, 0x100
	s_addc_u32 s49, s49, 0
	s_add_u32 s20, s20, 0x100
	s_addc_u32 s21, s21, 0
	s_cmp_gt_u32 s50, 29
	s_barrier
	s_cbranch_scc0 .LBB0_402
	s_waitcnt lgkmcnt(0)
	s_lshl_b32 s20, s43, 8
	v_lshl_add_u32 v145, s44, 8, v142
	s_ashr_i32 s21, s20, 31
	v_cvt_pk_bf16_f32 v126, v126, v127
	v_cvt_pk_bf16_f32 v127, v128, v129
	v_cvt_pk_bf16_f32 v128, v122, v123
	v_mov_b64_e32 v[122:123], s[4:5]
	s_movk_i32 s9, 0x5800
	v_cvt_pk_bf16_f32 v129, v124, v125
	v_mad_i64_i32 v[124:125], s[22:23], v145, s9, v[122:123]
	s_lshl_b64 s[20:21], s[20:21], 1
	v_lshl_add_u64 v[124:125], v[124:125], 0, s[20:21]
	v_lshl_add_u64 v[124:125], v[124:125], 0, s[14:15]
	v_lshl_add_u64 v[124:125], v[124:125], 0, v[0:1]
	global_store_dwordx4 v[124:125], v[126:129], off
	v_cvt_pk_bf16_f32 v114, v114, v115
	v_cvt_pk_bf16_f32 v115, v116, v117
	v_cvt_pk_bf16_f32 v116, v106, v107
	v_cvt_pk_bf16_f32 v117, v108, v109
	global_store_dwordx4 v[124:125], v[114:117], off offset:256
	v_cvt_pk_bf16_f32 v106, v118, v119
	v_cvt_pk_bf16_f32 v107, v120, v121
	v_cvt_pk_bf16_f32 v108, v110, v111
	v_cvt_pk_bf16_f32 v109, v112, v113
	s_and_b64 vcc, exec, s[0:1]
	s_nop 0
	v_or_b32_e32 v114, 16, v145
	v_mad_i64_i32 v[110:111], s[22:23], v114, s9, v[122:123]
	v_lshl_add_u64 v[110:111], v[110:111], 0, s[20:21]
	v_lshl_add_u64 v[110:111], v[110:111], 0, s[14:15]
	v_lshl_add_u64 v[110:111], v[110:111], 0, v[0:1]
	global_store_dwordx4 v[110:111], v[106:109], off
	v_cvt_pk_bf16_f32 v98, v98, v99
	v_cvt_pk_bf16_f32 v99, v100, v101
	v_cvt_pk_bf16_f32 v100, v90, v91
	v_cvt_pk_bf16_f32 v101, v92, v93
	global_store_dwordx4 v[110:111], v[98:101], off offset:256
	v_cvt_pk_bf16_f32 v90, v102, v103
	v_cvt_pk_bf16_f32 v91, v104, v105
	v_cvt_pk_bf16_f32 v92, v94, v95
	v_cvt_pk_bf16_f32 v93, v96, v97
	s_mov_b32 s43, s8
	s_nop 0
	v_or_b32_e32 v98, 32, v145
	v_mad_i64_i32 v[94:95], s[22:23], v98, s9, v[122:123]
	v_lshl_add_u64 v[94:95], v[94:95], 0, s[20:21]
	v_lshl_add_u64 v[94:95], v[94:95], 0, s[14:15]
	v_lshl_add_u64 v[94:95], v[94:95], 0, v[0:1]
	global_store_dwordx4 v[94:95], v[90:93], off
	v_cvt_pk_bf16_f32 v82, v82, v83
	v_cvt_pk_bf16_f32 v83, v84, v85
	v_cvt_pk_bf16_f32 v84, v74, v75
	v_cvt_pk_bf16_f32 v85, v76, v77
	global_store_dwordx4 v[94:95], v[82:85], off offset:256
	v_cvt_pk_bf16_f32 v74, v86, v87
	v_cvt_pk_bf16_f32 v75, v88, v89
	v_cvt_pk_bf16_f32 v76, v78, v79
	v_cvt_pk_bf16_f32 v77, v80, v81
	s_mov_b32 s44, s10
	s_nop 0
	v_or_b32_e32 v82, 48, v145
	v_mad_i64_i32 v[78:79], s[22:23], v82, s9, v[122:123]
	v_lshl_add_u64 v[78:79], v[78:79], 0, s[20:21]
	v_lshl_add_u64 v[78:79], v[78:79], 0, s[14:15]
	v_lshl_add_u64 v[78:79], v[78:79], 0, v[0:1]
	global_store_dwordx4 v[78:79], v[74:77], off
	v_cvt_pk_bf16_f32 v70, v70, v71
	v_cvt_pk_bf16_f32 v71, v72, v73
	v_cvt_pk_bf16_f32 v72, v66, v67
	v_add_u32_e32 v66, 0x80, v145
	v_cvt_pk_bf16_f32 v73, v68, v69
	global_store_dwordx4 v[78:79], v[70:73], off offset:256
	v_cvt_pk_bf16_f32 v62, v62, v63
	v_cvt_pk_bf16_f32 v63, v64, v65
	v_cvt_pk_bf16_f32 v64, v58, v59
	v_mad_i64_i32 v[58:59], s[22:23], v66, s9, v[122:123]
	v_lshl_add_u64 v[58:59], v[58:59], 0, s[20:21]
	v_lshl_add_u64 v[58:59], v[58:59], 0, s[14:15]
	v_lshl_add_u64 v[58:59], v[58:59], 0, v[0:1]
	v_cvt_pk_bf16_f32 v65, v60, v61
	global_store_dwordx4 v[58:59], v[62:65], off
	v_cvt_pk_bf16_f32 v50, v50, v51
	v_cvt_pk_bf16_f32 v51, v52, v53
	v_cvt_pk_bf16_f32 v52, v42, v43
	v_cvt_pk_bf16_f32 v53, v44, v45
	global_store_dwordx4 v[58:59], v[50:53], off offset:256
	v_cvt_pk_bf16_f32 v42, v54, v55
	v_cvt_pk_bf16_f32 v43, v56, v57
	v_cvt_pk_bf16_f32 v44, v46, v47
	v_cvt_pk_bf16_f32 v45, v48, v49
	v_readlane_b32 s47, v254, 24
	s_nop 0
	v_add_u32_e32 v50, 0x90, v145
	v_mad_i64_i32 v[46:47], s[22:23], v50, s9, v[122:123]
	v_lshl_add_u64 v[46:47], v[46:47], 0, s[20:21]
	v_lshl_add_u64 v[46:47], v[46:47], 0, s[14:15]
	v_lshl_add_u64 v[46:47], v[46:47], 0, v[0:1]
	global_store_dwordx4 v[46:47], v[42:45], off
	v_cvt_pk_bf16_f32 v34, v34, v35
	v_cvt_pk_bf16_f32 v35, v36, v37
	v_cvt_pk_bf16_f32 v36, v26, v27
	v_cvt_pk_bf16_f32 v37, v28, v29
	global_store_dwordx4 v[46:47], v[34:37], off offset:256
	v_cvt_pk_bf16_f32 v26, v38, v39
	v_cvt_pk_bf16_f32 v27, v40, v41
	v_cvt_pk_bf16_f32 v28, v30, v31
	v_cvt_pk_bf16_f32 v29, v32, v33
	s_nop 1
	v_add_u32_e32 v34, 0xa0, v145
	v_mad_i64_i32 v[30:31], s[22:23], v34, s9, v[122:123]
	v_lshl_add_u64 v[30:31], v[30:31], 0, s[20:21]
	v_lshl_add_u64 v[30:31], v[30:31], 0, s[14:15]
	v_lshl_add_u64 v[30:31], v[30:31], 0, v[0:1]
	global_store_dwordx4 v[30:31], v[26:29], off
	v_cvt_pk_bf16_f32 v18, v18, v19
	v_cvt_pk_bf16_f32 v19, v20, v21
	v_cvt_pk_bf16_f32 v20, v10, v11
	v_cvt_pk_bf16_f32 v21, v12, v13
	global_store_dwordx4 v[30:31], v[18:21], off offset:256
	v_cvt_pk_bf16_f32 v10, v22, v23
	v_cvt_pk_bf16_f32 v11, v24, v25
	v_cvt_pk_bf16_f32 v12, v14, v15
	v_cvt_pk_bf16_f32 v13, v16, v17
	s_nop 1
	v_add_u32_e32 v18, 0xb0, v145
	v_mad_i64_i32 v[14:15], s[22:23], v18, s9, v[122:123]
	v_lshl_add_u64 v[14:15], v[14:15], 0, s[20:21]
	v_lshl_add_u64 v[14:15], v[14:15], 0, s[14:15]
	v_lshl_add_u64 v[14:15], v[14:15], 0, v[0:1]
	s_mov_b64 s[20:21], s[18:19]
	s_mov_b64 s[22:23], s[16:17]
	global_store_dwordx4 v[14:15], v[10:13], off
	v_cvt_pk_bf16_f32 v6, v6, v7
	v_cvt_pk_bf16_f32 v7, v8, v9
	v_cvt_pk_bf16_f32 v8, v2, v3
	v_cvt_pk_bf16_f32 v9, v4, v5
	global_store_dwordx4 v[14:15], v[6:9], off offset:256
	s_cbranch_vccz .LBB0_395
	s_waitcnt vmcnt(0)
	s_cmpk_gt_u32 s2, 0xff
	v_readlane_b32 s25, v254, 25
	s_cbranch_scc1 .LBB0_406
	s_barrier

; #define PG8_STAGE(bufoff, gbase, voff) do { _Pragma("unroll") for (int _i = 0; _i < 2; ++_i) \
;         __builtin_amdgcn_global_load_lds((const unsigned*)((const char*)(gbase) + (voff)[_i]), (LAS unsigned*)(lds + (bufoff) + ldsw + _i * 8192), 16, 0, 0); } while (0)
; #define PG8_LDA(dst, b, h) do { _Pragma("unroll") for (int m = 0; m < 4; ++m) _Pragma("unroll") for (int k = 0; k < 2; ++k) dst[m][k] = *(const LAS bf16x8*)(lds + PG8_SA(b, h) + aoff + m * 2048 + k * 1024); } while (0)
; #define PG8_LDB(dst, b, h) do { _Pragma("unroll") for (int n = 0; n < 2; ++n) _Pragma("unroll") for (int k = 0; k < 2; ++k) dst[n][k] = *(const LAS bf16x8*)(lds + PG8_SB(b, h) + boff + n * 2048 + k * 1024); } while (0)
; #define PG8_MMA(ai, bj, At, Bt) do { __builtin_amdgcn_s_setprio(1); _Pragma("unroll") for (int m = 0; m < 4; ++m) _Pragma("unroll") for (int n = 0; n < 2; ++n) _Pragma("unroll") for (int k = 0; k < 2; ++k) \
;         acc[ai][bj][m][n] = __builtin_amdgcn_mfma_f32_16x16x32_bf16(Bt[n][k], At[m][k], acc[ai][bj][m][n], 0, 0, 0); __builtin_amdgcn_s_setprio(0); } while (0)
; #define PG8_BAR __builtin_amdgcn_s_barrier()
; template <class Epi, class Sched>
; __device__ __forceinline__ void gemm_phase(LAS unsigned char* lds, const Gemm g, const Sched& S, const Epi& E) {
;     ...
;     for (;;) {
;         const bool has_next = S.next(ui + 1, nxt);
;         const char* nA = has_next ? PG8_APTR(nxt) : cA; const char* nB = has_next ? PG8_BPTR(nxt) : cB;
;         const int nt = cur.nt;
;         for (int t = 0; t < nt; t += 2) {
;             const bool last = (t == nt - 2);
;             const char* a1 = cA + (size_t)(t + 1) * kstep;
;             const char* a2 = last ? nA : cA + (size_t)(t + 2) * kstep; const char* b2 = last ? nB : cB + (size_t)(t + 2) * kstep;
;             const char* a3 = a2 + kstep; const char* b3 = b2 + kstep;
;             PG8_LDB(B0, 0, 0); PG8_SCHED; PG8_LDA(At, 0, 0); PG8_STAGE(PG8_SA(1, 1), a1 + hstepA, voffA);
;             PG8_WAIT_L(8); PG8_BAR; PG8_WAIT_L(0); PG8_MMA(0, 0, At, B0); PG8_BAR; PG8_SCHED;
;     ...
; #pragma unroll
;         for (int a = 0; a < 2; ++a)
; #pragma unroll
;             for (int b = 0; b < 2; ++b)
; #pragma unroll
;                 for (int m = 0; m < 4; ++m)
; #pragma unroll
;                     for (int n = 0; n < 2; ++n) acc[a][b][m][n] = (f32x4){0.f, 0.f, 0.f, 0.f};
;         cur = nxt; cA = nA; cB = nB; ++ui;
.LBB0_795:
	s_ashr_i32 s23, s22, 31
	s_xor_b64 s[38:39], s[46:47], -1
	s_lshl_b64 s[36:37], s[22:23], 20
	s_add_u32 s7, s14, s36
	s_addc_u32 s17, s24, s37
	s_ashr_i32 s19, s18, 31
	s_lshl_b64 s[40:41], s[18:19], 7
	s_add_u32 s36, s7, s40
	s_addc_u32 s37, s17, s41
	s_and_b64 s[52:53], s[46:47], exec
	s_cselect_b32 s7, s37, s45
	s_cselect_b32 s17, s36, s44
	s_ashr_i32 s21, s20, 31
	s_lshl_b64 s[52:53], s[20:21], 20
	s_add_u32 s19, s28, s52
	s_addc_u32 s21, s29, s53
	s_add_u32 s40, s19, s40
	s_addc_u32 s41, s21, s41
	s_and_b64 s[46:47], s[46:47], exec
	s_cselect_b32 s19, s41, s43
	s_cselect_b32 s21, s40, s42
	s_add_i32 s23, s12, -2
	s_add_u32 s25, s42, 0x100
	s_addc_u32 s52, s43, 0
	s_add_u32 s42, s44, 0x80080
	v_mov_b32_e32 v2, 0
	s_addc_u32 s43, s45, 0
	s_mov_b32 s44, 0
	v_mov_b32_e32 v3, v2
	v_mov_b32_e32 v4, v2
	v_mov_b32_e32 v5, v2
	v_mov_b32_e32 v6, v2
	v_mov_b32_e32 v7, v2
	v_mov_b32_e32 v8, v2
	v_mov_b32_e32 v9, v2
	v_mov_b32_e32 v18, v2
	v_mov_b32_e32 v19, v2
	v_mov_b32_e32 v20, v2
	v_mov_b32_e32 v21, v2
	v_mov_b32_e32 v22, v2
	v_mov_b32_e32 v23, v2
	v_mov_b32_e32 v24, v2
	v_mov_b32_e32 v25, v2
	v_mov_b32_e32 v26, v2
	v_mov_b32_e32 v27, v2
	v_mov_b32_e32 v28, v2
	v_mov_b32_e32 v29, v2
	v_mov_b32_e32 v34, v2
	v_mov_b32_e32 v35, v2
	v_mov_b32_e32 v36, v2
	v_mov_b32_e32 v37, v2
	v_mov_b32_e32 v42, v2
	v_mov_b32_e32 v43, v2
	v_mov_b32_e32 v44, v2
	v_mov_b32_e32 v45, v2
	v_mov_b32_e32 v50, v2
	v_mov_b32_e32 v51, v2
	v_mov_b32_e32 v52, v2
	v_mov_b32_e32 v53, v2
	v_mov_b32_e32 v10, v2
	v_mov_b32_e32 v11, v2
	v_mov_b32_e32 v12, v2
	v_mov_b32_e32 v13, v2
	v_mov_b32_e32 v14, v2
	v_mov_b32_e32 v15, v2
	v_mov_b32_e32 v16, v2
	v_mov_b32_e32 v17, v2
	v_mov_b32_e32 v30, v2
	v_mov_b32_e32 v31, v2
	v_mov_b32_e32 v32, v2
	v_mov_b32_e32 v33, v2
	v_mov_b32_e32 v38, v2
	v_mov_b32_e32 v39, v2
	v_mov_b32_e32 v40, v2
	v_mov_b32_e32 v41, v2
	v_mov_b32_e32 v46, v2
	v_mov_b32_e32 v47, v2
	v_mov_b32_e32 v48, v2
	v_mov_b32_e32 v49, v2
	v_mov_b32_e32 v54, v2
	v_mov_b32_e32 v55, v2
	v_mov_b32_e32 v56, v2
	v_mov_b32_e32 v57, v2
	v_mov_b32_e32 v58, v2
	v_mov_b32_e32 v59, v2
	v_mov_b32_e32 v60, v2
	v_mov_b32_e32 v61, v2
	v_mov_b32_e32 v62, v2
	v_mov_b32_e32 v63, v2
	v_mov_b32_e32 v64, v2
	v_mov_b32_e32 v65, v2
	v_mov_b32_e32 v66, v2
	v_mov_b32_e32 v67, v2
	v_mov_b32_e32 v68, v2
	v_mov_b32_e32 v69, v2
	v_mov_b32_e32 v70, v2
	v_mov_b32_e32 v71, v2
	v_mov_b32_e32 v72, v2
	v_mov_b32_e32 v73, v2
	v_mov_b32_e32 v74, v2
	v_mov_b32_e32 v75, v2
	v_mov_b32_e32 v76, v2
	v_mov_b32_e32 v77, v2
	v_mov_b32_e32 v82, v2
	v_mov_b32_e32 v83, v2
	v_mov_b32_e32 v84, v2
	v_mov_b32_e32 v85, v2
	v_mov_b32_e32 v90, v2
	v_mov_b32_e32 v91, v2
	v_mov_b32_e32 v92, v2
	v_mov_b32_e32 v93, v2
	v_mov_b32_e32 v98, v2
	v_mov_b32_e32 v99, v2
	v_mov_b32_e32 v100, v2
	v_mov_b32_e32 v101, v2
	v_mov_b32_e32 v106, v2
	v_mov_b32_e32 v107, v2
	v_mov_b32_e32 v108, v2
	v_mov_b32_e32 v109, v2
	v_mov_b32_e32 v114, v2
	v_mov_b32_e32 v115, v2
	v_mov_b32_e32 v116, v2
	v_mov_b32_e32 v117, v2
	v_mov_b32_e32 v78, v2
	v_mov_b32_e32 v79, v2
	v_mov_b32_e32 v80, v2
	v_mov_b32_e32 v81, v2
	v_mov_b32_e32 v86, v2
	v_mov_b32_e32 v87, v2
	v_mov_b32_e32 v88, v2
	v_mov_b32_e32 v89, v2
	v_mov_b32_e32 v94, v2
	v_mov_b32_e32 v95, v2
	v_mov_b32_e32 v96, v2
	v_mov_b32_e32 v97, v2
	v_mov_b32_e32 v102, v2
	v_mov_b32_e32 v103, v2
	v_mov_b32_e32 v104, v2
	v_mov_b32_e32 v105, v2
	v_mov_b32_e32 v110, v2
	v_mov_b32_e32 v111, v2
	v_mov_b32_e32 v112, v2
	v_mov_b32_e32 v113, v2
	s_waitcnt lgkmcnt(0)
	v_mov_b32_e32 v118, v2
	v_mov_b32_e32 v119, v2
	v_mov_b32_e32 v120, v2
	v_mov_b32_e32 v121, v2
	v_mov_b32_e32 v122, v2
	v_mov_b32_e32 v123, v2
	v_mov_b32_e32 v124, v2
	v_mov_b32_e32 v125, v2
	v_mov_b32_e32 v126, v2
	v_mov_b32_e32 v127, v2
	v_mov_b32_e32 v128, v2
	v_mov_b32_e32 v129, v2
	v_add_u32_e32 v0, 0x10000, v148
	ds_read_b128 v[142:145], v0
	ds_read_b128 v[152:155], v0 offset:1024
	ds_read_b128 v[156:159], v0 offset:2048
	ds_read_b128 v[160:163], v0 offset:3072
.LBB0_796:
	s_add_i32 s53, s44, 2
	s_add_u32 s45, s42, 0xfff80080
	s_addc_u32 s46, s43, -1
	s_add_i32 s54, 0, 0x10000
	v_add_u32_e32 v0, s54, v148
	s_cmp_eq_u32 s23, s44
	s_cselect_b32 s44, s21, s25
	s_cselect_b32 s47, s7, s46
	s_cselect_b32 s46, s17, s45
	s_cselect_b32 s45, s19, s52
	v_lshl_add_u64 v[196:197], s[42:43], 0, v[140:141]
	s_add_i32 m0, s11, 0xc000
	ds_read_b128 v[164:167], v150
	ds_read_b128 v[168:171], v150 offset:1024
	ds_read_b128 v[172:175], v150 offset:2048
	ds_read_b128 v[176:179], v150 offset:3072
	ds_read_b128 v[180:183], v150 offset:4096
	ds_read_b128 v[184:187], v150 offset:5120
	ds_read_b128 v[188:191], v150 offset:6144
	ds_read_b128 v[192:195], v150 offset:7168
	global_load_lds_dwordx4 v[196:197], off
	v_lshl_add_u64 v[196:197], s[42:43], 0, v[138:139]
	s_add_i32 m0, s11, 0xe000
	s_nop 0
	global_load_lds_dwordx4 v[196:197], off
	s_waitcnt lgkmcnt(8)
	s_barrier
	s_waitcnt lgkmcnt(0)
	s_setprio 1
	s_waitcnt lgkmcnt(0)
	v_mfma_f32_16x16x32_bf16 v[126:129], v[142:145], v[164:167], v[126:129]
	v_mfma_f32_16x16x32_bf16 v[122:125], v[156:159], v[164:167], v[122:125]
	v_mfma_f32_16x16x32_bf16 v[118:121], v[142:145], v[172:175], v[118:121]
	v_mfma_f32_16x16x32_bf16 v[110:113], v[156:159], v[172:175], v[110:113]
	v_mfma_f32_16x16x32_bf16 v[102:105], v[142:145], v[180:183], v[102:105]
	v_mfma_f32_16x16x32_bf16 v[94:97], v[156:159], v[180:183], v[94:97]
	v_mfma_f32_16x16x32_bf16 v[86:89], v[142:145], v[188:191], v[86:89]
	v_mfma_f32_16x16x32_bf16 v[78:81], v[156:159], v[188:191], v[78:81]
	v_mfma_f32_16x16x32_bf16 v[126:129], v[152:155], v[168:171], v[126:129]
	v_mfma_f32_16x16x32_bf16 v[122:125], v[160:163], v[168:171], v[122:125]
	v_mfma_f32_16x16x32_bf16 v[118:121], v[152:155], v[176:179], v[118:121]
	v_mfma_f32_16x16x32_bf16 v[110:113], v[160:163], v[176:179], v[110:113]
	v_mfma_f32_16x16x32_bf16 v[102:105], v[152:155], v[184:187], v[102:105]
	v_mfma_f32_16x16x32_bf16 v[94:97], v[160:163], v[184:187], v[94:97]
	v_mfma_f32_16x16x32_bf16 v[86:89], v[152:155], v[192:195], v[86:89]
	v_mfma_f32_16x16x32_bf16 v[78:81], v[160:163], v[192:195], v[78:81]
	s_setprio 0
	s_barrier
; #define PG8_STAGE(bufoff, gbase, voff) do { _Pragma("unroll") for (int _i = 0; _i < 2; ++_i) \
;         __builtin_amdgcn_global_load_lds((const unsigned*)((const char*)(gbase) + (voff)[_i]), (LAS unsigned*)(lds + (bufoff) + ldsw + _i * 8192), 16, 0, 0); } while (0)
; #define PG8_LDA(dst, b, h) do { _Pragma("unroll") for (int m = 0; m < 4; ++m) _Pragma("unroll") for (int k = 0; k < 2; ++k) dst[m][k] = *(const LAS bf16x8*)(lds + PG8_SA(b, h) + aoff + m * 2048 + k * 1024); } while (0)
; #define PG8_LDB(dst, b, h) do { _Pragma("unroll") for (int n = 0; n < 2; ++n) _Pragma("unroll") for (int k = 0; k < 2; ++k) dst[n][k] = *(const LAS bf16x8*)(lds + PG8_SB(b, h) + boff + n * 2048 + k * 1024); } while (0)
; #define PG8_MMA(ai, bj, At, Bt) do { __builtin_amdgcn_s_setprio(1); _Pragma("unroll") for (int m = 0; m < 4; ++m) _Pragma("unroll") for (int n = 0; n < 2; ++n) _Pragma("unroll") for (int k = 0; k < 2; ++k) \
;         acc[ai][bj][m][n] = __builtin_amdgcn_mfma_f32_16x16x32_bf16(Bt[n][k], At[m][k], acc[ai][bj][m][n], 0, 0, 0); __builtin_amdgcn_s_setprio(0); } while (0)
; #define PG8_WAIT_V(n) asm volatile("s_waitcnt vmcnt(" #n ")" ::: "memory")
; #define PG8_WAIT_L(n) asm volatile("s_waitcnt lgkmcnt(" #n ")" ::: "memory")
; #define PG8_BAR __builtin_amdgcn_s_barrier()
; #define PG8_SCHED __builtin_amdgcn_sched_barrier(0)
; template <class Epi, class Sched>
; __device__ __forceinline__ void gemm_phase(LAS unsigned char* lds, const Gemm g, const Sched& S, const Epi& E) {
;     ...
;             PG8_LDB(B1, 0, 1); PG8_STAGE(PG8_SB(0, 0), b2, voffB);
;             PG8_BAR; PG8_WAIT_L(0); PG8_MMA(0, 1, At, B1); PG8_BAR;
;             PG8_LDA(At, 0, 1); PG8_STAGE(PG8_SA(0, 0), a2, voffA);
;             PG8_BAR; PG8_WAIT_L(0); PG8_MMA(1, 0, At, B0); PG8_BAR; PG8_SCHED;
;             PG8_STAGE(PG8_SB(0, 1), b2 + hstepB, voffB);
;             PG8_WAIT_V(6); PG8_BAR; PG8_MMA(1, 1, At, B1); PG8_BAR;
;             PG8_LDB(B0, 1, 0); PG8_SCHED; PG8_LDA(At, 1, 0); PG8_STAGE(PG8_SA(0, 1), a2 + hstepA, voffA);
;             PG8_WAIT_L(8); PG8_BAR; PG8_WAIT_L(0); PG8_MMA(0, 0, At, B0); PG8_BAR; PG8_SCHED;
	s_add_i32 s56, 0, 0x14000
	s_add_i32 s54, s54, s30
	v_add_u32_e32 v0, s56, v148
	v_lshl_add_u64 v[208:209], s[44:45], 0, v[132:133]
	s_mov_b32 m0, s54
	ds_read_b128 v[196:199], v0
	ds_read_b128 v[200:203], v0 offset:1024
	ds_read_b128 v[204:207], v0 offset:2048
	ds_read_b128 v[224:227], v0 offset:3072
	global_load_lds_dwordx4 v[208:209], off
	v_lshl_add_u64 v[228:229], s[44:45], 0, v[136:137]
	s_add_i32 m0, s54, 0x2000
	s_nop 0
	global_load_lds_dwordx4 v[228:229], off
	s_waitcnt vmcnt(8)
	s_barrier
	s_waitcnt lgkmcnt(0)
	s_setprio 1
	s_waitcnt lgkmcnt(0)
	v_mfma_f32_16x16x32_bf16 v[114:117], v[196:199], v[164:167], v[114:117]
	v_mfma_f32_16x16x32_bf16 v[106:109], v[204:207], v[164:167], v[106:109]
	v_mfma_f32_16x16x32_bf16 v[98:101], v[196:199], v[172:175], v[98:101]
	v_mfma_f32_16x16x32_bf16 v[90:93], v[204:207], v[172:175], v[90:93]
	v_mfma_f32_16x16x32_bf16 v[82:85], v[196:199], v[180:183], v[82:85]
	v_mfma_f32_16x16x32_bf16 v[74:77], v[204:207], v[180:183], v[74:77]
	v_mfma_f32_16x16x32_bf16 v[70:73], v[196:199], v[188:191], v[70:73]
	v_mfma_f32_16x16x32_bf16 v[66:69], v[204:207], v[188:191], v[66:69]
	v_mfma_f32_16x16x32_bf16 v[114:117], v[200:203], v[168:171], v[114:117]
	v_mfma_f32_16x16x32_bf16 v[106:109], v[224:227], v[168:171], v[106:109]
	v_mfma_f32_16x16x32_bf16 v[98:101], v[200:203], v[176:179], v[98:101]
	v_mfma_f32_16x16x32_bf16 v[90:93], v[224:227], v[176:179], v[90:93]
	v_mfma_f32_16x16x32_bf16 v[82:85], v[200:203], v[184:187], v[82:85]
	v_mfma_f32_16x16x32_bf16 v[74:77], v[224:227], v[184:187], v[74:77]
	v_mfma_f32_16x16x32_bf16 v[70:73], v[200:203], v[192:195], v[70:73]
	v_mfma_f32_16x16x32_bf16 v[66:69], v[224:227], v[192:195], v[66:69]
	s_setprio 0
	s_mov_b32 m0, s11
	v_lshl_add_u64 v[230:231], s[46:47], 0, v[130:131]
	s_barrier
	ds_read_b128 v[164:167], v150 offset:16384
	ds_read_b128 v[168:171], v150 offset:17408
	ds_read_b128 v[172:175], v150 offset:18432
	ds_read_b128 v[176:179], v150 offset:19456
	ds_read_b128 v[180:183], v150 offset:20480
	ds_read_b128 v[184:187], v150 offset:21504
	ds_read_b128 v[188:191], v150 offset:22528
	ds_read_b128 v[192:195], v150 offset:23552
	global_load_lds_dwordx4 v[230:231], off
	v_lshl_add_u64 v[232:233], s[46:47], 0, v[134:135]
	s_mov_b32 m0, s31
	s_nop 0
	global_load_lds_dwordx4 v[232:233], off
	s_barrier
	s_waitcnt lgkmcnt(0)
	s_setprio 1
	s_waitcnt lgkmcnt(0)
	v_mfma_f32_16x16x32_bf16 v[62:65], v[142:145], v[164:167], v[62:65]
	v_mfma_f32_16x16x32_bf16 v[58:61], v[156:159], v[164:167], v[58:61]
	v_mfma_f32_16x16x32_bf16 v[54:57], v[142:145], v[172:175], v[54:57]
	v_mfma_f32_16x16x32_bf16 v[46:49], v[156:159], v[172:175], v[46:49]
	v_mfma_f32_16x16x32_bf16 v[38:41], v[142:145], v[180:183], v[38:41]
	v_mfma_f32_16x16x32_bf16 v[30:33], v[156:159], v[180:183], v[30:33]
	v_mfma_f32_16x16x32_bf16 v[14:17], v[142:145], v[188:191], v[14:17]
	v_mfma_f32_16x16x32_bf16 v[10:13], v[156:159], v[188:191], v[10:13]
	v_mfma_f32_16x16x32_bf16 v[62:65], v[152:155], v[168:171], v[62:65]
	v_mfma_f32_16x16x32_bf16 v[58:61], v[160:163], v[168:171], v[58:61]
	v_mfma_f32_16x16x32_bf16 v[54:57], v[152:155], v[176:179], v[54:57]
	v_mfma_f32_16x16x32_bf16 v[46:49], v[160:163], v[176:179], v[46:49]
	v_mfma_f32_16x16x32_bf16 v[38:41], v[152:155], v[184:187], v[38:41]
	v_mfma_f32_16x16x32_bf16 v[30:33], v[160:163], v[184:187], v[30:33]
	v_mfma_f32_16x16x32_bf16 v[14:17], v[152:155], v[192:195], v[14:17]
	v_mfma_f32_16x16x32_bf16 v[10:13], v[160:163], v[192:195], v[10:13]
	s_setprio 0
	s_barrier
	s_add_u32 s54, s44, 0x80000
	s_addc_u32 s55, s45, 0
	s_add_i32 s56, s56, s30
	v_lshl_add_u64 v[142:143], s[54:55], 0, v[132:133]
	s_mov_b32 m0, s56
	s_nop 0
	global_load_lds_dwordx4 v[142:143], off
	v_lshl_add_u64 v[142:143], s[54:55], 0, v[136:137]
	s_add_i32 m0, s56, 0x2000
	s_nop 0
	global_load_lds_dwordx4 v[142:143], off
	v_add_u32_e32 v0, 0x18000, v148
	ds_read_b128 v[142:145], v0
	ds_read_b128 v[152:155], v0 offset:1024
	ds_read_b128 v[156:159], v0 offset:2048
	ds_read_b128 v[160:163], v0 offset:3072
	s_waitcnt vmcnt(6)
	s_barrier
	s_setprio 1
	v_mfma_f32_16x16x32_bf16 v[50:53], v[196:199], v[164:167], v[50:53]
	v_mfma_f32_16x16x32_bf16 v[42:45], v[204:207], v[164:167], v[42:45]
	v_mfma_f32_16x16x32_bf16 v[34:37], v[196:199], v[172:175], v[34:37]
	v_mfma_f32_16x16x32_bf16 v[26:29], v[204:207], v[172:175], v[26:29]
	v_mfma_f32_16x16x32_bf16 v[22:25], v[196:199], v[180:183], v[22:25]
	v_mfma_f32_16x16x32_bf16 v[18:21], v[204:207], v[180:183], v[18:21]
	v_mfma_f32_16x16x32_bf16 v[6:9], v[196:199], v[188:191], v[6:9]
	v_mfma_f32_16x16x32_bf16 v[2:5], v[204:207], v[188:191], v[2:5]
	v_mfma_f32_16x16x32_bf16 v[50:53], v[200:203], v[168:171], v[50:53]
	v_mfma_f32_16x16x32_bf16 v[42:45], v[224:227], v[168:171], v[42:45]
	v_mfma_f32_16x16x32_bf16 v[34:37], v[200:203], v[176:179], v[34:37]
	v_mfma_f32_16x16x32_bf16 v[26:29], v[224:227], v[176:179], v[26:29]
	v_mfma_f32_16x16x32_bf16 v[22:25], v[200:203], v[184:187], v[22:25]
	v_mfma_f32_16x16x32_bf16 v[18:21], v[224:227], v[184:187], v[18:21]
	v_mfma_f32_16x16x32_bf16 v[6:9], v[200:203], v[192:195], v[6:9]
	v_mfma_f32_16x16x32_bf16 v[2:5], v[224:227], v[192:195], v[2:5]
	s_setprio 0
	s_add_i32 s54, 0, 0x18000
	v_add_u32_e32 v0, s54, v148
	s_barrier
	s_add_u32 s46, s46, 0x80000
	s_addc_u32 s47, s47, 0
	s_mov_b32 m0, s33
	v_lshl_add_u64 v[196:197], s[46:47], 0, v[130:131]
	ds_read_b128 v[164:167], v150 offset:32768
	ds_read_b128 v[168:171], v150 offset:33792
	ds_read_b128 v[172:175], v150 offset:34816
	ds_read_b128 v[176:179], v150 offset:35840
	ds_read_b128 v[180:183], v150 offset:36864
	ds_read_b128 v[184:187], v150 offset:37888
	ds_read_b128 v[188:191], v150 offset:38912
	ds_read_b128 v[192:195], v150 offset:39936
	global_load_lds_dwordx4 v[196:197], off
	v_lshl_add_u64 v[196:197], s[46:47], 0, v[134:135]
	s_mov_b32 m0, s48
	s_nop 0
	global_load_lds_dwordx4 v[196:197], off
	s_waitcnt lgkmcnt(8)
	s_barrier
; #define PG8_STAGE(bufoff, gbase, voff) do { _Pragma("unroll") for (int _i = 0; _i < 2; ++_i) \
;         __builtin_amdgcn_global_load_lds((const unsigned*)((const char*)(gbase) + (voff)[_i]), (LAS unsigned*)(lds + (bufoff) + ldsw + _i * 8192), 16, 0, 0); } while (0)
; #define PG8_LDA(dst, b, h) do { _Pragma("unroll") for (int m = 0; m < 4; ++m) _Pragma("unroll") for (int k = 0; k < 2; ++k) dst[m][k] = *(const LAS bf16x8*)(lds + PG8_SA(b, h) + aoff + m * 2048 + k * 1024); } while (0)
; #define PG8_LDB(dst, b, h) do { _Pragma("unroll") for (int n = 0; n < 2; ++n) _Pragma("unroll") for (int k = 0; k < 2; ++k) dst[n][k] = *(const LAS bf16x8*)(lds + PG8_SB(b, h) + boff + n * 2048 + k * 1024); } while (0)
; #define PG8_MMA(ai, bj, At, Bt) do { __builtin_amdgcn_s_setprio(1); _Pragma("unroll") for (int m = 0; m < 4; ++m) _Pragma("unroll") for (int n = 0; n < 2; ++n) _Pragma("unroll") for (int k = 0; k < 2; ++k) \
;         acc[ai][bj][m][n] = __builtin_amdgcn_mfma_f32_16x16x32_bf16(Bt[n][k], At[m][k], acc[ai][bj][m][n], 0, 0, 0); __builtin_amdgcn_s_setprio(0); } while (0)
; #define PG8_WAIT_V(n) asm volatile("s_waitcnt vmcnt(" #n ")" ::: "memory")
; #define PG8_WAIT_L(n) asm volatile("s_waitcnt lgkmcnt(" #n ")" ::: "memory")
; #define PG8_BAR __builtin_amdgcn_s_barrier()
; #define PG8_SCHED __builtin_amdgcn_sched_barrier(0)
; template <class Epi, class Sched>
; __device__ __forceinline__ void gemm_phase(LAS unsigned char* lds, const Gemm g, const Sched& S, const Epi& E) {
;     ...
;             PG8_WAIT_L(8); PG8_BAR; PG8_WAIT_L(0); PG8_MMA(0, 0, At, B0); PG8_BAR; PG8_SCHED;
;             PG8_LDB(B1, 1, 1); PG8_STAGE(PG8_SB(1, 0), b3, voffB);
;             PG8_BAR; PG8_WAIT_L(0); PG8_MMA(0, 1, At, B1); PG8_BAR;
;             PG8_LDA(At, 1, 1); PG8_STAGE(PG8_SA(1, 0), a3, voffA);
;             PG8_BAR; PG8_WAIT_L(0); PG8_MMA(1, 0, At, B0); PG8_BAR; PG8_SCHED;
;             PG8_STAGE(PG8_SB(1, 1), b3 + hstepB, voffB);
;             PG8_WAIT_V(6); PG8_BAR; PG8_MMA(1, 1, At, B1); PG8_BAR;
	s_waitcnt lgkmcnt(0)
	s_setprio 1
	s_waitcnt lgkmcnt(0)
	v_mfma_f32_16x16x32_bf16 v[126:129], v[142:145], v[164:167], v[126:129]
	v_mfma_f32_16x16x32_bf16 v[122:125], v[156:159], v[164:167], v[122:125]
	v_mfma_f32_16x16x32_bf16 v[118:121], v[142:145], v[172:175], v[118:121]
	v_mfma_f32_16x16x32_bf16 v[110:113], v[156:159], v[172:175], v[110:113]
	v_mfma_f32_16x16x32_bf16 v[102:105], v[142:145], v[180:183], v[102:105]
	v_mfma_f32_16x16x32_bf16 v[94:97], v[156:159], v[180:183], v[94:97]
	v_mfma_f32_16x16x32_bf16 v[86:89], v[142:145], v[188:191], v[86:89]
	v_mfma_f32_16x16x32_bf16 v[78:81], v[156:159], v[188:191], v[78:81]
	v_mfma_f32_16x16x32_bf16 v[126:129], v[152:155], v[168:171], v[126:129]
	v_mfma_f32_16x16x32_bf16 v[122:125], v[160:163], v[168:171], v[122:125]
	v_mfma_f32_16x16x32_bf16 v[118:121], v[152:155], v[176:179], v[118:121]
	v_mfma_f32_16x16x32_bf16 v[110:113], v[160:163], v[176:179], v[110:113]
	v_mfma_f32_16x16x32_bf16 v[102:105], v[152:155], v[184:187], v[102:105]
	v_mfma_f32_16x16x32_bf16 v[94:97], v[160:163], v[184:187], v[94:97]
	v_mfma_f32_16x16x32_bf16 v[86:89], v[152:155], v[192:195], v[86:89]
	v_mfma_f32_16x16x32_bf16 v[78:81], v[160:163], v[192:195], v[78:81]
	s_setprio 0
	s_barrier
	s_add_i32 s46, 0, 0x1c000
	s_add_i32 s47, s54, s30
	v_add_u32_e32 v0, s46, v148
	v_lshl_add_u64 v[208:209], v[208:209], 0, s[26:27]
	s_mov_b32 m0, s47
	ds_read_b128 v[196:199], v0
	ds_read_b128 v[200:203], v0 offset:1024
	ds_read_b128 v[204:207], v0 offset:2048
	ds_read_b128 v[224:227], v0 offset:3072
	global_load_lds_dwordx4 v[208:209], off
	v_lshl_add_u64 v[208:209], v[228:229], 0, s[26:27]
	s_add_i32 m0, s47, 0x2000
	s_nop 0
	global_load_lds_dwordx4 v[208:209], off
	s_waitcnt vmcnt(8)
	s_barrier
	s_waitcnt lgkmcnt(0)
	s_setprio 1
	s_waitcnt lgkmcnt(0)
	v_mfma_f32_16x16x32_bf16 v[114:117], v[196:199], v[164:167], v[114:117]
	v_mfma_f32_16x16x32_bf16 v[106:109], v[204:207], v[164:167], v[106:109]
	v_mfma_f32_16x16x32_bf16 v[98:101], v[196:199], v[172:175], v[98:101]
	v_mfma_f32_16x16x32_bf16 v[90:93], v[204:207], v[172:175], v[90:93]
	v_mfma_f32_16x16x32_bf16 v[82:85], v[196:199], v[180:183], v[82:85]
	v_mfma_f32_16x16x32_bf16 v[74:77], v[204:207], v[180:183], v[74:77]
	v_mfma_f32_16x16x32_bf16 v[70:73], v[196:199], v[188:191], v[70:73]
	v_mfma_f32_16x16x32_bf16 v[66:69], v[204:207], v[188:191], v[66:69]
	v_mfma_f32_16x16x32_bf16 v[114:117], v[200:203], v[168:171], v[114:117]
	v_mfma_f32_16x16x32_bf16 v[106:109], v[224:227], v[168:171], v[106:109]
	v_mfma_f32_16x16x32_bf16 v[98:101], v[200:203], v[176:179], v[98:101]
	v_mfma_f32_16x16x32_bf16 v[90:93], v[224:227], v[176:179], v[90:93]
	v_mfma_f32_16x16x32_bf16 v[82:85], v[200:203], v[184:187], v[82:85]
	v_mfma_f32_16x16x32_bf16 v[74:77], v[224:227], v[184:187], v[74:77]
	v_mfma_f32_16x16x32_bf16 v[70:73], v[200:203], v[192:195], v[70:73]
	v_mfma_f32_16x16x32_bf16 v[66:69], v[224:227], v[192:195], v[66:69]
	s_setprio 0
	s_mov_b32 m0, s49
	v_lshl_add_u64 v[208:209], v[230:231], 0, s[26:27]
	s_barrier
	ds_read_b128 v[164:167], v150 offset:49152
	ds_read_b128 v[168:171], v150 offset:50176
	ds_read_b128 v[172:175], v150 offset:51200
	ds_read_b128 v[176:179], v150 offset:52224
	ds_read_b128 v[180:183], v150 offset:53248
	ds_read_b128 v[184:187], v150 offset:54272
	ds_read_b128 v[188:191], v150 offset:55296
	ds_read_b128 v[192:195], v150 offset:56320
	global_load_lds_dwordx4 v[208:209], off
	v_lshl_add_u64 v[208:209], v[232:233], 0, s[26:27]
	s_mov_b32 m0, s50
	s_nop 0
	global_load_lds_dwordx4 v[208:209], off
	s_barrier
	s_waitcnt lgkmcnt(0)
	s_setprio 1
	s_waitcnt lgkmcnt(0)
	v_mfma_f32_16x16x32_bf16 v[62:65], v[142:145], v[164:167], v[62:65]
	v_mfma_f32_16x16x32_bf16 v[58:61], v[156:159], v[164:167], v[58:61]
	v_mfma_f32_16x16x32_bf16 v[54:57], v[142:145], v[172:175], v[54:57]
	v_mfma_f32_16x16x32_bf16 v[46:49], v[156:159], v[172:175], v[46:49]
	v_mfma_f32_16x16x32_bf16 v[38:41], v[142:145], v[180:183], v[38:41]
	v_mfma_f32_16x16x32_bf16 v[30:33], v[156:159], v[180:183], v[30:33]
	v_mfma_f32_16x16x32_bf16 v[14:17], v[142:145], v[188:191], v[14:17]
	v_mfma_f32_16x16x32_bf16 v[10:13], v[156:159], v[188:191], v[10:13]
	v_mfma_f32_16x16x32_bf16 v[62:65], v[152:155], v[168:171], v[62:65]
	v_mfma_f32_16x16x32_bf16 v[58:61], v[160:163], v[168:171], v[58:61]
	v_mfma_f32_16x16x32_bf16 v[54:57], v[152:155], v[176:179], v[54:57]
	v_mfma_f32_16x16x32_bf16 v[46:49], v[160:163], v[176:179], v[46:49]
	v_mfma_f32_16x16x32_bf16 v[38:41], v[152:155], v[184:187], v[38:41]
	v_mfma_f32_16x16x32_bf16 v[30:33], v[160:163], v[184:187], v[30:33]
	v_mfma_f32_16x16x32_bf16 v[14:17], v[152:155], v[192:195], v[14:17]
	v_mfma_f32_16x16x32_bf16 v[10:13], v[160:163], v[192:195], v[10:13]
	s_setprio 0
	s_barrier
	s_add_u32 s44, s44, 0x80080
	s_addc_u32 s45, s45, 0
	s_add_i32 s46, s46, s30
	v_lshl_add_u64 v[142:143], s[44:45], 0, v[132:133]
	s_mov_b32 m0, s46
	s_nop 0
	global_load_lds_dwordx4 v[142:143], off
	v_lshl_add_u64 v[142:143], s[44:45], 0, v[136:137]
	s_add_i32 m0, s46, 0x2000
	s_nop 0
	global_load_lds_dwordx4 v[142:143], off
	v_add_u32_e32 v0, 0x10000, v148
	ds_read_b128 v[142:145], v0
	ds_read_b128 v[152:155], v0 offset:1024
	ds_read_b128 v[156:159], v0 offset:2048
	ds_read_b128 v[160:163], v0 offset:3072
	s_waitcnt vmcnt(6)
	s_barrier
; #define PG8_MMA(ai, bj, At, Bt) do { __builtin_amdgcn_s_setprio(1); _Pragma("unroll") for (int m = 0; m < 4; ++m) _Pragma("unroll") for (int n = 0; n < 2; ++n) _Pragma("unroll") for (int k = 0; k < 2; ++k) \
;         acc[ai][bj][m][n] = __builtin_amdgcn_mfma_f32_16x16x32_bf16(Bt[n][k], At[m][k], acc[ai][bj][m][n], 0, 0, 0); __builtin_amdgcn_s_setprio(0); } while (0)
; #define PG8_WAIT_V(n) asm volatile("s_waitcnt vmcnt(" #n ")" ::: "memory")
; #define PG8_BAR __builtin_amdgcn_s_barrier()
; template <class Epi, class Sched>
; __device__ __forceinline__ void gemm_phase(LAS unsigned char* lds, const Gemm g, const Sched& S, const Epi& E) {
;     ...
;             PG8_WAIT_V(6); PG8_BAR; PG8_MMA(1, 1, At, B1); PG8_BAR;
;         }
;         E(acc, cur, wr, wc, fr, fq);
;         if (!has_next) break;
;     __device__ __forceinline__ void operator()(const AccT& acc, const pg8::Unit& u, int wr, int wc, int fr, int fq) const {
;         const int row0 = u.pm * 256 + wr * 64 + fr, col0 = u.pn * 256 + wc * 32 + 8 * fq;
;         if (u.part >= 0) {
;             if (wr == 1) { float* rowp = Part + (size_t)(u.part * 16 + fr) * DM + col0;
; #pragma unroll
;                 for (int bj = 0; bj < 2; ++bj)
; #pragma unroll
;                     for (int n = 0; n < 2; ++n) *(f32x4*)(rowp + bj * 128 + n * 4) = acc[1][bj][3][n]; }
;             return;
;         }
; #pragma unroll
;         for (int ai = 0; ai < 2; ++ai)
; #pragma unroll
;             for (int m = 0; m < 4; ++m) { bf16_t* rowp = C + (size_t)(row0 + ai * 128 + m * 16) * DM + col0;
; #pragma unroll
;                 for (int bj = 0; bj < 2; ++bj) *(u32x4*)(rowp + bj * 128) = pack8s(acc[ai][bj][m][0], acc[ai][bj][m][1], 1.0f); }
	s_setprio 1
	v_mfma_f32_16x16x32_bf16 v[50:53], v[196:199], v[164:167], v[50:53]
	v_mfma_f32_16x16x32_bf16 v[42:45], v[204:207], v[164:167], v[42:45]
	v_mfma_f32_16x16x32_bf16 v[34:37], v[196:199], v[172:175], v[34:37]
	v_mfma_f32_16x16x32_bf16 v[26:29], v[204:207], v[172:175], v[26:29]
	v_mfma_f32_16x16x32_bf16 v[22:25], v[196:199], v[180:183], v[22:25]
	v_mfma_f32_16x16x32_bf16 v[18:21], v[204:207], v[180:183], v[18:21]
	v_mfma_f32_16x16x32_bf16 v[6:9], v[196:199], v[188:191], v[6:9]
	v_mfma_f32_16x16x32_bf16 v[2:5], v[204:207], v[188:191], v[2:5]
	v_mfma_f32_16x16x32_bf16 v[50:53], v[200:203], v[168:171], v[50:53]
	v_mfma_f32_16x16x32_bf16 v[42:45], v[224:227], v[168:171], v[42:45]
	v_mfma_f32_16x16x32_bf16 v[34:37], v[200:203], v[176:179], v[34:37]
	v_mfma_f32_16x16x32_bf16 v[26:29], v[224:227], v[176:179], v[26:29]
	v_mfma_f32_16x16x32_bf16 v[22:25], v[200:203], v[184:187], v[22:25]
	v_mfma_f32_16x16x32_bf16 v[18:21], v[224:227], v[184:187], v[18:21]
	v_mfma_f32_16x16x32_bf16 v[6:9], v[200:203], v[192:195], v[6:9]
	v_mfma_f32_16x16x32_bf16 v[2:5], v[224:227], v[192:195], v[2:5]
	s_setprio 0
	s_add_u32 s25, s25, 0x100
	s_addc_u32 s52, s52, 0
	s_add_u32 s42, s42, 0x100
	s_addc_u32 s43, s43, 0
	s_cmp_ge_i32 s53, s12
	s_mov_b32 s44, s53
	s_barrier
	s_cbranch_scc0 .LBB0_796
	s_waitcnt lgkmcnt(0)
	v_lshl_or_b32 v142, s16, 8, v149
	s_cmp_gt_i32 s13, -1
	s_mov_b64 s[16:17], -1
	s_cbranch_scc1 .LBB0_799
	v_lshl_add_u32 v152, s10, 8, v147
	v_ashrrev_i32_e32 v153, 31, v152
	v_ashrrev_i32_e32 v143, 31, v142
	v_lshlrev_b64 v[144:145], 12, v[152:153]
	v_lshl_add_u64 v[144:145], s[4:5], 0, v[144:145]
	v_lshlrev_b64 v[154:155], 1, v[142:143]
	v_lshl_add_u64 v[144:145], v[144:145], 0, v[154:155]
	v_cvt_pk_bf16_f32 v126, v126, v127
	v_cvt_pk_bf16_f32 v127, v128, v129
	v_cvt_pk_bf16_f32 v128, v122, v123
	v_cvt_pk_bf16_f32 v129, v124, v125
	global_store_dwordx4 v[144:145], v[126:129], off
	v_cvt_pk_bf16_f32 v114, v114, v115
	v_cvt_pk_bf16_f32 v115, v116, v117
	v_cvt_pk_bf16_f32 v116, v106, v107
	v_or_b32_e32 v106, 16, v152
	v_ashrrev_i32_e32 v107, 31, v106
	v_lshlrev_b64 v[106:107], 12, v[106:107]
	v_lshl_add_u64 v[106:107], s[4:5], 0, v[106:107]
	v_cvt_pk_bf16_f32 v117, v108, v109
	global_store_dwordx4 v[144:145], v[114:117], off offset:256
	s_mov_b32 s7, 0x80000
	s_mov_b64 s[16:17], 0x80000
	v_lshl_add_u64 v[114:115], v[106:107], 0, v[154:155]
	v_cvt_pk_bf16_f32 v106, v118, v119
	v_cvt_pk_bf16_f32 v107, v120, v121
	v_cvt_pk_bf16_f32 v108, v110, v111
	v_cvt_pk_bf16_f32 v109, v112, v113
	global_store_dwordx4 v[114:115], v[106:109], off
	v_cvt_pk_bf16_f32 v98, v98, v99
	v_cvt_pk_bf16_f32 v99, v100, v101
	v_cvt_pk_bf16_f32 v100, v90, v91
	v_or_b32_e32 v90, 32, v152
	v_ashrrev_i32_e32 v91, 31, v90
	v_lshlrev_b64 v[90:91], 12, v[90:91]
	v_lshl_add_u64 v[90:91], s[4:5], 0, v[90:91]
	v_cvt_pk_bf16_f32 v101, v92, v93
	global_store_dwordx4 v[114:115], v[98:101], off offset:256
	s_nop 1
	v_lshl_add_u64 v[98:99], v[90:91], 0, v[154:155]
	v_cvt_pk_bf16_f32 v90, v102, v103
	v_cvt_pk_bf16_f32 v91, v104, v105
	v_cvt_pk_bf16_f32 v92, v94, v95
	v_cvt_pk_bf16_f32 v93, v96, v97
	global_store_dwordx4 v[98:99], v[90:93], off
	v_cvt_pk_bf16_f32 v82, v82, v83
	v_cvt_pk_bf16_f32 v83, v84, v85
	v_cvt_pk_bf16_f32 v84, v74, v75
	v_or_b32_e32 v74, 48, v152
	v_ashrrev_i32_e32 v75, 31, v74
	v_lshlrev_b64 v[74:75], 12, v[74:75]
	v_lshl_add_u64 v[74:75], s[4:5], 0, v[74:75]
	v_cvt_pk_bf16_f32 v85, v76, v77
	global_store_dwordx4 v[98:99], v[82:85], off offset:256
	s_nop 1
	v_lshl_add_u64 v[82:83], v[74:75], 0, v[154:155]
	v_cvt_pk_bf16_f32 v74, v86, v87
	v_cvt_pk_bf16_f32 v75, v88, v89
	v_cvt_pk_bf16_f32 v76, v78, v79
	v_cvt_pk_bf16_f32 v77, v80, v81
	global_store_dwordx4 v[82:83], v[74:77], off
	v_cvt_pk_bf16_f32 v70, v70, v71
	v_cvt_pk_bf16_f32 v71, v72, v73
	v_cvt_pk_bf16_f32 v72, v66, v67
	v_cvt_pk_bf16_f32 v73, v68, v69
	global_store_dwordx4 v[82:83], v[70:73], off offset:256
	v_cvt_pk_bf16_f32 v62, v62, v63
	v_cvt_pk_bf16_f32 v63, v64, v65
	v_cvt_pk_bf16_f32 v64, v58, v59
	v_add_co_u32_e32 v58, vcc, s7, v144
	v_lshl_add_u64 v[66:67], v[144:145], 0, s[16:17]
	s_nop 0
	v_addc_co_u32_e32 v59, vcc, 0, v145, vcc
	s_mov_b32 s7, 0x90000
	v_cvt_pk_bf16_f32 v65, v60, v61
	global_store_dwordx4 v[58:59], v[62:65], off
	v_cvt_pk_bf16_f32 v50, v50, v51
	v_cvt_pk_bf16_f32 v51, v52, v53
	v_cvt_pk_bf16_f32 v52, v42, v43
	v_cvt_pk_bf16_f32 v53, v44, v45
	global_store_dwordx4 v[66:67], v[50:53], off offset:256
	s_mov_b64 s[16:17], 0x90000
	v_cvt_pk_bf16_f32 v42, v54, v55
	v_cvt_pk_bf16_f32 v43, v56, v57
	v_cvt_pk_bf16_f32 v44, v46, v47
	v_add_co_u32_e32 v46, vcc, s7, v144
	v_lshl_add_u64 v[50:51], v[144:145], 0, s[16:17]
	s_nop 0
	v_addc_co_u32_e32 v47, vcc, 0, v145, vcc
	s_mov_b32 s7, 0xa0000
	v_cvt_pk_bf16_f32 v45, v48, v49
	global_store_dwordx4 v[46:47], v[42:45], off
	v_cvt_pk_bf16_f32 v34, v34, v35
	v_cvt_pk_bf16_f32 v35, v36, v37
	v_cvt_pk_bf16_f32 v36, v26, v27
	v_cvt_pk_bf16_f32 v37, v28, v29
	global_store_dwordx4 v[50:51], v[34:37], off offset:256
	v_cvt_pk_bf16_f32 v26, v38, v39
	v_cvt_pk_bf16_f32 v27, v40, v41
	v_cvt_pk_bf16_f32 v28, v30, v31
	v_add_co_u32_e32 v30, vcc, s7, v144
	s_mov_b64 s[16:17], 0xa0000
	s_nop 0
	v_addc_co_u32_e32 v31, vcc, 0, v145, vcc
	v_lshl_add_u64 v[34:35], v[144:145], 0, s[16:17]
	v_cvt_pk_bf16_f32 v29, v32, v33
	global_store_dwordx4 v[30:31], v[26:29], off
	v_cvt_pk_bf16_f32 v22, v22, v23
	v_cvt_pk_bf16_f32 v23, v24, v25
	v_cvt_pk_bf16_f32 v24, v18, v19
	s_mov_b32 s7, 0xb0000
	v_cvt_pk_bf16_f32 v25, v20, v21
	global_store_dwordx4 v[34:35], v[22:25], off offset:256
	s_mov_b64 s[16:17], 0xb0000
	v_cvt_pk_bf16_f32 v18, v14, v15
	v_cvt_pk_bf16_f32 v19, v16, v17
	v_cvt_pk_bf16_f32 v20, v10, v11
	v_cvt_pk_bf16_f32 v21, v12, v13
	s_nop 0
	v_add_co_u32_e32 v24, vcc, s7, v144
	v_lshl_add_u64 v[22:23], v[144:145], 0, s[16:17]
	s_nop 0
	v_addc_co_u32_e32 v25, vcc, 0, v145, vcc
	s_mov_b64 s[16:17], 0
	global_store_dwordx4 v[24:25], v[18:21], off
	s_nop 1
	v_cvt_pk_bf16_f32 v18, v6, v7
	v_cvt_pk_bf16_f32 v19, v8, v9
	v_cvt_pk_bf16_f32 v20, v2, v3
	v_cvt_pk_bf16_f32 v21, v4, v5
	global_store_dwordx4 v[22:23], v[18:21], off offset:256

; #define PG8_STAGE(bufoff, gbase, voff) do { _Pragma("unroll") for (int _i = 0; _i < 2; ++_i) \
;         __builtin_amdgcn_global_load_lds((const unsigned*)((const char*)(gbase) + (voff)[_i]), (LAS unsigned*)(lds + (bufoff) + ldsw + _i * 8192), 16, 0, 0); } while (0)
; #define PG8_LDA(dst, b, h) do { _Pragma("unroll") for (int m = 0; m < 4; ++m) _Pragma("unroll") for (int k = 0; k < 2; ++k) dst[m][k] = *(const LAS bf16x8*)(lds + PG8_SA(b, h) + aoff + m * 2048 + k * 1024); } while (0)
; #define PG8_LDB(dst, b, h) do { _Pragma("unroll") for (int n = 0; n < 2; ++n) _Pragma("unroll") for (int k = 0; k < 2; ++k) dst[n][k] = *(const LAS bf16x8*)(lds + PG8_SB(b, h) + boff + n * 2048 + k * 1024); } while (0)
; #define PG8_MMA(ai, bj, At, Bt) do { __builtin_amdgcn_s_setprio(1); _Pragma("unroll") for (int m = 0; m < 4; ++m) _Pragma("unroll") for (int n = 0; n < 2; ++n) _Pragma("unroll") for (int k = 0; k < 2; ++k) \
;         acc[ai][bj][m][n] = __builtin_amdgcn_mfma_f32_16x16x32_bf16(Bt[n][k], At[m][k], acc[ai][bj][m][n], 0, 0, 0); __builtin_amdgcn_s_setprio(0); } while (0)
; #define PG8_BAR __builtin_amdgcn_s_barrier()
; template <class Epi, class Sched>
; __device__ __forceinline__ void gemm_phase(LAS unsigned char* lds, const Gemm g, const Sched& S, const Epi& E) {
;     ...
;     for (;;) {
;         const bool has_next = S.next(ui + 1, nxt);
;         const char* nA = has_next ? PG8_APTR(nxt) : cA; const char* nB = has_next ? PG8_BPTR(nxt) : cB;
;         const int nt = cur.nt;
;         for (int t = 0; t < nt; t += 2) {
;             const bool last = (t == nt - 2);
;             const char* a1 = cA + (size_t)(t + 1) * kstep;
;             const char* a2 = last ? nA : cA + (size_t)(t + 2) * kstep; const char* b2 = last ? nB : cB + (size_t)(t + 2) * kstep;
;             const char* a3 = a2 + kstep; const char* b3 = b2 + kstep;
;             PG8_LDB(B0, 0, 0); PG8_SCHED; PG8_LDA(At, 0, 0); PG8_STAGE(PG8_SA(1, 1), a1 + hstepA, voffA);
;             PG8_WAIT_L(8); PG8_BAR; PG8_WAIT_L(0); PG8_MMA(0, 0, At, B0); PG8_BAR; PG8_SCHED;
;     ...
; #pragma unroll
;         for (int a = 0; a < 2; ++a)
; #pragma unroll
;             for (int b = 0; b < 2; ++b)
; #pragma unroll
;                 for (int m = 0; m < 4; ++m)
; #pragma unroll
;                     for (int n = 0; n < 2; ++n) acc[a][b][m][n] = (f32x4){0.f, 0.f, 0.f, 0.f};
;         cur = nxt; cA = nA; cB = nB; ++ui;
.LBB0_944:
	s_ashr_i32 s63, s62, 31
	s_lshl_b64 s[2:3], s[62:63], 20
	v_mov_b64_e32 v[2:3], 0x2b5
	s_add_u32 s64, s22, s2
	v_cmp_lt_i64_e32 vcc, s[18:19], v[2:3]
	s_addc_u32 s65, s23, s3
	s_and_b64 s[2:3], vcc, exec
	s_cselect_b32 s2, s65, s17
	s_cselect_b32 s3, s64, s16
	s_ashr_i32 s61, s60, 31
	s_lshl_b64 s[6:7], s[60:61], 20
	s_add_u32 s66, s33, s6
	s_addc_u32 s67, s91, s7
	s_and_b64 s[6:7], vcc, exec
	s_cselect_b32 s6, s67, s11
	s_cselect_b32 s7, s66, s10
	s_add_u32 s9, s10, 0x100
	s_addc_u32 s12, s11, 0
	s_add_u32 s10, s16, 0x80080
	v_mov_b32_e32 v2, 0
	s_addc_u32 s11, s17, 0
	s_mov_b32 s14, -2
	v_mov_b32_e32 v3, v2
	v_mov_b32_e32 v4, v2
	v_mov_b32_e32 v5, v2
	v_mov_b32_e32 v6, v2
	v_mov_b32_e32 v7, v2
	v_mov_b32_e32 v8, v2
	v_mov_b32_e32 v9, v2
	v_mov_b32_e32 v18, v2
	v_mov_b32_e32 v19, v2
	v_mov_b32_e32 v20, v2
	v_mov_b32_e32 v21, v2
	v_mov_b32_e32 v22, v2
	v_mov_b32_e32 v23, v2
	v_mov_b32_e32 v24, v2
	v_mov_b32_e32 v25, v2
	v_mov_b32_e32 v34, v2
	v_mov_b32_e32 v35, v2
	v_mov_b32_e32 v36, v2
	v_mov_b32_e32 v37, v2
	v_mov_b32_e32 v38, v2
	v_mov_b32_e32 v39, v2
	v_mov_b32_e32 v40, v2
	v_mov_b32_e32 v41, v2
	v_mov_b32_e32 v50, v2
	v_mov_b32_e32 v51, v2
	v_mov_b32_e32 v52, v2
	v_mov_b32_e32 v53, v2
	v_mov_b32_e32 v54, v2
	v_mov_b32_e32 v55, v2
	v_mov_b32_e32 v56, v2
	v_mov_b32_e32 v57, v2
	v_mov_b32_e32 v10, v2
	v_mov_b32_e32 v11, v2
	v_mov_b32_e32 v12, v2
	v_mov_b32_e32 v13, v2
	v_mov_b32_e32 v14, v2
	v_mov_b32_e32 v15, v2
	v_mov_b32_e32 v16, v2
	v_mov_b32_e32 v17, v2
	v_mov_b32_e32 v26, v2
	v_mov_b32_e32 v27, v2
	v_mov_b32_e32 v28, v2
	v_mov_b32_e32 v29, v2
	v_mov_b32_e32 v30, v2
	v_mov_b32_e32 v31, v2
	v_mov_b32_e32 v32, v2
	v_mov_b32_e32 v33, v2
	v_mov_b32_e32 v42, v2
	v_mov_b32_e32 v43, v2
	v_mov_b32_e32 v44, v2
	v_mov_b32_e32 v45, v2
	v_mov_b32_e32 v46, v2
	v_mov_b32_e32 v47, v2
	v_mov_b32_e32 v48, v2
	v_mov_b32_e32 v49, v2
	v_mov_b32_e32 v58, v2
	v_mov_b32_e32 v59, v2
	v_mov_b32_e32 v60, v2
	v_mov_b32_e32 v61, v2
	v_mov_b32_e32 v62, v2
	v_mov_b32_e32 v63, v2
	v_mov_b32_e32 v64, v2
	v_mov_b32_e32 v65, v2
	v_mov_b32_e32 v66, v2
	v_mov_b32_e32 v67, v2
	v_mov_b32_e32 v68, v2
	v_mov_b32_e32 v69, v2
	v_mov_b32_e32 v70, v2
	v_mov_b32_e32 v71, v2
	v_mov_b32_e32 v72, v2
	v_mov_b32_e32 v73, v2
	v_mov_b32_e32 v82, v2
	v_mov_b32_e32 v83, v2
	v_mov_b32_e32 v84, v2
	v_mov_b32_e32 v85, v2
	v_mov_b32_e32 v86, v2
	v_mov_b32_e32 v87, v2
	v_mov_b32_e32 v88, v2
	v_mov_b32_e32 v89, v2
	v_mov_b32_e32 v98, v2
	v_mov_b32_e32 v99, v2
	v_mov_b32_e32 v100, v2
	v_mov_b32_e32 v101, v2
	v_mov_b32_e32 v102, v2
	v_mov_b32_e32 v103, v2
	v_mov_b32_e32 v104, v2
	v_mov_b32_e32 v105, v2
	v_mov_b32_e32 v114, v2
	v_mov_b32_e32 v115, v2
	v_mov_b32_e32 v116, v2
	v_mov_b32_e32 v117, v2
	s_waitcnt lgkmcnt(0)
	v_mov_b32_e32 v118, v2
	v_mov_b32_e32 v119, v2
	v_mov_b32_e32 v120, v2
	v_mov_b32_e32 v121, v2
	v_mov_b32_e32 v74, v2
	v_mov_b32_e32 v75, v2
	v_mov_b32_e32 v76, v2
	v_mov_b32_e32 v77, v2
	v_mov_b32_e32 v78, v2
	v_mov_b32_e32 v79, v2
	v_mov_b32_e32 v80, v2
	v_mov_b32_e32 v81, v2
	v_mov_b32_e32 v90, v2
	v_mov_b32_e32 v91, v2
	v_mov_b32_e32 v92, v2
	v_mov_b32_e32 v93, v2
	v_mov_b32_e32 v94, v2
	v_mov_b32_e32 v95, v2
	v_mov_b32_e32 v96, v2
	v_mov_b32_e32 v97, v2
	v_mov_b32_e32 v106, v2
	v_mov_b32_e32 v107, v2
	v_mov_b32_e32 v108, v2
	v_mov_b32_e32 v109, v2
	v_mov_b32_e32 v110, v2
	v_mov_b32_e32 v111, v2
	v_mov_b32_e32 v112, v2
	v_mov_b32_e32 v113, v2
	v_mov_b32_e32 v122, v2
	v_mov_b32_e32 v123, v2
	v_mov_b32_e32 v124, v2
	v_mov_b32_e32 v125, v2
	v_mov_b32_e32 v126, v2
	v_mov_b32_e32 v127, v2
	v_mov_b32_e32 v128, v2
	v_mov_b32_e32 v129, v2
	v_add_u32_e32 v0, 0x10000, v156
	ds_read_b128 v[150:153], v0
	ds_read_b128 v[158:161], v0 offset:1024
	ds_read_b128 v[162:165], v0 offset:2048
	ds_read_b128 v[166:169], v0 offset:3072
.LBB0_945:
	s_add_u32 s16, s10, 0xfff80080
	s_addc_u32 s17, s11, -1
	s_add_i32 s20, 0, 0x10000
	v_add_u32_e32 v0, s20, v156
	s_cmp_eq_u32 s14, 28
	s_cselect_b32 s19, s2, s17
	s_cselect_b32 s18, s3, s16
	s_cselect_b32 s17, s6, s12
	s_cselect_b32 s16, s7, s9
	v_lshl_add_u64 v[154:155], s[10:11], 0, v[148:149]
	s_add_i32 m0, s47, 0xc000
	ds_read_b128 v[170:173], v157
	ds_read_b128 v[174:177], v157 offset:1024
	ds_read_b128 v[178:181], v157 offset:2048
	ds_read_b128 v[182:185], v157 offset:3072
	ds_read_b128 v[186:189], v157 offset:4096
	ds_read_b128 v[190:193], v157 offset:5120
	ds_read_b128 v[198:201], v157 offset:6144
	ds_read_b128 v[202:205], v157 offset:7168
	global_load_lds_dwordx4 v[154:155], off
	v_lshl_add_u64 v[154:155], s[10:11], 0, v[146:147]
	s_add_i32 m0, s47, 0xe000
	s_nop 0
	global_load_lds_dwordx4 v[154:155], off
	s_waitcnt lgkmcnt(8)
	s_barrier
	s_waitcnt lgkmcnt(0)
	s_setprio 1
	s_waitcnt lgkmcnt(0)
	v_mfma_f32_16x16x32_bf16 v[126:129], v[150:153], v[170:173], v[126:129]
	v_mfma_f32_16x16x32_bf16 v[122:125], v[162:165], v[170:173], v[122:125]
	v_mfma_f32_16x16x32_bf16 v[110:113], v[150:153], v[178:181], v[110:113]
	v_mfma_f32_16x16x32_bf16 v[106:109], v[162:165], v[178:181], v[106:109]
	v_mfma_f32_16x16x32_bf16 v[94:97], v[150:153], v[186:189], v[94:97]
	v_mfma_f32_16x16x32_bf16 v[90:93], v[162:165], v[186:189], v[90:93]
	v_mfma_f32_16x16x32_bf16 v[78:81], v[150:153], v[198:201], v[78:81]
	v_mfma_f32_16x16x32_bf16 v[74:77], v[162:165], v[198:201], v[74:77]
	v_mfma_f32_16x16x32_bf16 v[126:129], v[158:161], v[174:177], v[126:129]
	v_mfma_f32_16x16x32_bf16 v[122:125], v[166:169], v[174:177], v[122:125]
	v_mfma_f32_16x16x32_bf16 v[110:113], v[158:161], v[182:185], v[110:113]
	v_mfma_f32_16x16x32_bf16 v[106:109], v[166:169], v[182:185], v[106:109]
	v_mfma_f32_16x16x32_bf16 v[94:97], v[158:161], v[190:193], v[94:97]
	v_mfma_f32_16x16x32_bf16 v[90:93], v[166:169], v[190:193], v[90:93]
	v_mfma_f32_16x16x32_bf16 v[78:81], v[158:161], v[202:205], v[78:81]
	v_mfma_f32_16x16x32_bf16 v[74:77], v[166:169], v[202:205], v[74:77]
	s_setprio 0
	s_barrier
; #define PG8_STAGE(bufoff, gbase, voff) do { _Pragma("unroll") for (int _i = 0; _i < 2; ++_i) \
;         __builtin_amdgcn_global_load_lds((const unsigned*)((const char*)(gbase) + (voff)[_i]), (LAS unsigned*)(lds + (bufoff) + ldsw + _i * 8192), 16, 0, 0); } while (0)
; #define PG8_LDA(dst, b, h) do { _Pragma("unroll") for (int m = 0; m < 4; ++m) _Pragma("unroll") for (int k = 0; k < 2; ++k) dst[m][k] = *(const LAS bf16x8*)(lds + PG8_SA(b, h) + aoff + m * 2048 + k * 1024); } while (0)
; #define PG8_LDB(dst, b, h) do { _Pragma("unroll") for (int n = 0; n < 2; ++n) _Pragma("unroll") for (int k = 0; k < 2; ++k) dst[n][k] = *(const LAS bf16x8*)(lds + PG8_SB(b, h) + boff + n * 2048 + k * 1024); } while (0)
; #define PG8_MMA(ai, bj, At, Bt) do { __builtin_amdgcn_s_setprio(1); _Pragma("unroll") for (int m = 0; m < 4; ++m) _Pragma("unroll") for (int n = 0; n < 2; ++n) _Pragma("unroll") for (int k = 0; k < 2; ++k) \
;         acc[ai][bj][m][n] = __builtin_amdgcn_mfma_f32_16x16x32_bf16(Bt[n][k], At[m][k], acc[ai][bj][m][n], 0, 0, 0); __builtin_amdgcn_s_setprio(0); } while (0)
; #define PG8_WAIT_V(n) asm volatile("s_waitcnt vmcnt(" #n ")" ::: "memory")
; #define PG8_WAIT_L(n) asm volatile("s_waitcnt lgkmcnt(" #n ")" ::: "memory")
; #define PG8_BAR __builtin_amdgcn_s_barrier()
; #define PG8_SCHED __builtin_amdgcn_sched_barrier(0)
; template <class Epi, class Sched>
; __device__ __forceinline__ void gemm_phase(LAS unsigned char* lds, const Gemm g, const Sched& S, const Epi& E) {
;     ...
;             PG8_LDB(B1, 0, 1); PG8_STAGE(PG8_SB(0, 0), b2, voffB);
;             PG8_BAR; PG8_WAIT_L(0); PG8_MMA(0, 1, At, B1); PG8_BAR;
;             PG8_LDA(At, 0, 1); PG8_STAGE(PG8_SA(0, 0), a2, voffA);
;             PG8_BAR; PG8_WAIT_L(0); PG8_MMA(1, 0, At, B0); PG8_BAR; PG8_SCHED;
;             PG8_STAGE(PG8_SB(0, 1), b2 + hstepB, voffB);
;             PG8_WAIT_V(6); PG8_BAR; PG8_MMA(1, 1, At, B1); PG8_BAR;
;             PG8_LDB(B0, 1, 0); PG8_SCHED; PG8_LDA(At, 1, 0); PG8_STAGE(PG8_SA(0, 1), a2 + hstepA, voffA);
	s_add_i32 s24, 0, 0x14000
	s_add_i32 s20, s20, s46
	v_add_u32_e32 v0, s24, v156
	v_lshl_add_u64 v[154:155], s[16:17], 0, v[132:133]
	s_mov_b32 m0, s20
	ds_read_b128 v[206:209], v0
	ds_read_b128 v[224:227], v0 offset:1024
	ds_read_b128 v[228:231], v0 offset:2048
	ds_read_b128 v[232:235], v0 offset:3072
	global_load_lds_dwordx4 v[154:155], off
	v_lshl_add_u64 v[194:195], s[16:17], 0, v[136:137]
	s_add_i32 m0, s20, 0x2000
	s_nop 0
	global_load_lds_dwordx4 v[194:195], off
	s_waitcnt vmcnt(8)
	s_barrier
	s_waitcnt lgkmcnt(0)
	s_setprio 1
	s_waitcnt lgkmcnt(0)
	v_mfma_f32_16x16x32_bf16 v[118:121], v[206:209], v[170:173], v[118:121]
	v_mfma_f32_16x16x32_bf16 v[114:117], v[228:231], v[170:173], v[114:117]
	v_mfma_f32_16x16x32_bf16 v[102:105], v[206:209], v[178:181], v[102:105]
	v_mfma_f32_16x16x32_bf16 v[98:101], v[228:231], v[178:181], v[98:101]
	v_mfma_f32_16x16x32_bf16 v[86:89], v[206:209], v[186:189], v[86:89]
	v_mfma_f32_16x16x32_bf16 v[82:85], v[228:231], v[186:189], v[82:85]
	v_mfma_f32_16x16x32_bf16 v[70:73], v[206:209], v[198:201], v[70:73]
	v_mfma_f32_16x16x32_bf16 v[66:69], v[228:231], v[198:201], v[66:69]
	v_mfma_f32_16x16x32_bf16 v[118:121], v[224:227], v[174:177], v[118:121]
	v_mfma_f32_16x16x32_bf16 v[114:117], v[232:235], v[174:177], v[114:117]
	v_mfma_f32_16x16x32_bf16 v[102:105], v[224:227], v[182:185], v[102:105]
	v_mfma_f32_16x16x32_bf16 v[98:101], v[232:235], v[182:185], v[98:101]
	v_mfma_f32_16x16x32_bf16 v[86:89], v[224:227], v[190:193], v[86:89]
	v_mfma_f32_16x16x32_bf16 v[82:85], v[232:235], v[190:193], v[82:85]
	v_mfma_f32_16x16x32_bf16 v[70:73], v[224:227], v[202:205], v[70:73]
	v_mfma_f32_16x16x32_bf16 v[66:69], v[232:235], v[202:205], v[66:69]
	s_setprio 0
	s_mov_b32 m0, s47
	v_lshl_add_u64 v[196:197], s[18:19], 0, v[130:131]
	s_barrier
	ds_read_b128 v[170:173], v157 offset:16384
	ds_read_b128 v[174:177], v157 offset:17408
	ds_read_b128 v[178:181], v157 offset:18432
	ds_read_b128 v[182:185], v157 offset:19456
	ds_read_b128 v[186:189], v157 offset:20480
	ds_read_b128 v[190:193], v157 offset:21504
	ds_read_b128 v[198:201], v157 offset:22528
	ds_read_b128 v[202:205], v157 offset:23552
	global_load_lds_dwordx4 v[196:197], off
	v_lshl_add_u64 v[236:237], s[18:19], 0, v[134:135]
	s_mov_b32 m0, s72
	s_nop 0
	global_load_lds_dwordx4 v[236:237], off
	s_barrier
	s_waitcnt lgkmcnt(0)
	s_setprio 1
	s_waitcnt lgkmcnt(0)
	v_mfma_f32_16x16x32_bf16 v[62:65], v[150:153], v[170:173], v[62:65]
	v_mfma_f32_16x16x32_bf16 v[58:61], v[162:165], v[170:173], v[58:61]
	v_mfma_f32_16x16x32_bf16 v[46:49], v[150:153], v[178:181], v[46:49]
	v_mfma_f32_16x16x32_bf16 v[42:45], v[162:165], v[178:181], v[42:45]
	v_mfma_f32_16x16x32_bf16 v[30:33], v[150:153], v[186:189], v[30:33]
	v_mfma_f32_16x16x32_bf16 v[26:29], v[162:165], v[186:189], v[26:29]
	v_mfma_f32_16x16x32_bf16 v[14:17], v[150:153], v[198:201], v[14:17]
	v_mfma_f32_16x16x32_bf16 v[10:13], v[162:165], v[198:201], v[10:13]
	v_mfma_f32_16x16x32_bf16 v[62:65], v[158:161], v[174:177], v[62:65]
	v_mfma_f32_16x16x32_bf16 v[58:61], v[166:169], v[174:177], v[58:61]
	v_mfma_f32_16x16x32_bf16 v[46:49], v[158:161], v[182:185], v[46:49]
	v_mfma_f32_16x16x32_bf16 v[42:45], v[166:169], v[182:185], v[42:45]
	v_mfma_f32_16x16x32_bf16 v[30:33], v[158:161], v[190:193], v[30:33]
	v_mfma_f32_16x16x32_bf16 v[26:29], v[166:169], v[190:193], v[26:29]
	v_mfma_f32_16x16x32_bf16 v[14:17], v[158:161], v[202:205], v[14:17]
	v_mfma_f32_16x16x32_bf16 v[10:13], v[166:169], v[202:205], v[10:13]
	s_setprio 0
	s_barrier
	s_add_u32 s20, s16, 0x80000
	s_addc_u32 s21, s17, 0
	s_add_i32 s24, s24, s46
	v_lshl_add_u64 v[150:151], s[20:21], 0, v[132:133]
	s_mov_b32 m0, s24
	s_nop 0
	global_load_lds_dwordx4 v[150:151], off
	v_lshl_add_u64 v[150:151], s[20:21], 0, v[136:137]
	s_add_i32 m0, s24, 0x2000
	s_nop 0
	global_load_lds_dwordx4 v[150:151], off
	v_add_u32_e32 v0, 0x18000, v156
	ds_read_b128 v[150:153], v0
	ds_read_b128 v[158:161], v0 offset:1024
	ds_read_b128 v[162:165], v0 offset:2048
	ds_read_b128 v[166:169], v0 offset:3072
	s_waitcnt vmcnt(6)
	s_barrier
	s_setprio 1
	v_mfma_f32_16x16x32_bf16 v[54:57], v[206:209], v[170:173], v[54:57]
	v_mfma_f32_16x16x32_bf16 v[50:53], v[228:231], v[170:173], v[50:53]
	v_mfma_f32_16x16x32_bf16 v[38:41], v[206:209], v[178:181], v[38:41]
	v_mfma_f32_16x16x32_bf16 v[34:37], v[228:231], v[178:181], v[34:37]
	v_mfma_f32_16x16x32_bf16 v[22:25], v[206:209], v[186:189], v[22:25]
	v_mfma_f32_16x16x32_bf16 v[18:21], v[228:231], v[186:189], v[18:21]
	v_mfma_f32_16x16x32_bf16 v[6:9], v[206:209], v[198:201], v[6:9]
	v_mfma_f32_16x16x32_bf16 v[2:5], v[228:231], v[198:201], v[2:5]
	v_mfma_f32_16x16x32_bf16 v[54:57], v[224:227], v[174:177], v[54:57]
	v_mfma_f32_16x16x32_bf16 v[50:53], v[232:235], v[174:177], v[50:53]
	v_mfma_f32_16x16x32_bf16 v[38:41], v[224:227], v[182:185], v[38:41]
	v_mfma_f32_16x16x32_bf16 v[34:37], v[232:235], v[182:185], v[34:37]
	v_mfma_f32_16x16x32_bf16 v[22:25], v[224:227], v[190:193], v[22:25]
	v_mfma_f32_16x16x32_bf16 v[18:21], v[232:235], v[190:193], v[18:21]
	v_mfma_f32_16x16x32_bf16 v[6:9], v[224:227], v[202:205], v[6:9]
	v_mfma_f32_16x16x32_bf16 v[2:5], v[232:235], v[202:205], v[2:5]
	s_setprio 0
	s_add_i32 s20, 0, 0x18000
	v_add_u32_e32 v0, s20, v156
	s_barrier
	s_add_u32 s18, s18, 0x80000
	s_addc_u32 s19, s19, 0
	s_mov_b32 m0, s73
	v_lshl_add_u64 v[206:207], s[18:19], 0, v[130:131]
	ds_read_b128 v[170:173], v157 offset:32768
	ds_read_b128 v[174:177], v157 offset:33792
	ds_read_b128 v[178:181], v157 offset:34816
	ds_read_b128 v[182:185], v157 offset:35840
	ds_read_b128 v[186:189], v157 offset:36864
	ds_read_b128 v[190:193], v157 offset:37888
	ds_read_b128 v[198:201], v157 offset:38912
	ds_read_b128 v[202:205], v157 offset:39936
	global_load_lds_dwordx4 v[206:207], off
	v_lshl_add_u64 v[206:207], s[18:19], 0, v[134:135]
	s_mov_b32 m0, s74
	s_nop 0
	global_load_lds_dwordx4 v[206:207], off
	s_waitcnt lgkmcnt(8)
	s_barrier
; #define PG8_STAGE(bufoff, gbase, voff) do { _Pragma("unroll") for (int _i = 0; _i < 2; ++_i) \
;         __builtin_amdgcn_global_load_lds((const unsigned*)((const char*)(gbase) + (voff)[_i]), (LAS unsigned*)(lds + (bufoff) + ldsw + _i * 8192), 16, 0, 0); } while (0)
; #define PG8_LDA(dst, b, h) do { _Pragma("unroll") for (int m = 0; m < 4; ++m) _Pragma("unroll") for (int k = 0; k < 2; ++k) dst[m][k] = *(const LAS bf16x8*)(lds + PG8_SA(b, h) + aoff + m * 2048 + k * 1024); } while (0)
; #define PG8_LDB(dst, b, h) do { _Pragma("unroll") for (int n = 0; n < 2; ++n) _Pragma("unroll") for (int k = 0; k < 2; ++k) dst[n][k] = *(const LAS bf16x8*)(lds + PG8_SB(b, h) + boff + n * 2048 + k * 1024); } while (0)
; #define PG8_MMA(ai, bj, At, Bt) do { __builtin_amdgcn_s_setprio(1); _Pragma("unroll") for (int m = 0; m < 4; ++m) _Pragma("unroll") for (int n = 0; n < 2; ++n) _Pragma("unroll") for (int k = 0; k < 2; ++k) \
;         acc[ai][bj][m][n] = __builtin_amdgcn_mfma_f32_16x16x32_bf16(Bt[n][k], At[m][k], acc[ai][bj][m][n], 0, 0, 0); __builtin_amdgcn_s_setprio(0); } while (0)
; #define PG8_WAIT_L(n) asm volatile("s_waitcnt lgkmcnt(" #n ")" ::: "memory")
; #define PG8_BAR __builtin_amdgcn_s_barrier()
; #define PG8_SCHED __builtin_amdgcn_sched_barrier(0)
; template <class Epi, class Sched>
; __device__ __forceinline__ void gemm_phase(LAS unsigned char* lds, const Gemm g, const Sched& S, const Epi& E) {
;     ...
;             PG8_WAIT_L(8); PG8_BAR; PG8_WAIT_L(0); PG8_MMA(0, 0, At, B0); PG8_BAR; PG8_SCHED;
;             PG8_LDB(B1, 1, 1); PG8_STAGE(PG8_SB(1, 0), b3, voffB);
;             PG8_BAR; PG8_WAIT_L(0); PG8_MMA(0, 1, At, B1); PG8_BAR;
;             PG8_LDA(At, 1, 1); PG8_STAGE(PG8_SA(1, 0), a3, voffA);
;             PG8_BAR; PG8_WAIT_L(0); PG8_MMA(1, 0, At, B0); PG8_BAR; PG8_SCHED;
;             PG8_STAGE(PG8_SB(1, 1), b3 + hstepB, voffB);
	s_waitcnt lgkmcnt(0)
	s_setprio 1
	s_waitcnt lgkmcnt(0)
	v_mfma_f32_16x16x32_bf16 v[126:129], v[150:153], v[170:173], v[126:129]
	v_mfma_f32_16x16x32_bf16 v[122:125], v[162:165], v[170:173], v[122:125]
	v_mfma_f32_16x16x32_bf16 v[110:113], v[150:153], v[178:181], v[110:113]
	v_mfma_f32_16x16x32_bf16 v[106:109], v[162:165], v[178:181], v[106:109]
	v_mfma_f32_16x16x32_bf16 v[94:97], v[150:153], v[186:189], v[94:97]
	v_mfma_f32_16x16x32_bf16 v[90:93], v[162:165], v[186:189], v[90:93]
	v_mfma_f32_16x16x32_bf16 v[78:81], v[150:153], v[198:201], v[78:81]
	v_mfma_f32_16x16x32_bf16 v[74:77], v[162:165], v[198:201], v[74:77]
	v_mfma_f32_16x16x32_bf16 v[126:129], v[158:161], v[174:177], v[126:129]
	v_mfma_f32_16x16x32_bf16 v[122:125], v[166:169], v[174:177], v[122:125]
	v_mfma_f32_16x16x32_bf16 v[110:113], v[158:161], v[182:185], v[110:113]
	v_mfma_f32_16x16x32_bf16 v[106:109], v[166:169], v[182:185], v[106:109]
	v_mfma_f32_16x16x32_bf16 v[94:97], v[158:161], v[190:193], v[94:97]
	v_mfma_f32_16x16x32_bf16 v[90:93], v[166:169], v[190:193], v[90:93]
	v_mfma_f32_16x16x32_bf16 v[78:81], v[158:161], v[202:205], v[78:81]
	v_mfma_f32_16x16x32_bf16 v[74:77], v[166:169], v[202:205], v[74:77]
	s_setprio 0
	s_barrier
	s_add_i32 s18, 0, 0x1c000
	s_add_i32 s19, s20, s46
	v_add_u32_e32 v0, s18, v156
	v_lshl_add_u64 v[154:155], v[154:155], 0, s[26:27]
	s_mov_b32 m0, s19
	ds_read_b128 v[206:209], v0
	ds_read_b128 v[224:227], v0 offset:1024
	ds_read_b128 v[228:231], v0 offset:2048
	ds_read_b128 v[232:235], v0 offset:3072
	global_load_lds_dwordx4 v[154:155], off
	v_lshl_add_u64 v[154:155], v[194:195], 0, s[26:27]
	s_add_i32 m0, s19, 0x2000
	s_nop 0
	global_load_lds_dwordx4 v[154:155], off
	s_waitcnt vmcnt(8)
	s_barrier
	s_waitcnt lgkmcnt(0)
	s_setprio 1
	s_waitcnt lgkmcnt(0)
	v_mfma_f32_16x16x32_bf16 v[118:121], v[206:209], v[170:173], v[118:121]
	v_mfma_f32_16x16x32_bf16 v[114:117], v[228:231], v[170:173], v[114:117]
	v_mfma_f32_16x16x32_bf16 v[102:105], v[206:209], v[178:181], v[102:105]
	v_mfma_f32_16x16x32_bf16 v[98:101], v[228:231], v[178:181], v[98:101]
	v_mfma_f32_16x16x32_bf16 v[86:89], v[206:209], v[186:189], v[86:89]
	v_mfma_f32_16x16x32_bf16 v[82:85], v[228:231], v[186:189], v[82:85]
	v_mfma_f32_16x16x32_bf16 v[70:73], v[206:209], v[198:201], v[70:73]
	v_mfma_f32_16x16x32_bf16 v[66:69], v[228:231], v[198:201], v[66:69]
	v_mfma_f32_16x16x32_bf16 v[118:121], v[224:227], v[174:177], v[118:121]
	v_mfma_f32_16x16x32_bf16 v[114:117], v[232:235], v[174:177], v[114:117]
	v_mfma_f32_16x16x32_bf16 v[102:105], v[224:227], v[182:185], v[102:105]
	v_mfma_f32_16x16x32_bf16 v[98:101], v[232:235], v[182:185], v[98:101]
	v_mfma_f32_16x16x32_bf16 v[86:89], v[224:227], v[190:193], v[86:89]
	v_mfma_f32_16x16x32_bf16 v[82:85], v[232:235], v[190:193], v[82:85]
	v_mfma_f32_16x16x32_bf16 v[70:73], v[224:227], v[202:205], v[70:73]
	v_mfma_f32_16x16x32_bf16 v[66:69], v[232:235], v[202:205], v[66:69]
	s_setprio 0
	s_mov_b32 m0, s77
	v_lshl_add_u64 v[154:155], v[196:197], 0, s[26:27]
	s_barrier
	ds_read_b128 v[170:173], v157 offset:49152
	ds_read_b128 v[174:177], v157 offset:50176
	ds_read_b128 v[178:181], v157 offset:51200
	ds_read_b128 v[182:185], v157 offset:52224
	ds_read_b128 v[186:189], v157 offset:53248
	ds_read_b128 v[190:193], v157 offset:54272
	ds_read_b128 v[198:201], v157 offset:55296
	ds_read_b128 v[202:205], v157 offset:56320
	global_load_lds_dwordx4 v[154:155], off
	v_lshl_add_u64 v[154:155], v[236:237], 0, s[26:27]
	s_mov_b32 m0, s78
	s_nop 0
	global_load_lds_dwordx4 v[154:155], off
	s_barrier
	s_waitcnt lgkmcnt(0)
	s_setprio 1
	s_waitcnt lgkmcnt(0)
	v_mfma_f32_16x16x32_bf16 v[62:65], v[150:153], v[170:173], v[62:65]
	v_mfma_f32_16x16x32_bf16 v[58:61], v[162:165], v[170:173], v[58:61]
	v_mfma_f32_16x16x32_bf16 v[46:49], v[150:153], v[178:181], v[46:49]
	v_mfma_f32_16x16x32_bf16 v[42:45], v[162:165], v[178:181], v[42:45]
	v_mfma_f32_16x16x32_bf16 v[30:33], v[150:153], v[186:189], v[30:33]
	v_mfma_f32_16x16x32_bf16 v[26:29], v[162:165], v[186:189], v[26:29]
	v_mfma_f32_16x16x32_bf16 v[14:17], v[150:153], v[198:201], v[14:17]
	v_mfma_f32_16x16x32_bf16 v[10:13], v[162:165], v[198:201], v[10:13]
	v_mfma_f32_16x16x32_bf16 v[62:65], v[158:161], v[174:177], v[62:65]
	v_mfma_f32_16x16x32_bf16 v[58:61], v[166:169], v[174:177], v[58:61]
	v_mfma_f32_16x16x32_bf16 v[46:49], v[158:161], v[182:185], v[46:49]
	v_mfma_f32_16x16x32_bf16 v[42:45], v[166:169], v[182:185], v[42:45]
	v_mfma_f32_16x16x32_bf16 v[30:33], v[158:161], v[190:193], v[30:33]
	v_mfma_f32_16x16x32_bf16 v[26:29], v[166:169], v[190:193], v[26:29]
	v_mfma_f32_16x16x32_bf16 v[14:17], v[158:161], v[202:205], v[14:17]
	v_mfma_f32_16x16x32_bf16 v[10:13], v[166:169], v[202:205], v[10:13]
	s_setprio 0
	s_barrier
	s_add_u32 s16, s16, 0x80080
	s_addc_u32 s17, s17, 0
	s_add_i32 s18, s18, s46
	v_lshl_add_u64 v[150:151], s[16:17], 0, v[132:133]
	s_mov_b32 m0, s18
	s_nop 0
	global_load_lds_dwordx4 v[150:151], off
	v_lshl_add_u64 v[150:151], s[16:17], 0, v[136:137]
	s_add_i32 m0, s18, 0x2000
	s_nop 0
	global_load_lds_dwordx4 v[150:151], off
	v_add_u32_e32 v0, 0x10000, v156
	ds_read_b128 v[150:153], v0
	ds_read_b128 v[158:161], v0 offset:1024
	ds_read_b128 v[162:165], v0 offset:2048
	ds_read_b128 v[166:169], v0 offset:3072
	s_waitcnt vmcnt(6)
	s_barrier
; #define PG8_WAIT_V(n) asm volatile("s_waitcnt vmcnt(" #n ")" ::: "memory")
; template <class Epi, class Sched>
; __device__ __forceinline__ void gemm_phase(LAS unsigned char* lds, const Gemm g, const Sched& S, const Epi& E) {
;     ...
;             PG8_WAIT_V(6); PG8_BAR; PG8_MMA(1, 1, At, B1); PG8_BAR;
;         }
;         E(acc, cur, wr, wc, fr, fq);
;         if (!has_next) break;
;     __device__ __forceinline__ void operator()(const AccT& acc, const pg8::Unit& u, int wr, int wc, int fr, int fq) const {
;     ...
;                 if (u.pn < 20) {
;                     float ss = 0.f;
; #pragma unroll
;                     for (int bj = 0; bj < 2; ++bj) {
;                         const f32x4 a = acc[ai][bj][m][0], b = acc[ai][bj][m][1];
;                         *(u32x4*)(Z + (size_t)row * ZLD + u.pn * 256 + bj * 128 + wc * 32 + 8 * fq) = pack8s(a, b, rs);
; #pragma unroll
;                         for (int j = 0; j < 4; ++j) ss += a[j] * a[j] + b[j] * b[j];
;                     }
;                     if (u.pn < 4) {
;                         ss *= rs * rs;
;                         ss += __shfl_xor(ss, 16); ss += __shfl_xor(ss, 32);
;                         if (fq == 0) ssqp[row * 16 + u.pn * 4 + wc] = ss;
;                     }
;                 } else {
;                     if (wc == 0) {
;                         const f32x4 c0 = *(const f32x4*)(cosT + row * 32 + 8 * fq), c1 = *(const f32x4*)(cosT + row * 32 + 8 * fq + 4);
;                         const f32x4 s0 = *(const f32x4*)(sinT + row * 32 + 8 * fq), s1 = *(const f32x4*)(sinT + row * 32 + 8 * fq + 4);
;                         const f32x4 x1a = acc[ai][0][m][0] * rs, x1b = acc[ai][0][m][1] * rs, x2a = acc[ai][1][m][0] * rs, x2b = acc[ai][1][m][1] * rs;
;                         const f32x4 y1a = x1a * c0 - x2a * s0, y1b = x1b * c1 - x2b * s1, y2a = x2a * c0 + x1a * s0, y2b = x2b * c1 + x1b * s1;
;                         *(u32x4*)(Kr + (size_t)row * 64 + 8 * fq) = pack8s(y1a, y1b, 1.0f);
;                         *(u32x4*)(Kr + (size_t)row * 64 + 32 + 8 * fq) = pack8s(y2a, y2b, 1.0f);
;                     } else if (wc == 1 && fq == 0) {
; #pragma unroll
;                         for (int n = 0; n < 2; ++n)
; #pragma unroll
;                             for (int j = 0; j < 4; ++j) {
;                                 const float x = acc[ai][0][m][n][j] * rs + bfg[4 * n + j];
	s_setprio 1
	v_mfma_f32_16x16x32_bf16 v[54:57], v[206:209], v[170:173], v[54:57]
	v_mfma_f32_16x16x32_bf16 v[50:53], v[228:231], v[170:173], v[50:53]
	v_mfma_f32_16x16x32_bf16 v[38:41], v[206:209], v[178:181], v[38:41]
	v_mfma_f32_16x16x32_bf16 v[34:37], v[228:231], v[178:181], v[34:37]
	v_mfma_f32_16x16x32_bf16 v[22:25], v[206:209], v[186:189], v[22:25]
	v_mfma_f32_16x16x32_bf16 v[18:21], v[228:231], v[186:189], v[18:21]
	v_mfma_f32_16x16x32_bf16 v[6:9], v[206:209], v[198:201], v[6:9]
	v_mfma_f32_16x16x32_bf16 v[2:5], v[228:231], v[198:201], v[2:5]
	v_mfma_f32_16x16x32_bf16 v[54:57], v[224:227], v[174:177], v[54:57]
	v_mfma_f32_16x16x32_bf16 v[50:53], v[232:235], v[174:177], v[50:53]
	v_mfma_f32_16x16x32_bf16 v[38:41], v[224:227], v[182:185], v[38:41]
	v_mfma_f32_16x16x32_bf16 v[34:37], v[232:235], v[182:185], v[34:37]
	v_mfma_f32_16x16x32_bf16 v[22:25], v[224:227], v[190:193], v[22:25]
	v_mfma_f32_16x16x32_bf16 v[18:21], v[232:235], v[190:193], v[18:21]
	v_mfma_f32_16x16x32_bf16 v[6:9], v[224:227], v[202:205], v[6:9]
	v_mfma_f32_16x16x32_bf16 v[2:5], v[232:235], v[202:205], v[2:5]
	s_setprio 0
	s_add_i32 s14, s14, 2
	s_add_u32 s9, s9, 0x100
	s_addc_u32 s12, s12, 0
	s_add_u32 s10, s10, 0x100
	s_addc_u32 s11, s11, 0
	s_cmp_gt_u32 s14, 29
	s_barrier
	s_cbranch_scc0 .LBB0_945
	s_waitcnt lgkmcnt(0)
	s_cmp_gt_i32 s40, 19
	s_cselect_b64 s[42:43], -1, 0
	s_cmp_lt_i32 s40, 4
	v_lshl_add_u32 v150, s8, 8, v139
	s_cselect_b64 s[44:45], -1, 0
	s_mov_b64 s[8:9], -1
	s_and_b64 vcc, exec, s[42:43]
	s_cbranch_vccz .LBB0_954
	s_and_b64 vcc, exec, s[56:57]
	s_cbranch_vccz .LBB0_951
	s_mov_b64 s[68:69], exec
	s_and_b64 s[100:101], exec, s[58:59]
	s_cbranch_scc0 .LBB0_950
	global_load_dword v240, v1, s[54:55]
	global_load_dword v241, v1, s[54:55] offset:4
	global_load_dword v242, v1, s[54:55] offset:8
	global_load_dword v243, v1, s[54:55] offset:12
	global_load_dword v244, v1, s[54:55] offset:16
	global_load_dword v245, v1, s[54:55] offset:20
	global_load_dword v246, v1, s[54:55] offset:24
	global_load_dword v247, v1, s[54:55] offset:28
	v_lshrrev_b32_e32 v239, 4, v215
	v_and_b32_e32 v250, 15, v215
	v_lshlrev_b32_e32 v250, 2, v250
	s_waitcnt vmcnt(0)
	v_mov_b32_e32 v223, v240
	v_mov_b32_e32 v238, v241
	v_cmp_eq_u32_e32 vcc, 1, v239
	s_nop 1
	v_cndmask_b32_e32 v223, v223, v242, vcc
	v_cndmask_b32_e32 v238, v238, v243, vcc
	v_cmp_eq_u32_e32 vcc, 2, v239
	s_nop 1
	v_cndmask_b32_e32 v223, v223, v244, vcc
	v_cndmask_b32_e32 v238, v238, v245, vcc
	v_cmp_eq_u32_e32 vcc, 3, v239
	s_nop 1
	v_cndmask_b32_e32 v223, v223, v246, vcc
	v_cndmask_b32_e32 v238, v238, v247, vcc
	s_mov_b32 s3, 0xbfb8aa3b
	s_mov_b32 s6, 0x3f2aaaab
	s_mov_b32 s7, 0x3f317218
	s_mov_b32 s8, 0x7f800000
	s_mov_b32 s9, 0x33800000
	s_mov_b32 s2, 0x8000
	s_waitcnt lgkmcnt(0)
	ds_bpermute_b32 v126, v250, v126
	ds_bpermute_b32 v127, v250, v127
	ds_bpermute_b32 v128, v250, v128
	ds_bpermute_b32 v129, v250, v129
	ds_bpermute_b32 v122, v250, v122
	ds_bpermute_b32 v123, v250, v123
	ds_bpermute_b32 v124, v250, v124
	ds_bpermute_b32 v125, v250, v125
	s_mov_b32 s100, 0x10800
	v_lshlrev_b32_e32 v251, 2, v150
	s_waitcnt lgkmcnt(0)
	v_mov_b32_e32 v248, v126
	v_mov_b32_e32 v249, v127
	v_cmp_eq_u32_e32 vcc, 1, v239
	s_nop 1
	v_cndmask_b32_e32 v248, v248, v128, vcc
	v_cndmask_b32_e32 v249, v249, v129, vcc
	v_cmp_eq_u32_e32 vcc, 2, v239
	s_nop 1
	v_cndmask_b32_e32 v248, v248, v122, vcc
	v_cndmask_b32_e32 v249, v249, v123, vcc
	v_cmp_eq_u32_e32 vcc, 3, v239
	s_nop 1
	v_cndmask_b32_e32 v248, v248, v124, vcc
	v_cndmask_b32_e32 v249, v249, v125, vcc
	v_mad_u32_u24 v251, v239, s100, v251
	v_add_u32_e32 v246, 0x8400, v251
	v_add_f32_e32 v0, v248, v223
	v_min_f32_e32 v151, 0, v0
	v_mul_f32_e64 v0, |v0|, s3
	v_exp_f32_e32 v0, v0
	s_nop 0
	v_add_f32_e32 v154, 1.0, v0
	v_add_f32_e32 v152, -1.0, v154
	v_sub_f32_e32 v153, v152, v154
	v_add_f32_e32 v153, 1.0, v153
	v_sub_f32_e32 v152, v0, v152
	v_add_f32_e32 v155, v152, v153
	v_frexp_mant_f32_e32 v152, v154
	v_cmp_gt_f32_e32 vcc, s6, v152
	v_cvt_f64_f32_e32 v[152:153], v154
	v_frexp_exp_i32_f64_e32 v152, v[152:153]
	v_subbrev_co_u32_e32 v152, vcc, 0, v152, vcc
	v_sub_u32_e32 v153, 0, v152
	v_ldexp_f32 v154, v154, v153
	v_ldexp_f32 v153, v155, v153
	v_add_f32_e32 v155, -1.0, v154
	v_add_f32_e32 v158, 1.0, v155
	v_sub_f32_e32 v158, v154, v158
	v_add_f32_e32 v158, v153, v158
	v_add_f32_e32 v159, v155, v158
	v_sub_f32_e32 v155, v159, v155
	v_sub_f32_e32 v155, v158, v155
	v_add_f32_e32 v158, 1.0, v154
	v_add_f32_e32 v160, -1.0, v158
	v_sub_f32_e32 v154, v154, v160
	v_add_f32_e32 v153, v153, v154
	v_add_f32_e32 v154, v158, v153
	v_sub_f32_e32 v158, v154, v158
	v_sub_f32_e32 v153, v153, v158
	v_rcp_f32_e32 v158, v154
	v_cvt_f32_i32_e32 v152, v152
	v_cmp_neq_f32_e32 vcc, s8, v0
	v_mul_f32_e32 v160, v159, v158
	v_mul_f32_e32 v161, v154, v160
	v_fma_f32 v162, v160, v154, -v161
	v_fmac_f32_e32 v162, v160, v153
	v_add_f32_e32 v163, v161, v162
	v_sub_f32_e32 v164, v159, v163
	v_sub_f32_e32 v159, v159, v164
	v_sub_f32_e32 v161, v163, v161
	v_sub_f32_e32 v159, v159, v163
	v_add_f32_e32 v155, v155, v159
	v_sub_f32_e32 v159, v161, v162
	v_add_f32_e32 v155, v159, v155
	v_add_f32_e32 v159, v164, v155
	v_mul_f32_e32 v161, v158, v159
	v_mul_f32_e32 v162, v154, v161
	v_fma_f32 v154, v161, v154, -v162
	v_fmac_f32_e32 v154, v161, v153
	v_sub_f32_e32 v153, v164, v159
	v_add_f32_e32 v153, v155, v153
	v_add_f32_e32 v155, v162, v154
	v_sub_f32_e32 v163, v159, v155
	v_sub_f32_e32 v159, v159, v163
	v_sub_f32_e32 v162, v155, v162
	v_sub_f32_e32 v155, v159, v155
	v_add_f32_e32 v153, v153, v155
	v_sub_f32_e32 v154, v162, v154
	v_add_f32_e32 v153, v154, v153
	v_add_f32_e32 v154, v160, v161
	v_add_f32_e32 v153, v163, v153
;     __device__ __forceinline__ void operator()(const AccT& acc, const pg8::Unit& u, int wr, int wc, int fr, int fq) const {
;     ...
;                     } else if (wc == 1 && fq == 0) {
; #pragma unroll
;                         for (int n = 0; n < 2; ++n)
; #pragma unroll
;                             for (int j = 0; j < 4; ++j) {
;                                 const float x = acc[ai][0][m][n][j] * rs + bfg[4 * n + j];
;                                 lf[(4 * n + j) * MROWS + row] = fminf(x, 0.f) - log1pf(__expf(-fabsf(x)));
;                             }
	v_sub_f32_e32 v155, v154, v160
	v_mul_f32_e32 v153, v158, v153
	v_sub_f32_e32 v155, v161, v155
	v_add_f32_e32 v153, v155, v153
	v_mul_f32_e32 v160, 0x3f317218, v152
	v_add_f32_e32 v155, v154, v153
	v_fma_f32 v161, v152, s7, -v160
	v_mul_f32_e32 v158, v155, v155
	v_fmac_f32_e32 v161, 0xb102e308, v152
	v_sub_f32_e32 v152, v155, v154
	v_fmamk_f32 v159, v158, 0x3e9b6dac, v214
	v_sub_f32_e32 v152, v153, v152
	v_add_f32_e32 v153, v160, v161
	v_fmaak_f32 v159, v158, v159, 0x3f2aaada
	v_sub_f32_e32 v154, v153, v160
	v_ldexp_f32 v160, v155, 1
	v_mul_f32_e32 v155, v155, v158
	v_mul_f32_e32 v155, v155, v159
	v_add_f32_e32 v158, v160, v155
	v_sub_f32_e32 v159, v158, v160
	v_ldexp_f32 v152, v152, 1
	v_sub_f32_e32 v155, v155, v159
	v_add_f32_e32 v152, v152, v155
	v_add_f32_e32 v155, v158, v152
	v_sub_f32_e32 v158, v155, v158
	v_sub_f32_e32 v152, v152, v158
	v_add_f32_e32 v158, v153, v155
	v_sub_f32_e32 v159, v158, v153
	v_sub_f32_e32 v160, v158, v159
	v_sub_f32_e32 v154, v161, v154
	v_sub_f32_e32 v153, v153, v160
	v_sub_f32_e32 v155, v155, v159
	v_add_f32_e32 v153, v155, v153
	v_add_f32_e32 v155, v154, v152
	v_sub_f32_e32 v159, v155, v154
	v_sub_f32_e32 v160, v155, v159
	v_sub_f32_e32 v154, v154, v160
	v_sub_f32_e32 v152, v152, v159
	v_add_f32_e32 v153, v155, v153
	v_add_f32_e32 v152, v152, v154
	v_add_f32_e32 v154, v158, v153
	v_sub_f32_e32 v155, v154, v158
	v_sub_f32_e32 v153, v153, v155
	v_add_f32_e32 v152, v152, v153
	v_add_f32_e32 v152, v154, v152
	v_cndmask_b32_e32 v152, v221, v152, vcc
	v_cmp_ngt_f32_e32 vcc, -1.0, v0
	s_nop 1
	v_cndmask_b32_e32 v152, v222, v152, vcc
	v_cmp_neq_f32_e32 vcc, -1.0, v0
	s_nop 1
	v_cndmask_b32_e32 v152, v219, v152, vcc
	v_cmp_lt_f32_e64 vcc, |v0|, s9
	s_nop 1
	v_cndmask_b32_e32 v0, v152, v0, vcc
	v_sub_f32_e32 v0, v151, v0
	global_store_dword v251, v0, s[52:53]
	v_add_f32_e32 v0, v249, v238
	v_min_f32_e32 v151, 0, v0
	v_mul_f32_e64 v0, |v0|, s3
	v_exp_f32_e32 v0, v0
	s_nop 0
	v_add_f32_e32 v154, 1.0, v0
	v_add_f32_e32 v152, -1.0, v154
	v_sub_f32_e32 v153, v152, v154
	v_add_f32_e32 v153, 1.0, v153
	v_sub_f32_e32 v152, v0, v152
	v_add_f32_e32 v155, v152, v153
	v_frexp_mant_f32_e32 v152, v154
	v_cmp_gt_f32_e32 vcc, s6, v152
	v_cvt_f64_f32_e32 v[152:153], v154
	v_frexp_exp_i32_f64_e32 v152, v[152:153]
	v_subbrev_co_u32_e32 v152, vcc, 0, v152, vcc
	v_sub_u32_e32 v153, 0, v152
	v_ldexp_f32 v154, v154, v153
	v_ldexp_f32 v153, v155, v153
	v_add_f32_e32 v155, -1.0, v154
	v_add_f32_e32 v158, 1.0, v155
	v_sub_f32_e32 v158, v154, v158
	v_add_f32_e32 v158, v153, v158
	v_add_f32_e32 v159, v155, v158
	v_sub_f32_e32 v155, v159, v155
	v_sub_f32_e32 v155, v158, v155
	v_add_f32_e32 v158, 1.0, v154
	v_add_f32_e32 v160, -1.0, v158
	v_sub_f32_e32 v154, v154, v160
	v_add_f32_e32 v153, v153, v154
	v_add_f32_e32 v154, v158, v153
	v_sub_f32_e32 v158, v154, v158
	v_sub_f32_e32 v153, v153, v158
	v_rcp_f32_e32 v158, v154
	v_cvt_f32_i32_e32 v152, v152
	v_cmp_neq_f32_e32 vcc, s8, v0
	v_mul_f32_e32 v160, v159, v158
	v_mul_f32_e32 v161, v154, v160
	v_fma_f32 v162, v160, v154, -v161
	v_fmac_f32_e32 v162, v160, v153
	v_add_f32_e32 v163, v161, v162
	v_sub_f32_e32 v164, v159, v163
	v_sub_f32_e32 v159, v159, v164
	v_sub_f32_e32 v161, v163, v161
	v_sub_f32_e32 v159, v159, v163
	v_add_f32_e32 v155, v155, v159
	v_sub_f32_e32 v159, v161, v162
	v_add_f32_e32 v155, v159, v155
	v_add_f32_e32 v159, v164, v155
	v_mul_f32_e32 v161, v158, v159
	v_mul_f32_e32 v162, v154, v161
	v_fma_f32 v154, v161, v154, -v162
	v_fmac_f32_e32 v154, v161, v153
	v_sub_f32_e32 v153, v164, v159
	v_add_f32_e32 v153, v155, v153
	v_add_f32_e32 v155, v162, v154
	v_sub_f32_e32 v163, v159, v155
	v_sub_f32_e32 v159, v159, v163
	v_sub_f32_e32 v162, v155, v162
	v_sub_f32_e32 v155, v159, v155
	v_add_f32_e32 v153, v153, v155
	v_sub_f32_e32 v154, v162, v154
	v_add_f32_e32 v153, v154, v153
	v_add_f32_e32 v154, v160, v161
	v_add_f32_e32 v153, v163, v153
	v_sub_f32_e32 v155, v154, v160
	v_mul_f32_e32 v153, v158, v153
	v_sub_f32_e32 v155, v161, v155
	v_add_f32_e32 v153, v155, v153
	v_mul_f32_e32 v160, 0x3f317218, v152
	v_add_f32_e32 v155, v154, v153
	v_fma_f32 v161, v152, s7, -v160
	v_mul_f32_e32 v158, v155, v155
	v_fmac_f32_e32 v161, 0xb102e308, v152
	v_sub_f32_e32 v152, v155, v154
	v_fmamk_f32 v159, v158, 0x3e9b6dac, v214
	v_sub_f32_e32 v152, v153, v152
	v_add_f32_e32 v153, v160, v161
	v_fmaak_f32 v159, v158, v159, 0x3f2aaada
	v_sub_f32_e32 v154, v153, v160
	v_ldexp_f32 v160, v155, 1
	v_mul_f32_e32 v155, v155, v158
	v_mul_f32_e32 v155, v155, v159
	v_add_f32_e32 v158, v160, v155
	v_sub_f32_e32 v159, v158, v160
	v_ldexp_f32 v152, v152, 1
	v_sub_f32_e32 v155, v155, v159
	v_add_f32_e32 v152, v152, v155
	v_add_f32_e32 v155, v158, v152
	v_sub_f32_e32 v158, v155, v158
	v_sub_f32_e32 v152, v152, v158
	v_add_f32_e32 v158, v153, v155
	v_sub_f32_e32 v159, v158, v153
	v_sub_f32_e32 v160, v158, v159
	v_sub_f32_e32 v154, v161, v154
	v_sub_f32_e32 v153, v153, v160
	v_sub_f32_e32 v155, v155, v159
	v_add_f32_e32 v153, v155, v153
	v_add_f32_e32 v155, v154, v152
	v_sub_f32_e32 v159, v155, v154
	v_sub_f32_e32 v160, v155, v159
	v_sub_f32_e32 v154, v154, v160
	v_sub_f32_e32 v152, v152, v159
	v_add_f32_e32 v153, v155, v153
	v_add_f32_e32 v152, v152, v154
	v_add_f32_e32 v154, v158, v153
	v_sub_f32_e32 v155, v154, v158
	v_sub_f32_e32 v153, v153, v155
	v_add_f32_e32 v152, v152, v153
	v_add_f32_e32 v152, v154, v152
	v_cndmask_b32_e32 v152, v221, v152, vcc
	v_cmp_ngt_f32_e32 vcc, -1.0, v0
	s_nop 1
	v_cndmask_b32_e32 v152, v222, v152, vcc
	v_cmp_neq_f32_e32 vcc, -1.0, v0
	s_nop 1
	v_cndmask_b32_e32 v152, v219, v152, vcc
	v_cmp_lt_f32_e64 vcc, |v0|, s9
	s_nop 1
	v_cndmask_b32_e32 v0, v152, v0, vcc
	v_sub_f32_e32 v0, v151, v0
	global_store_dword v246, v0, s[52:53]

; #define PG8_STAGE(bufoff, gbase, voff) do { _Pragma("unroll") for (int _i = 0; _i < 2; ++_i) \
;         __builtin_amdgcn_global_load_lds((const unsigned*)((const char*)(gbase) + (voff)[_i]), (LAS unsigned*)(lds + (bufoff) + ldsw + _i * 8192), 16, 0, 0); } while (0)
; #define PG8_LDA(dst, b, h) do { _Pragma("unroll") for (int m = 0; m < 4; ++m) _Pragma("unroll") for (int k = 0; k < 2; ++k) dst[m][k] = *(const LAS bf16x8*)(lds + PG8_SA(b, h) + aoff + m * 2048 + k * 1024); } while (0)
; #define PG8_LDB(dst, b, h) do { _Pragma("unroll") for (int n = 0; n < 2; ++n) _Pragma("unroll") for (int k = 0; k < 2; ++k) dst[n][k] = *(const LAS bf16x8*)(lds + PG8_SB(b, h) + boff + n * 2048 + k * 1024); } while (0)
; #define PG8_MMA(ai, bj, At, Bt) do { __builtin_amdgcn_s_setprio(1); _Pragma("unroll") for (int m = 0; m < 4; ++m) _Pragma("unroll") for (int n = 0; n < 2; ++n) _Pragma("unroll") for (int k = 0; k < 2; ++k) \
;         acc[ai][bj][m][n] = __builtin_amdgcn_mfma_f32_16x16x32_bf16(Bt[n][k], At[m][k], acc[ai][bj][m][n], 0, 0, 0); __builtin_amdgcn_s_setprio(0); } while (0)
; #define PG8_BAR __builtin_amdgcn_s_barrier()
; template <class Epi, class Sched>
; __device__ __forceinline__ void gemm_phase(LAS unsigned char* lds, const Gemm g, const Sched& S, const Epi& E) {
;     ...
;     for (;;) {
;         const bool has_next = S.next(ui + 1, nxt);
;         const char* nA = has_next ? PG8_APTR(nxt) : cA; const char* nB = has_next ? PG8_BPTR(nxt) : cB;
;         const int nt = cur.nt;
;         for (int t = 0; t < nt; t += 2) {
;             const bool last = (t == nt - 2);
;             const char* a1 = cA + (size_t)(t + 1) * kstep;
;             const char* a2 = last ? nA : cA + (size_t)(t + 2) * kstep; const char* b2 = last ? nB : cB + (size_t)(t + 2) * kstep;
;             const char* a3 = a2 + kstep; const char* b3 = b2 + kstep;
;             PG8_LDB(B0, 0, 0); PG8_SCHED; PG8_LDA(At, 0, 0); PG8_STAGE(PG8_SA(1, 1), a1 + hstepA, voffA);
;             PG8_WAIT_L(8); PG8_BAR; PG8_WAIT_L(0); PG8_MMA(0, 0, At, B0); PG8_BAR; PG8_SCHED;
;     ...
; #pragma unroll
;         for (int a = 0; a < 2; ++a)
; #pragma unroll
;             for (int b = 0; b < 2; ++b)
; #pragma unroll
;                 for (int m = 0; m < 4; ++m)
; #pragma unroll
;                     for (int n = 0; n < 2; ++n) acc[a][b][m][n] = (f32x4){0.f, 0.f, 0.f, 0.f};
;         cur = nxt; cA = nA; cB = nB; ++ui;
.LBB0_1426:
	s_ashr_i32 s49, s48, 31
	s_lshl_b64 s[6:7], s[48:49], 18
	s_add_u32 s52, s13, s6
	s_addc_u32 s53, s20, s7
	s_and_b64 s[0:1], s[0:1], exec
	s_cselect_b32 s3, s53, s17
	s_cselect_b32 s6, s52, s16
	s_add_u32 s7, s16, 0x100
	v_mov_b32_e32 v2, 0
	s_addc_u32 s9, s17, 0
	s_mov_b32 s14, -2
	v_mov_b32_e32 v3, v2
	v_mov_b32_e32 v4, v2
	v_mov_b32_e32 v5, v2
	v_mov_b32_e32 v6, v2
	v_mov_b32_e32 v7, v2
	v_mov_b32_e32 v8, v2
	v_mov_b32_e32 v9, v2
	v_mov_b32_e32 v18, v2
	v_mov_b32_e32 v19, v2
	v_mov_b32_e32 v20, v2
	v_mov_b32_e32 v21, v2
	v_mov_b32_e32 v22, v2
	v_mov_b32_e32 v23, v2
	v_mov_b32_e32 v24, v2
	v_mov_b32_e32 v25, v2
	v_mov_b32_e32 v34, v2
	v_mov_b32_e32 v35, v2
	v_mov_b32_e32 v36, v2
	v_mov_b32_e32 v37, v2
	v_mov_b32_e32 v38, v2
	v_mov_b32_e32 v39, v2
	v_mov_b32_e32 v40, v2
	v_mov_b32_e32 v41, v2
	v_mov_b32_e32 v50, v2
	v_mov_b32_e32 v51, v2
	v_mov_b32_e32 v52, v2
	v_mov_b32_e32 v53, v2
	v_mov_b32_e32 v54, v2
	v_mov_b32_e32 v55, v2
	v_mov_b32_e32 v56, v2
	v_mov_b32_e32 v57, v2
	v_mov_b32_e32 v10, v2
	v_mov_b32_e32 v11, v2
	v_mov_b32_e32 v12, v2
	v_mov_b32_e32 v13, v2
	v_mov_b32_e32 v14, v2
	v_mov_b32_e32 v15, v2
	v_mov_b32_e32 v16, v2
	v_mov_b32_e32 v17, v2
	v_mov_b32_e32 v26, v2
	v_mov_b32_e32 v27, v2
	v_mov_b32_e32 v28, v2
	v_mov_b32_e32 v29, v2
	v_mov_b32_e32 v30, v2
	v_mov_b32_e32 v31, v2
	v_mov_b32_e32 v32, v2
	v_mov_b32_e32 v33, v2
	v_mov_b32_e32 v42, v2
	v_mov_b32_e32 v43, v2
	v_mov_b32_e32 v44, v2
	v_mov_b32_e32 v45, v2
	v_mov_b32_e32 v46, v2
	v_mov_b32_e32 v47, v2
	v_mov_b32_e32 v48, v2
	v_mov_b32_e32 v49, v2
	v_mov_b32_e32 v58, v2
	v_mov_b32_e32 v59, v2
	v_mov_b32_e32 v60, v2
	v_mov_b32_e32 v61, v2
	v_mov_b32_e32 v62, v2
	v_mov_b32_e32 v63, v2
	v_mov_b32_e32 v64, v2
	v_mov_b32_e32 v65, v2
	v_mov_b32_e32 v66, v2
	v_mov_b32_e32 v67, v2
	v_mov_b32_e32 v68, v2
	v_mov_b32_e32 v69, v2
	v_mov_b32_e32 v70, v2
	v_mov_b32_e32 v71, v2
	v_mov_b32_e32 v72, v2
	v_mov_b32_e32 v73, v2
	v_mov_b32_e32 v82, v2
	v_mov_b32_e32 v83, v2
	v_mov_b32_e32 v84, v2
	v_mov_b32_e32 v85, v2
	v_mov_b32_e32 v86, v2
	v_mov_b32_e32 v87, v2
	v_mov_b32_e32 v88, v2
	v_mov_b32_e32 v89, v2
	v_mov_b32_e32 v98, v2
	v_mov_b32_e32 v99, v2
	v_mov_b32_e32 v100, v2
	v_mov_b32_e32 v101, v2
	v_mov_b32_e32 v102, v2
	v_mov_b32_e32 v103, v2
	v_mov_b32_e32 v104, v2
	v_mov_b32_e32 v105, v2
	v_mov_b32_e32 v114, v2
	v_mov_b32_e32 v115, v2
	v_mov_b32_e32 v116, v2
	v_mov_b32_e32 v117, v2
	v_mov_b32_e32 v118, v2
	v_mov_b32_e32 v119, v2
	v_mov_b32_e32 v120, v2
	v_mov_b32_e32 v121, v2
	v_mov_b32_e32 v74, v2
	v_mov_b32_e32 v75, v2
	v_mov_b32_e32 v76, v2
	v_mov_b32_e32 v77, v2
	v_mov_b32_e32 v78, v2
	v_mov_b32_e32 v79, v2
	v_mov_b32_e32 v80, v2
	v_mov_b32_e32 v81, v2
	v_mov_b32_e32 v90, v2
	v_mov_b32_e32 v91, v2
	v_mov_b32_e32 v92, v2
	v_mov_b32_e32 v93, v2
	v_mov_b32_e32 v94, v2
	v_mov_b32_e32 v95, v2
	v_mov_b32_e32 v96, v2
	v_mov_b32_e32 v97, v2
	v_mov_b32_e32 v106, v2
	v_mov_b32_e32 v107, v2
	v_mov_b32_e32 v108, v2
	v_mov_b32_e32 v109, v2
	v_mov_b32_e32 v110, v2
	v_mov_b32_e32 v111, v2
	v_mov_b32_e32 v112, v2
	v_mov_b32_e32 v113, v2
	v_mov_b32_e32 v122, v2
	v_mov_b32_e32 v123, v2
	v_mov_b32_e32 v124, v2
	v_mov_b32_e32 v125, v2
	v_mov_b32_e32 v126, v2
	v_mov_b32_e32 v127, v2
	v_mov_b32_e32 v128, v2
	v_mov_b32_e32 v129, v2
	v_add_u32_e32 v0, 0x10000, v164
	ds_read_b128 v[130:133], v0
	ds_read_b128 v[152:155], v0 offset:1024
	ds_read_b128 v[156:159], v0 offset:2048
	ds_read_b128 v[160:163], v0 offset:3072
.LBB0_1427:
	s_add_u32 s0, s10, 0x100
	s_addc_u32 s1, s11, 0
	s_add_i32 s24, 0, 0x10000
	v_add_u32_e32 v0, s24, v164
	s_cmp_eq_u32 s14, 4
	s_cselect_b32 s19, s51, s1
	s_cselect_b32 s18, s50, s0
	s_cselect_b32 s17, s3, s9
	s_cselect_b32 s16, s6, s7
	v_lshl_add_u64 v[194:195], s[10:11], 0, v[150:151]
	s_add_i32 m0, s22, 0xc000
	ds_read_b128 v[166:169], v165
	ds_read_b128 v[170:173], v165 offset:1024
	ds_read_b128 v[174:177], v165 offset:2048
	ds_read_b128 v[178:181], v165 offset:3072
	ds_read_b128 v[182:185], v165 offset:4096
	ds_read_b128 v[186:189], v165 offset:5120
	ds_read_b128 v[190:193], v165 offset:6144
	ds_read_b128 v[198:201], v165 offset:7168
	global_load_lds_dwordx4 v[194:195], off
	v_lshl_add_u64 v[194:195], s[10:11], 0, v[148:149]
	s_add_i32 m0, s22, 0xe000
	s_nop 0
	global_load_lds_dwordx4 v[194:195], off
	s_waitcnt lgkmcnt(8)
	s_barrier
	s_waitcnt lgkmcnt(0)
	s_setprio 1
	s_waitcnt lgkmcnt(0)
	v_mfma_f32_16x16x32_bf16 v[126:129], v[130:133], v[166:169], v[126:129]
	v_mfma_f32_16x16x32_bf16 v[122:125], v[156:159], v[166:169], v[122:125]
	v_mfma_f32_16x16x32_bf16 v[110:113], v[130:133], v[174:177], v[110:113]
	v_mfma_f32_16x16x32_bf16 v[106:109], v[156:159], v[174:177], v[106:109]
	v_mfma_f32_16x16x32_bf16 v[94:97], v[130:133], v[182:185], v[94:97]
	v_mfma_f32_16x16x32_bf16 v[90:93], v[156:159], v[182:185], v[90:93]
	v_mfma_f32_16x16x32_bf16 v[78:81], v[130:133], v[190:193], v[78:81]
	v_mfma_f32_16x16x32_bf16 v[74:77], v[156:159], v[190:193], v[74:77]
	v_mfma_f32_16x16x32_bf16 v[126:129], v[152:155], v[170:173], v[126:129]
	v_mfma_f32_16x16x32_bf16 v[122:125], v[160:163], v[170:173], v[122:125]
	v_mfma_f32_16x16x32_bf16 v[110:113], v[152:155], v[178:181], v[110:113]
	v_mfma_f32_16x16x32_bf16 v[106:109], v[160:163], v[178:181], v[106:109]
	v_mfma_f32_16x16x32_bf16 v[94:97], v[152:155], v[186:189], v[94:97]
	v_mfma_f32_16x16x32_bf16 v[90:93], v[160:163], v[186:189], v[90:93]
	v_mfma_f32_16x16x32_bf16 v[78:81], v[152:155], v[198:201], v[78:81]
	v_mfma_f32_16x16x32_bf16 v[74:77], v[160:163], v[198:201], v[74:77]
	s_setprio 0
	s_barrier
; #define PG8_STAGE(bufoff, gbase, voff) do { _Pragma("unroll") for (int _i = 0; _i < 2; ++_i) \
;         __builtin_amdgcn_global_load_lds((const unsigned*)((const char*)(gbase) + (voff)[_i]), (LAS unsigned*)(lds + (bufoff) + ldsw + _i * 8192), 16, 0, 0); } while (0)
; #define PG8_LDA(dst, b, h) do { _Pragma("unroll") for (int m = 0; m < 4; ++m) _Pragma("unroll") for (int k = 0; k < 2; ++k) dst[m][k] = *(const LAS bf16x8*)(lds + PG8_SA(b, h) + aoff + m * 2048 + k * 1024); } while (0)
; #define PG8_LDB(dst, b, h) do { _Pragma("unroll") for (int n = 0; n < 2; ++n) _Pragma("unroll") for (int k = 0; k < 2; ++k) dst[n][k] = *(const LAS bf16x8*)(lds + PG8_SB(b, h) + boff + n * 2048 + k * 1024); } while (0)
; #define PG8_MMA(ai, bj, At, Bt) do { __builtin_amdgcn_s_setprio(1); _Pragma("unroll") for (int m = 0; m < 4; ++m) _Pragma("unroll") for (int n = 0; n < 2; ++n) _Pragma("unroll") for (int k = 0; k < 2; ++k) \
;         acc[ai][bj][m][n] = __builtin_amdgcn_mfma_f32_16x16x32_bf16(Bt[n][k], At[m][k], acc[ai][bj][m][n], 0, 0, 0); __builtin_amdgcn_s_setprio(0); } while (0)
; #define PG8_WAIT_V(n) asm volatile("s_waitcnt vmcnt(" #n ")" ::: "memory")
; #define PG8_WAIT_L(n) asm volatile("s_waitcnt lgkmcnt(" #n ")" ::: "memory")
; #define PG8_BAR __builtin_amdgcn_s_barrier()
; #define PG8_SCHED __builtin_amdgcn_sched_barrier(0)
; template <class Epi, class Sched>
; __device__ __forceinline__ void gemm_phase(LAS unsigned char* lds, const Gemm g, const Sched& S, const Epi& E) {
;     ...
;             PG8_LDB(B1, 0, 1); PG8_STAGE(PG8_SB(0, 0), b2, voffB);
;             PG8_BAR; PG8_WAIT_L(0); PG8_MMA(0, 1, At, B1); PG8_BAR;
;             PG8_LDA(At, 0, 1); PG8_STAGE(PG8_SA(0, 0), a2, voffA);
;             PG8_BAR; PG8_WAIT_L(0); PG8_MMA(1, 0, At, B0); PG8_BAR; PG8_SCHED;
;             PG8_STAGE(PG8_SB(0, 1), b2 + hstepB, voffB);
;             PG8_WAIT_V(6); PG8_BAR; PG8_MMA(1, 1, At, B1); PG8_BAR;
;             PG8_LDB(B0, 1, 0); PG8_SCHED; PG8_LDA(At, 1, 0); PG8_STAGE(PG8_SA(0, 1), a2 + hstepA, voffA);
	s_add_i32 s25, 0, 0x14000
	s_add_i32 s10, s24, s21
	v_add_u32_e32 v0, s25, v164
	v_lshl_add_u64 v[194:195], s[16:17], 0, v[136:137]
	s_mov_b32 m0, s10
	ds_read_b128 v[202:205], v0
	ds_read_b128 v[206:209], v0 offset:1024
	ds_read_b128 v[224:227], v0 offset:2048
	ds_read_b128 v[228:231], v0 offset:3072
	global_load_lds_dwordx4 v[194:195], off
	v_lshl_add_u64 v[196:197], s[16:17], 0, v[140:141]
	s_add_i32 m0, s10, 0x2000
	s_nop 0
	global_load_lds_dwordx4 v[196:197], off
	s_waitcnt vmcnt(8)
	s_barrier
	s_waitcnt lgkmcnt(0)
	s_setprio 1
	s_waitcnt lgkmcnt(0)
	v_mfma_f32_16x16x32_bf16 v[118:121], v[202:205], v[166:169], v[118:121]
	v_mfma_f32_16x16x32_bf16 v[114:117], v[224:227], v[166:169], v[114:117]
	v_mfma_f32_16x16x32_bf16 v[102:105], v[202:205], v[174:177], v[102:105]
	v_mfma_f32_16x16x32_bf16 v[98:101], v[224:227], v[174:177], v[98:101]
	v_mfma_f32_16x16x32_bf16 v[86:89], v[202:205], v[182:185], v[86:89]
	v_mfma_f32_16x16x32_bf16 v[82:85], v[224:227], v[182:185], v[82:85]
	v_mfma_f32_16x16x32_bf16 v[70:73], v[202:205], v[190:193], v[70:73]
	v_mfma_f32_16x16x32_bf16 v[66:69], v[224:227], v[190:193], v[66:69]
	v_mfma_f32_16x16x32_bf16 v[118:121], v[206:209], v[170:173], v[118:121]
	v_mfma_f32_16x16x32_bf16 v[114:117], v[228:231], v[170:173], v[114:117]
	v_mfma_f32_16x16x32_bf16 v[102:105], v[206:209], v[178:181], v[102:105]
	v_mfma_f32_16x16x32_bf16 v[98:101], v[228:231], v[178:181], v[98:101]
	v_mfma_f32_16x16x32_bf16 v[86:89], v[206:209], v[186:189], v[86:89]
	v_mfma_f32_16x16x32_bf16 v[82:85], v[228:231], v[186:189], v[82:85]
	v_mfma_f32_16x16x32_bf16 v[70:73], v[206:209], v[198:201], v[70:73]
	v_mfma_f32_16x16x32_bf16 v[66:69], v[228:231], v[198:201], v[66:69]
	s_setprio 0
	s_mov_b32 m0, s22
	v_lshl_add_u64 v[232:233], s[18:19], 0, v[134:135]
	s_barrier
	ds_read_b128 v[166:169], v165 offset:16384
	ds_read_b128 v[170:173], v165 offset:17408
	ds_read_b128 v[174:177], v165 offset:18432
	ds_read_b128 v[178:181], v165 offset:19456
	ds_read_b128 v[182:185], v165 offset:20480
	ds_read_b128 v[186:189], v165 offset:21504
	ds_read_b128 v[190:193], v165 offset:22528
	ds_read_b128 v[198:201], v165 offset:23552
	global_load_lds_dwordx4 v[232:233], off
	v_lshl_add_u64 v[234:235], s[18:19], 0, v[138:139]
	s_mov_b32 m0, s23
	s_nop 0
	global_load_lds_dwordx4 v[234:235], off
	s_barrier
	s_waitcnt lgkmcnt(0)
	s_setprio 1
	s_waitcnt lgkmcnt(0)
	v_mfma_f32_16x16x32_bf16 v[62:65], v[130:133], v[166:169], v[62:65]
	v_mfma_f32_16x16x32_bf16 v[58:61], v[156:159], v[166:169], v[58:61]
	v_mfma_f32_16x16x32_bf16 v[46:49], v[130:133], v[174:177], v[46:49]
	v_mfma_f32_16x16x32_bf16 v[42:45], v[156:159], v[174:177], v[42:45]
	v_mfma_f32_16x16x32_bf16 v[30:33], v[130:133], v[182:185], v[30:33]
	v_mfma_f32_16x16x32_bf16 v[26:29], v[156:159], v[182:185], v[26:29]
	v_mfma_f32_16x16x32_bf16 v[14:17], v[130:133], v[190:193], v[14:17]
	v_mfma_f32_16x16x32_bf16 v[10:13], v[156:159], v[190:193], v[10:13]
	v_mfma_f32_16x16x32_bf16 v[62:65], v[152:155], v[170:173], v[62:65]
	v_mfma_f32_16x16x32_bf16 v[58:61], v[160:163], v[170:173], v[58:61]
	v_mfma_f32_16x16x32_bf16 v[46:49], v[152:155], v[178:181], v[46:49]
	v_mfma_f32_16x16x32_bf16 v[42:45], v[160:163], v[178:181], v[42:45]
	v_mfma_f32_16x16x32_bf16 v[30:33], v[152:155], v[186:189], v[30:33]
	v_mfma_f32_16x16x32_bf16 v[26:29], v[160:163], v[186:189], v[26:29]
	v_mfma_f32_16x16x32_bf16 v[14:17], v[152:155], v[198:201], v[14:17]
	v_mfma_f32_16x16x32_bf16 v[10:13], v[160:163], v[198:201], v[10:13]
	s_setprio 0
	s_barrier
	s_add_u32 s10, s16, 0x20000
	s_addc_u32 s11, s17, 0
	s_add_i32 s24, s25, s21
	v_lshl_add_u64 v[130:131], s[10:11], 0, v[136:137]
	s_mov_b32 m0, s24
	s_nop 0
	global_load_lds_dwordx4 v[130:131], off
	v_lshl_add_u64 v[130:131], s[10:11], 0, v[140:141]
	s_add_i32 m0, s24, 0x2000
	s_nop 0
	global_load_lds_dwordx4 v[130:131], off
	v_add_u32_e32 v0, 0x18000, v164
	ds_read_b128 v[130:133], v0
	ds_read_b128 v[152:155], v0 offset:1024
	ds_read_b128 v[156:159], v0 offset:2048
	ds_read_b128 v[160:163], v0 offset:3072
	s_waitcnt vmcnt(6)
	s_barrier
	s_setprio 1
	v_mfma_f32_16x16x32_bf16 v[54:57], v[202:205], v[166:169], v[54:57]
	v_mfma_f32_16x16x32_bf16 v[50:53], v[224:227], v[166:169], v[50:53]
	v_mfma_f32_16x16x32_bf16 v[38:41], v[202:205], v[174:177], v[38:41]
	v_mfma_f32_16x16x32_bf16 v[34:37], v[224:227], v[174:177], v[34:37]
	v_mfma_f32_16x16x32_bf16 v[22:25], v[202:205], v[182:185], v[22:25]
	v_mfma_f32_16x16x32_bf16 v[18:21], v[224:227], v[182:185], v[18:21]
	v_mfma_f32_16x16x32_bf16 v[6:9], v[202:205], v[190:193], v[6:9]
	v_mfma_f32_16x16x32_bf16 v[2:5], v[224:227], v[190:193], v[2:5]
	v_mfma_f32_16x16x32_bf16 v[54:57], v[206:209], v[170:173], v[54:57]
	v_mfma_f32_16x16x32_bf16 v[50:53], v[228:231], v[170:173], v[50:53]
	v_mfma_f32_16x16x32_bf16 v[38:41], v[206:209], v[178:181], v[38:41]
	v_mfma_f32_16x16x32_bf16 v[34:37], v[228:231], v[178:181], v[34:37]
	v_mfma_f32_16x16x32_bf16 v[22:25], v[206:209], v[186:189], v[22:25]
	v_mfma_f32_16x16x32_bf16 v[18:21], v[228:231], v[186:189], v[18:21]
	v_mfma_f32_16x16x32_bf16 v[6:9], v[206:209], v[198:201], v[6:9]
	v_mfma_f32_16x16x32_bf16 v[2:5], v[228:231], v[198:201], v[2:5]
	s_setprio 0
	s_add_i32 s24, 0, 0x18000
	v_add_u32_e32 v0, s24, v164
	s_barrier
	s_add_u32 s10, s18, 0x150000
	s_addc_u32 s11, s19, 0
	s_mov_b32 m0, s58
	v_lshl_add_u64 v[202:203], s[10:11], 0, v[134:135]
	ds_read_b128 v[166:169], v165 offset:32768
	ds_read_b128 v[170:173], v165 offset:33792
	ds_read_b128 v[174:177], v165 offset:34816
	ds_read_b128 v[178:181], v165 offset:35840
	ds_read_b128 v[182:185], v165 offset:36864
	ds_read_b128 v[186:189], v165 offset:37888
	ds_read_b128 v[190:193], v165 offset:38912
	ds_read_b128 v[198:201], v165 offset:39936
	global_load_lds_dwordx4 v[202:203], off
	v_lshl_add_u64 v[202:203], s[10:11], 0, v[138:139]
	s_mov_b32 m0, s59
	s_nop 0
	global_load_lds_dwordx4 v[202:203], off
	s_waitcnt lgkmcnt(8)
	s_barrier
; #define PG8_STAGE(bufoff, gbase, voff) do { _Pragma("unroll") for (int _i = 0; _i < 2; ++_i) \
;         __builtin_amdgcn_global_load_lds((const unsigned*)((const char*)(gbase) + (voff)[_i]), (LAS unsigned*)(lds + (bufoff) + ldsw + _i * 8192), 16, 0, 0); } while (0)
; #define PG8_LDA(dst, b, h) do { _Pragma("unroll") for (int m = 0; m < 4; ++m) _Pragma("unroll") for (int k = 0; k < 2; ++k) dst[m][k] = *(const LAS bf16x8*)(lds + PG8_SA(b, h) + aoff + m * 2048 + k * 1024); } while (0)
; #define PG8_LDB(dst, b, h) do { _Pragma("unroll") for (int n = 0; n < 2; ++n) _Pragma("unroll") for (int k = 0; k < 2; ++k) dst[n][k] = *(const LAS bf16x8*)(lds + PG8_SB(b, h) + boff + n * 2048 + k * 1024); } while (0)
; #define PG8_MMA(ai, bj, At, Bt) do { __builtin_amdgcn_s_setprio(1); _Pragma("unroll") for (int m = 0; m < 4; ++m) _Pragma("unroll") for (int n = 0; n < 2; ++n) _Pragma("unroll") for (int k = 0; k < 2; ++k) \
;         acc[ai][bj][m][n] = __builtin_amdgcn_mfma_f32_16x16x32_bf16(Bt[n][k], At[m][k], acc[ai][bj][m][n], 0, 0, 0); __builtin_amdgcn_s_setprio(0); } while (0)
; #define PG8_WAIT_L(n) asm volatile("s_waitcnt lgkmcnt(" #n ")" ::: "memory")
; #define PG8_BAR __builtin_amdgcn_s_barrier()
; #define PG8_SCHED __builtin_amdgcn_sched_barrier(0)
; template <class Epi, class Sched>
; __device__ __forceinline__ void gemm_phase(LAS unsigned char* lds, const Gemm g, const Sched& S, const Epi& E) {
;     ...
;             PG8_WAIT_L(8); PG8_BAR; PG8_WAIT_L(0); PG8_MMA(0, 0, At, B0); PG8_BAR; PG8_SCHED;
;             PG8_LDB(B1, 1, 1); PG8_STAGE(PG8_SB(1, 0), b3, voffB);
;             PG8_BAR; PG8_WAIT_L(0); PG8_MMA(0, 1, At, B1); PG8_BAR;
;             PG8_LDA(At, 1, 1); PG8_STAGE(PG8_SA(1, 0), a3, voffA);
;             PG8_BAR; PG8_WAIT_L(0); PG8_MMA(1, 0, At, B0); PG8_BAR; PG8_SCHED;
;             PG8_STAGE(PG8_SB(1, 1), b3 + hstepB, voffB);
	s_waitcnt lgkmcnt(0)
	s_setprio 1
	s_waitcnt lgkmcnt(0)
	v_mfma_f32_16x16x32_bf16 v[126:129], v[130:133], v[166:169], v[126:129]
	v_mfma_f32_16x16x32_bf16 v[122:125], v[156:159], v[166:169], v[122:125]
	v_mfma_f32_16x16x32_bf16 v[110:113], v[130:133], v[174:177], v[110:113]
	v_mfma_f32_16x16x32_bf16 v[106:109], v[156:159], v[174:177], v[106:109]
	v_mfma_f32_16x16x32_bf16 v[94:97], v[130:133], v[182:185], v[94:97]
	v_mfma_f32_16x16x32_bf16 v[90:93], v[156:159], v[182:185], v[90:93]
	v_mfma_f32_16x16x32_bf16 v[78:81], v[130:133], v[190:193], v[78:81]
	v_mfma_f32_16x16x32_bf16 v[74:77], v[156:159], v[190:193], v[74:77]
	v_mfma_f32_16x16x32_bf16 v[126:129], v[152:155], v[170:173], v[126:129]
	v_mfma_f32_16x16x32_bf16 v[122:125], v[160:163], v[170:173], v[122:125]
	v_mfma_f32_16x16x32_bf16 v[110:113], v[152:155], v[178:181], v[110:113]
	v_mfma_f32_16x16x32_bf16 v[106:109], v[160:163], v[178:181], v[106:109]
	v_mfma_f32_16x16x32_bf16 v[94:97], v[152:155], v[186:189], v[94:97]
	v_mfma_f32_16x16x32_bf16 v[90:93], v[160:163], v[186:189], v[90:93]
	v_mfma_f32_16x16x32_bf16 v[78:81], v[152:155], v[198:201], v[78:81]
	v_mfma_f32_16x16x32_bf16 v[74:77], v[160:163], v[198:201], v[74:77]
	s_setprio 0
	s_barrier
	s_add_i32 s18, 0, 0x1c000
	s_add_i32 s10, s24, s21
	v_add_u32_e32 v0, s18, v164
	v_lshl_add_u64 v[194:195], v[194:195], 0, s[26:27]
	s_mov_b32 m0, s10
	ds_read_b128 v[202:205], v0
	ds_read_b128 v[206:209], v0 offset:1024
	ds_read_b128 v[224:227], v0 offset:2048
	ds_read_b128 v[228:231], v0 offset:3072
	global_load_lds_dwordx4 v[194:195], off
	v_lshl_add_u64 v[194:195], v[196:197], 0, s[26:27]
	s_add_i32 m0, s10, 0x2000
	s_nop 0
	global_load_lds_dwordx4 v[194:195], off
	s_waitcnt vmcnt(8)
	s_barrier
	s_waitcnt lgkmcnt(0)
	s_setprio 1
	s_waitcnt lgkmcnt(0)
	v_mfma_f32_16x16x32_bf16 v[118:121], v[202:205], v[166:169], v[118:121]
	v_mfma_f32_16x16x32_bf16 v[114:117], v[224:227], v[166:169], v[114:117]
	v_mfma_f32_16x16x32_bf16 v[102:105], v[202:205], v[174:177], v[102:105]
	v_mfma_f32_16x16x32_bf16 v[98:101], v[224:227], v[174:177], v[98:101]
	v_mfma_f32_16x16x32_bf16 v[86:89], v[202:205], v[182:185], v[86:89]
	v_mfma_f32_16x16x32_bf16 v[82:85], v[224:227], v[182:185], v[82:85]
	v_mfma_f32_16x16x32_bf16 v[70:73], v[202:205], v[190:193], v[70:73]
	v_mfma_f32_16x16x32_bf16 v[66:69], v[224:227], v[190:193], v[66:69]
	v_mfma_f32_16x16x32_bf16 v[118:121], v[206:209], v[170:173], v[118:121]
	v_mfma_f32_16x16x32_bf16 v[114:117], v[228:231], v[170:173], v[114:117]
	v_mfma_f32_16x16x32_bf16 v[102:105], v[206:209], v[178:181], v[102:105]
	v_mfma_f32_16x16x32_bf16 v[98:101], v[228:231], v[178:181], v[98:101]
	v_mfma_f32_16x16x32_bf16 v[86:89], v[206:209], v[186:189], v[86:89]
	v_mfma_f32_16x16x32_bf16 v[82:85], v[228:231], v[186:189], v[82:85]
	v_mfma_f32_16x16x32_bf16 v[70:73], v[206:209], v[198:201], v[70:73]
	v_mfma_f32_16x16x32_bf16 v[66:69], v[228:231], v[198:201], v[66:69]
	s_setprio 0
	s_mov_b32 m0, s61
	v_lshl_add_u64 v[194:195], v[232:233], 0, s[26:27]
	s_barrier
	ds_read_b128 v[166:169], v165 offset:49152
	ds_read_b128 v[170:173], v165 offset:50176
	ds_read_b128 v[174:177], v165 offset:51200
	ds_read_b128 v[178:181], v165 offset:52224
	ds_read_b128 v[182:185], v165 offset:53248
	ds_read_b128 v[186:189], v165 offset:54272
	ds_read_b128 v[190:193], v165 offset:55296
	ds_read_b128 v[198:201], v165 offset:56320
	global_load_lds_dwordx4 v[194:195], off
	v_lshl_add_u64 v[194:195], v[234:235], 0, s[26:27]
	s_mov_b32 m0, s62
	s_nop 0
	global_load_lds_dwordx4 v[194:195], off
	s_barrier
	s_waitcnt lgkmcnt(0)
	s_setprio 1
	s_waitcnt lgkmcnt(0)
	v_mfma_f32_16x16x32_bf16 v[62:65], v[130:133], v[166:169], v[62:65]
	v_mfma_f32_16x16x32_bf16 v[58:61], v[156:159], v[166:169], v[58:61]
	v_mfma_f32_16x16x32_bf16 v[46:49], v[130:133], v[174:177], v[46:49]
	v_mfma_f32_16x16x32_bf16 v[42:45], v[156:159], v[174:177], v[42:45]
	v_mfma_f32_16x16x32_bf16 v[30:33], v[130:133], v[182:185], v[30:33]
	v_mfma_f32_16x16x32_bf16 v[26:29], v[156:159], v[182:185], v[26:29]
	v_mfma_f32_16x16x32_bf16 v[14:17], v[130:133], v[190:193], v[14:17]
	v_mfma_f32_16x16x32_bf16 v[10:13], v[156:159], v[190:193], v[10:13]
	v_mfma_f32_16x16x32_bf16 v[62:65], v[152:155], v[170:173], v[62:65]
	v_mfma_f32_16x16x32_bf16 v[58:61], v[160:163], v[170:173], v[58:61]
	v_mfma_f32_16x16x32_bf16 v[46:49], v[152:155], v[178:181], v[46:49]
	v_mfma_f32_16x16x32_bf16 v[42:45], v[160:163], v[178:181], v[42:45]
	v_mfma_f32_16x16x32_bf16 v[30:33], v[152:155], v[186:189], v[30:33]
	v_mfma_f32_16x16x32_bf16 v[26:29], v[160:163], v[186:189], v[26:29]
	v_mfma_f32_16x16x32_bf16 v[14:17], v[152:155], v[198:201], v[14:17]
	v_mfma_f32_16x16x32_bf16 v[10:13], v[160:163], v[198:201], v[10:13]
	s_setprio 0
	s_barrier
	s_add_u32 s10, s16, 0x20080
	s_addc_u32 s11, s17, 0
	s_add_i32 s16, s18, s21
	v_lshl_add_u64 v[130:131], s[10:11], 0, v[136:137]
	s_mov_b32 m0, s16
	s_nop 0
	global_load_lds_dwordx4 v[130:131], off
	v_lshl_add_u64 v[130:131], s[10:11], 0, v[140:141]
	s_add_i32 m0, s16, 0x2000
	s_nop 0
	global_load_lds_dwordx4 v[130:131], off
	v_add_u32_e32 v0, 0x10000, v164
	ds_read_b128 v[130:133], v0
	ds_read_b128 v[152:155], v0 offset:1024
	ds_read_b128 v[156:159], v0 offset:2048
	ds_read_b128 v[160:163], v0 offset:3072
	s_waitcnt vmcnt(6)
	s_barrier
; #define PG8_MMA(ai, bj, At, Bt) do { __builtin_amdgcn_s_setprio(1); _Pragma("unroll") for (int m = 0; m < 4; ++m) _Pragma("unroll") for (int n = 0; n < 2; ++n) _Pragma("unroll") for (int k = 0; k < 2; ++k) \
;         acc[ai][bj][m][n] = __builtin_amdgcn_mfma_f32_16x16x32_bf16(Bt[n][k], At[m][k], acc[ai][bj][m][n], 0, 0, 0); __builtin_amdgcn_s_setprio(0); } while (0)
; #define PG8_WAIT_V(n) asm volatile("s_waitcnt vmcnt(" #n ")" ::: "memory")
; #define PG8_BAR __builtin_amdgcn_s_barrier()
;     __device__ __forceinline__ float ssq8(int row, int which) const { const f32x4 a = *(const f32x4*)(ssqp + row * 16 + which * 8), b = *(const f32x4*)(ssqp + row * 16 + which * 8 + 4); return ((a[0] + a[1]) + (a[2] + a[3])) + ((b[0] + b[1]) + (b[2] + b[3])); }
; template <class Epi, class Sched>
; __device__ __forceinline__ void gemm_phase(LAS unsigned char* lds, const Gemm g, const Sched& S, const Epi& E) {
;     ...
;             PG8_WAIT_V(6); PG8_BAR; PG8_MMA(1, 1, At, B1); PG8_BAR;
;         }
;         E(acc, cur, wr, wc, fr, fq);
;         if (!has_next) break;
;     __device__ __forceinline__ void operator()(const AccT& acc, const pg8::Unit& u, int wr, int wc, int fr, int fq) const {
;         const int row0 = u.pm * 256 + wr * 64 + fr;
; #pragma unroll
;         for (int ai = 0; ai < 2; ++ai)
; #pragma unroll
;             for (int m = 0; m < 4; ++m) {
;                 const int row = row0 + ai * 128 + m * 16;
;                 if (u.pn < 4) {
;                     const float rs = rsqrtf(ssq8(row, 0) * (1.0f / 512) + EPSN) * QS_MLA;
; #pragma unroll
;                     for (int bj = 0; bj < 2; ++bj)
;                         *(u32x4*)(Qm + (size_t)row * 1536 + (2 * u.pn + bj) * 192 + wc * 32 + 8 * fq) = pack8s(acc[ai][bj][m][0], acc[ai][bj][m][1], rs);
;                 } else if (u.pn < 6) {
;                     const float rs = rsqrtf(ssq8(row, 0) * (1.0f / 512) + EPSN) * QS_MLA;
	s_setprio 1
	v_mfma_f32_16x16x32_bf16 v[54:57], v[202:205], v[166:169], v[54:57]
	v_mfma_f32_16x16x32_bf16 v[50:53], v[224:227], v[166:169], v[50:53]
	v_mfma_f32_16x16x32_bf16 v[38:41], v[202:205], v[174:177], v[38:41]
	v_mfma_f32_16x16x32_bf16 v[34:37], v[224:227], v[174:177], v[34:37]
	v_mfma_f32_16x16x32_bf16 v[22:25], v[202:205], v[182:185], v[22:25]
	v_mfma_f32_16x16x32_bf16 v[18:21], v[224:227], v[182:185], v[18:21]
	v_mfma_f32_16x16x32_bf16 v[6:9], v[202:205], v[190:193], v[6:9]
	v_mfma_f32_16x16x32_bf16 v[2:5], v[224:227], v[190:193], v[2:5]
	v_mfma_f32_16x16x32_bf16 v[54:57], v[206:209], v[170:173], v[54:57]
	v_mfma_f32_16x16x32_bf16 v[50:53], v[228:231], v[170:173], v[50:53]
	v_mfma_f32_16x16x32_bf16 v[38:41], v[206:209], v[178:181], v[38:41]
	v_mfma_f32_16x16x32_bf16 v[34:37], v[228:231], v[178:181], v[34:37]
	v_mfma_f32_16x16x32_bf16 v[22:25], v[206:209], v[186:189], v[22:25]
	v_mfma_f32_16x16x32_bf16 v[18:21], v[228:231], v[186:189], v[18:21]
	v_mfma_f32_16x16x32_bf16 v[6:9], v[206:209], v[198:201], v[6:9]
	v_mfma_f32_16x16x32_bf16 v[2:5], v[228:231], v[198:201], v[2:5]
	s_setprio 0
	s_add_i32 s14, s14, 2
	s_add_u32 s7, s7, 0x100
	s_addc_u32 s9, s9, 0
	s_cmp_gt_u32 s14, 5
	s_mov_b64 s[10:11], s[0:1]
	s_barrier
	s_cbranch_scc0 .LBB0_1427
	s_waitcnt lgkmcnt(0)
	s_cmp_gt_i32 s8, 3
	s_cselect_b64 s[10:11], -1, 0
	s_cmp_gt_u32 s8, 5
	s_cselect_b64 s[16:17], -1, 0
	s_lshl_b32 s0, s8, 8
	v_lshl_add_u32 v152, s2, 8, v143
	s_add_i32 s54, s0, 0xfffffa00
	s_lshl_b32 s0, s8, 2
	s_add_i32 s0, s63, s0
	v_lshlrev_b32_e32 v130, 4, v152
	s_mulk_i32 s0, 0xc0
	v_ashrrev_i32_e32 v131, 31, v130
	s_ashr_i32 s55, s54, 31
	s_ashr_i32 s1, s0, 31
	v_lshl_add_u64 v[154:155], v[130:131], 2, s[4:5]
	s_and_b32 s100, s16, 32
	s_mov_b32 s101, 0
	v_lshl_add_u64 v[236:237], v[154:155], 0, s[100:101]
	s_movk_i32 s100, 0x2000
	v_lshl_add_u64 v[238:239], v[236:237], 0, s[100:101]
	global_load_dwordx4 v[194:197], v[236:237], off
	global_load_dwordx4 v[198:201], v[236:237], off offset:16
	global_load_dwordx4 v[202:205], v[236:237], off offset:1024
	global_load_dwordx4 v[206:209], v[236:237], off offset:1040
	global_load_dwordx4 v[224:227], v[236:237], off offset:2048
	global_load_dwordx4 v[228:231], v[236:237], off offset:2064
	global_load_dwordx4 v[240:243], v[236:237], off offset:3072
	global_load_dwordx4 v[244:247], v[236:237], off offset:3088
	s_waitcnt vmcnt(0)
	v_add_f32_e32 v194, v194, v195
	v_add_f32_e32 v196, v196, v197
	v_add_f32_e32 v198, v198, v199
	v_add_f32_e32 v200, v200, v201
	v_add_f32_e32 v202, v202, v203
	v_add_f32_e32 v204, v204, v205
	v_add_f32_e32 v206, v206, v207
	v_add_f32_e32 v208, v208, v209
	v_add_f32_e32 v224, v224, v225
	v_add_f32_e32 v226, v226, v227
	v_add_f32_e32 v228, v228, v229
	v_add_f32_e32 v230, v230, v231
	v_add_f32_e32 v240, v240, v241
	v_add_f32_e32 v242, v242, v243
	v_add_f32_e32 v244, v244, v245
	v_add_f32_e32 v246, v246, v247
	v_add_f32_e32 v194, v194, v196
	v_add_f32_e32 v198, v198, v200
	v_add_f32_e32 v202, v202, v204
	v_add_f32_e32 v206, v206, v208
	v_add_f32_e32 v224, v224, v226
	v_add_f32_e32 v228, v228, v230
	v_add_f32_e32 v240, v240, v242
	v_add_f32_e32 v244, v244, v246
	v_add_f32_e32 v248, v194, v198
	v_add_f32_e32 v249, v202, v206
	v_add_f32_e32 v250, v224, v228
	v_add_f32_e32 v251, v240, v244
	global_load_dwordx4 v[194:197], v[238:239], off
	global_load_dwordx4 v[198:201], v[238:239], off offset:16
	global_load_dwordx4 v[202:205], v[238:239], off offset:1024
	global_load_dwordx4 v[206:209], v[238:239], off offset:1040
	global_load_dwordx4 v[224:227], v[238:239], off offset:2048
	global_load_dwordx4 v[228:231], v[238:239], off offset:2064
	global_load_dwordx4 v[240:243], v[238:239], off offset:3072
	global_load_dwordx4 v[244:247], v[238:239], off offset:3088
	s_waitcnt vmcnt(0)
	v_add_f32_e32 v194, v194, v195
	v_add_f32_e32 v196, v196, v197
	v_add_f32_e32 v198, v198, v199
	v_add_f32_e32 v200, v200, v201
	v_add_f32_e32 v202, v202, v203
	v_add_f32_e32 v204, v204, v205
	v_add_f32_e32 v206, v206, v207
	v_add_f32_e32 v208, v208, v209
	v_add_f32_e32 v224, v224, v225
	v_add_f32_e32 v226, v226, v227
	v_add_f32_e32 v228, v228, v229
	v_add_f32_e32 v230, v230, v231
	v_add_f32_e32 v240, v240, v241
	v_add_f32_e32 v242, v242, v243
	v_add_f32_e32 v244, v244, v245
	v_add_f32_e32 v246, v246, v247
	v_add_f32_e32 v194, v194, v196
	v_add_f32_e32 v198, v198, v200
	v_add_f32_e32 v202, v202, v204
	v_add_f32_e32 v206, v206, v208
	v_add_f32_e32 v224, v224, v226
	v_add_f32_e32 v228, v228, v230
	v_add_f32_e32 v240, v240, v242
	v_add_f32_e32 v244, v244, v246
	v_add_f32_e32 v236, v194, v198
	v_add_f32_e32 v237, v202, v206
	v_add_f32_e32 v238, v224, v228
	v_add_f32_e32 v239, v240, v244
	s_mov_b64 s[18:19], -1
	s_and_b64 vcc, exec, s[10:11]
	s_cbranch_vccz .LBB0_1434
	s_and_b64 vcc, exec, s[16:17]
	s_cbranch_vccz .LBB0_1431
	s_mov_b32 s2, 0x800000
	v_ashrrev_i32_e32 v153, 31, v152
	s_lshl_b32 s14, s60, 1
	s_mov_b64 s[18:19], 0
	v_lshlrev_b64 v[156:157], 12, v[152:153]
	v_lshl_add_u64 v[156:157], s[46:47], 0, v[156:157]
	v_mov_b32_e32 v0, v248
	v_fmamk_f32 v0, v0, 0x3b000000, v212
	v_cmp_gt_f32_e32 vcc, s2, v0
	v_mul_f32_e32 v130, 0x4b800000, v0
	v_lshl_add_u64 v[156:157], s[54:55], 1, v[156:157]
	v_cndmask_b32_e32 v0, v0, v130, vcc
	v_rsq_f32_e32 v0, v0
	v_lshl_add_u64 v[156:157], v[156:157], 0, s[14:15]
	s_mov_b64 s[2:3], 0x100
	v_mul_f32_e32 v130, 0x45800000, v0
	v_cndmask_b32_e32 v160, v0, v130, vcc
	v_mul_f32_e32 v0, v126, v160
	v_mul_f32_e32 v130, v127, v160
	v_cvt_pk_bf16_f32 v130, v0, v130
	v_mul_f32_e32 v0, v128, v160
	v_mul_f32_e32 v131, v129, v160
	v_cvt_pk_bf16_f32 v131, v0, v131
	v_mul_f32_e32 v0, v122, v160
	v_mul_f32_e32 v132, v123, v160
	v_cvt_pk_bf16_f32 v132, v0, v132
	v_mul_f32_e32 v0, v124, v160
	v_mul_f32_e32 v133, v125, v160
	v_cvt_pk_bf16_f32 v133, v0, v133
	v_lshlrev_b32_e32 v0, 1, v142
	v_lshl_add_u64 v[158:159], v[156:157], 0, v[0:1]
	global_store_dwordx4 v[158:159], v[130:133], off
	v_mul_f32_e32 v0, v118, v160
	v_lshl_add_u64 v[156:157], v[156:157], 0, s[2:3]
	v_mul_f32_e32 v130, v119, v160
	v_cvt_pk_bf16_f32 v130, v0, v130
	v_mul_f32_e32 v0, v120, v160
	v_mul_f32_e32 v131, v121, v160
	v_cvt_pk_bf16_f32 v131, v0, v131
	v_mul_f32_e32 v0, v114, v160
	v_mul_f32_e32 v132, v115, v160
	v_mul_f32_e32 v133, v117, v160
	v_cvt_pk_bf16_f32 v132, v0, v132
	v_mul_f32_e32 v0, v116, v160
	v_cvt_pk_bf16_f32 v133, v0, v133
